# GEMM: both K-halves of each accumulator issued back-to-back (dependent MFMA pairs, SrcC forwarding) on top of v4
# speedup vs baseline: 1.0077x; 1.0077x over previous
; #define PG8_STAGE(bufoff, gbase, voff) do { _Pragma("unroll") for (int _i = 0; _i < 2; ++_i) \
;         __builtin_amdgcn_global_load_lds((const unsigned*)((const char*)(gbase) + (voff)[_i]), (PG8_LAS unsigned*)(lds + (bufoff) + ldsw + _i * 8192), 16, 0, 0); } while (0)
; #define PG8_LDA(dst, b, h) do { _Pragma("unroll") for (int m = 0; m < 4; ++m) _Pragma("unroll") for (int k = 0; k < 2; ++k) dst[m][k] = *(const PG8_LAS bf16x8*)(lds + PG8_SA(b, h) + aoff + m * 2048 + k * 1024); } while (0)
; #define PG8_LDB(dst, b, h) do { _Pragma("unroll") for (int n = 0; n < 2; ++n) _Pragma("unroll") for (int k = 0; k < 2; ++k) dst[n][k] = *(const PG8_LAS bf16x8*)(lds + PG8_SB(b, h) + boff + n * 2048 + k * 1024); } while (0)
; #define PG8_MMA(ai, bj, At, Bt) do { __builtin_amdgcn_s_setprio(1); _Pragma("unroll") for (int m = 0; m < 4; ++m) _Pragma("unroll") for (int n = 0; n < 2; ++n) _Pragma("unroll") for (int k = 0; k < 2; ++k) \
;         acc[ai][bj][m][n] = __builtin_amdgcn_mfma_f32_16x16x32_bf16(Bt[n][k], At[m][k], acc[ai][bj][m][n], 0, 0, 0); __builtin_amdgcn_s_setprio(0); } while (0)
; #define PG8_WAIT_V(n) asm volatile("s_waitcnt vmcnt(" #n ")" ::: "memory")
; #define PG8_WAIT_L(n) asm volatile("s_waitcnt lgkmcnt(" #n ")" ::: "memory")
; #define PG8_BAR __builtin_amdgcn_s_barrier()
; #define PG8_SCHED __builtin_amdgcn_sched_barrier(0)
; template <class Epi, class Sched, bool ALIGN_EPI = false, bool SP2 = false>
; __device__ __forceinline__ void gemm_phase(PG8_LAS unsigned char* lds, const Gemm g, const Sched& S, const Epi& E) {
;     ...
;             PG8_LDB(B0, 0, 0); PG8_LDB(B1, 0, 1); PG8_SCHED; PG8_LDA(At, 0, 0); PG8_STAGE(PG8_SA(1, 1), a1 + hstep, voffA);
;             PG8_WAIT_V(8); PG8_WAIT_L(0); PG8_BAR; PG8_MMA(0, 0, At, B0); PG8_MMA(0, 1, At, B1); PG8_BAR; PG8_SCHED;
;             PG8_LDA(At, 0, 1); PG8_STAGE(PG8_SB(0, 0), b2, voffB); PG8_STAGE(PG8_SB(0, 1), b2 + hstep, voffB); PG8_STAGE(PG8_SA(0, 0), a2, voffA);
;             PG8_WAIT_V(8); PG8_WAIT_L(0); PG8_BAR; PG8_MMA(1, 0, At, B0); PG8_MMA(1, 1, At, B1); PG8_BAR; PG8_SCHED;
.LBB0_510:
	ds_read_b128 v[128:131], v184
	ds_read_b128 v[148:151], v184 offset:1024
	ds_read_b128 v[152:155], v184 offset:2048
	ds_read_b128 v[158:161], v184 offset:3072
	ds_read_b128 v[190:193], v185
	ds_read_b128 v[194:197], v185 offset:1024
	ds_read_b128 v[198:201], v185 offset:2048
	ds_read_b128 v[202:205], v185 offset:3072
	s_add_u32 s34, s10, 0xfffc0080
	s_addc_u32 s35, s11, -1
	s_cmp_eq_u32 vcc_lo, 12
	s_cselect_b32 s69, s57, s35
	s_cselect_b32 s68, s63, s34
	s_cselect_b32 s67, s55, s97
	s_cselect_b32 s66, s95, s96
	s_add_i32 m0, s65, 0xc000
	ds_read_b128 v[206:209], v186
	ds_read_b128 v[210:213], v186 offset:1024
	ds_read_b128 v[214:217], v186 offset:2048
	ds_read_b128 v[218:221], v186 offset:3072
	ds_read_b128 v[222:225], v186 offset:4096
	ds_read_b128 v[226:229], v186 offset:5120
	ds_read_b128 v[230:233], v186 offset:6144
	ds_read_b128 v[234:237], v186 offset:7168
	global_load_lds_dwordx4 v142, s[10:11]
	s_add_i32 m0, s65, 0xe000
	s_nop 0
	global_load_lds_dwordx4 v140, s[10:11]
	s_waitcnt vmcnt(8)
	s_waitcnt lgkmcnt(0)
	s_barrier
	s_setprio 1
	s_waitcnt lgkmcnt(0)
	v_mfma_f32_16x16x32_bf16 v[124:127], v[128:131], v[206:209], v[124:127]
	v_mfma_f32_16x16x32_bf16 v[124:127], v[148:151], v[210:213], v[124:127]
	v_mfma_f32_16x16x32_bf16 v[120:123], v[152:155], v[206:209], v[120:123]
	v_mfma_f32_16x16x32_bf16 v[120:123], v[158:161], v[210:213], v[120:123]
	v_mfma_f32_16x16x32_bf16 v[104:107], v[152:155], v[214:217], v[104:107]
	v_mfma_f32_16x16x32_bf16 v[104:107], v[158:161], v[218:221], v[104:107]
	v_mfma_f32_16x16x32_bf16 v[108:111], v[128:131], v[214:217], v[108:111]
	v_mfma_f32_16x16x32_bf16 v[108:111], v[148:151], v[218:221], v[108:111]
	v_mfma_f32_16x16x32_bf16 v[92:95], v[128:131], v[222:225], v[92:95]
	v_mfma_f32_16x16x32_bf16 v[92:95], v[148:151], v[226:229], v[92:95]
	v_mfma_f32_16x16x32_bf16 v[88:91], v[152:155], v[222:225], v[88:91]
	v_mfma_f32_16x16x32_bf16 v[88:91], v[158:161], v[226:229], v[88:91]
	v_mfma_f32_16x16x32_bf16 v[72:75], v[152:155], v[230:233], v[72:75]
	v_mfma_f32_16x16x32_bf16 v[72:75], v[158:161], v[234:237], v[72:75]
	v_mfma_f32_16x16x32_bf16 v[76:79], v[128:131], v[230:233], v[76:79]
	v_mfma_f32_16x16x32_bf16 v[76:79], v[148:151], v[234:237], v[76:79]
	s_setprio 0
	s_setprio 1
	v_mfma_f32_16x16x32_bf16 v[116:119], v[190:193], v[206:209], v[116:119]
	v_mfma_f32_16x16x32_bf16 v[116:119], v[194:197], v[210:213], v[116:119]
	v_mfma_f32_16x16x32_bf16 v[112:115], v[198:201], v[206:209], v[112:115]
	v_mfma_f32_16x16x32_bf16 v[112:115], v[202:205], v[210:213], v[112:115]
	v_mfma_f32_16x16x32_bf16 v[96:99], v[198:201], v[214:217], v[96:99]
	v_mfma_f32_16x16x32_bf16 v[96:99], v[202:205], v[218:221], v[96:99]
	v_mfma_f32_16x16x32_bf16 v[100:103], v[190:193], v[214:217], v[100:103]
	v_mfma_f32_16x16x32_bf16 v[100:103], v[194:197], v[218:221], v[100:103]
	v_mfma_f32_16x16x32_bf16 v[84:87], v[190:193], v[222:225], v[84:87]
	v_mfma_f32_16x16x32_bf16 v[84:87], v[194:197], v[226:229], v[84:87]
	v_mfma_f32_16x16x32_bf16 v[80:83], v[198:201], v[222:225], v[80:83]
	v_mfma_f32_16x16x32_bf16 v[80:83], v[202:205], v[226:229], v[80:83]
	v_mfma_f32_16x16x32_bf16 v[64:67], v[198:201], v[230:233], v[64:67]
	v_mfma_f32_16x16x32_bf16 v[64:67], v[202:205], v[234:237], v[64:67]
	v_mfma_f32_16x16x32_bf16 v[68:71], v[190:193], v[230:233], v[68:71]
	v_mfma_f32_16x16x32_bf16 v[68:71], v[194:197], v[234:237], v[68:71]
	s_setprio 0
	s_barrier
	s_add_i32 s34, s84, s71
	s_mov_b32 m0, s34
	ds_read_b128 v[206:209], v186 offset:16384
	ds_read_b128 v[210:213], v186 offset:17408
	ds_read_b128 v[214:217], v186 offset:18432
	ds_read_b128 v[218:221], v186 offset:19456
	ds_read_b128 v[222:225], v186 offset:20480
	ds_read_b128 v[226:229], v186 offset:21504
	ds_read_b128 v[230:233], v186 offset:22528
	ds_read_b128 v[234:237], v186 offset:23552
	global_load_lds_dwordx4 v134, s[66:67]
	s_add_i32 m0, s34, 0x2000
	s_add_u32 s34, s66, 0x40000
	s_addc_u32 s35, s67, 0
	s_add_i32 vcc_hi, s85, s71
	global_load_lds_dwordx4 v138, s[66:67]
	s_mov_b32 m0, vcc_hi
	s_nop 0
	global_load_lds_dwordx4 v134, s[34:35]
	s_add_i32 m0, vcc_hi, 0x2000
	s_nop 0
	global_load_lds_dwordx4 v138, s[34:35]
	s_mov_b32 m0, s65
	s_nop 0
	global_load_lds_dwordx4 v132, s[68:69]
	s_mov_b32 m0, s73
	s_nop 0
	global_load_lds_dwordx4 v136, s[68:69]
	s_waitcnt vmcnt(8)
	s_waitcnt lgkmcnt(0)
	s_barrier
	s_setprio 1
	s_waitcnt lgkmcnt(0)
	v_mfma_f32_16x16x32_bf16 v[60:63], v[128:131], v[206:209], v[60:63]
	v_mfma_f32_16x16x32_bf16 v[60:63], v[148:151], v[210:213], v[60:63]
	v_mfma_f32_16x16x32_bf16 v[56:59], v[152:155], v[206:209], v[56:59]
	v_mfma_f32_16x16x32_bf16 v[56:59], v[158:161], v[210:213], v[56:59]
	v_mfma_f32_16x16x32_bf16 v[40:43], v[152:155], v[214:217], v[40:43]
	v_mfma_f32_16x16x32_bf16 v[40:43], v[158:161], v[218:221], v[40:43]
	v_mfma_f32_16x16x32_bf16 v[44:47], v[128:131], v[214:217], v[44:47]
	v_mfma_f32_16x16x32_bf16 v[44:47], v[148:151], v[218:221], v[44:47]
	v_mfma_f32_16x16x32_bf16 v[28:31], v[128:131], v[222:225], v[28:31]
	v_mfma_f32_16x16x32_bf16 v[28:31], v[148:151], v[226:229], v[28:31]
	v_mfma_f32_16x16x32_bf16 v[24:27], v[152:155], v[222:225], v[24:27]
	v_mfma_f32_16x16x32_bf16 v[24:27], v[158:161], v[226:229], v[24:27]
	v_mfma_f32_16x16x32_bf16 v[8:11], v[152:155], v[230:233], v[8:11]
	v_mfma_f32_16x16x32_bf16 v[8:11], v[158:161], v[234:237], v[8:11]
	v_mfma_f32_16x16x32_bf16 v[12:15], v[128:131], v[230:233], v[12:15]
	v_mfma_f32_16x16x32_bf16 v[12:15], v[148:151], v[234:237], v[12:15]
	s_setprio 0
	s_setprio 1
	v_mfma_f32_16x16x32_bf16 v[52:55], v[190:193], v[206:209], v[52:55]
	v_mfma_f32_16x16x32_bf16 v[52:55], v[194:197], v[210:213], v[52:55]
	v_mfma_f32_16x16x32_bf16 v[48:51], v[198:201], v[206:209], v[48:51]
	v_mfma_f32_16x16x32_bf16 v[48:51], v[202:205], v[210:213], v[48:51]
	v_mfma_f32_16x16x32_bf16 v[32:35], v[198:201], v[214:217], v[32:35]
	v_mfma_f32_16x16x32_bf16 v[32:35], v[202:205], v[218:221], v[32:35]
	v_mfma_f32_16x16x32_bf16 v[36:39], v[190:193], v[214:217], v[36:39]
	v_mfma_f32_16x16x32_bf16 v[36:39], v[194:197], v[218:221], v[36:39]
	v_mfma_f32_16x16x32_bf16 v[20:23], v[190:193], v[222:225], v[20:23]
	v_mfma_f32_16x16x32_bf16 v[20:23], v[194:197], v[226:229], v[20:23]
	v_mfma_f32_16x16x32_bf16 v[16:19], v[198:201], v[222:225], v[16:19]
	v_mfma_f32_16x16x32_bf16 v[16:19], v[202:205], v[226:229], v[16:19]
	v_mfma_f32_16x16x32_bf16 v[0:3], v[198:201], v[230:233], v[0:3]
	v_mfma_f32_16x16x32_bf16 v[0:3], v[202:205], v[234:237], v[0:3]
	v_mfma_f32_16x16x32_bf16 v[4:7], v[190:193], v[230:233], v[4:7]
	v_mfma_f32_16x16x32_bf16 v[4:7], v[194:197], v[234:237], v[4:7]
	s_setprio 0
	s_barrier
; #define PG8_STAGE(bufoff, gbase, voff) do { _Pragma("unroll") for (int _i = 0; _i < 2; ++_i) \
;         __builtin_amdgcn_global_load_lds((const unsigned*)((const char*)(gbase) + (voff)[_i]), (PG8_LAS unsigned*)(lds + (bufoff) + ldsw + _i * 8192), 16, 0, 0); } while (0)
; #define PG8_LDA(dst, b, h) do { _Pragma("unroll") for (int m = 0; m < 4; ++m) _Pragma("unroll") for (int k = 0; k < 2; ++k) dst[m][k] = *(const PG8_LAS bf16x8*)(lds + PG8_SA(b, h) + aoff + m * 2048 + k * 1024); } while (0)
; #define PG8_LDB(dst, b, h) do { _Pragma("unroll") for (int n = 0; n < 2; ++n) _Pragma("unroll") for (int k = 0; k < 2; ++k) dst[n][k] = *(const PG8_LAS bf16x8*)(lds + PG8_SB(b, h) + boff + n * 2048 + k * 1024); } while (0)
; #define PG8_MMA(ai, bj, At, Bt) do { __builtin_amdgcn_s_setprio(1); _Pragma("unroll") for (int m = 0; m < 4; ++m) _Pragma("unroll") for (int n = 0; n < 2; ++n) _Pragma("unroll") for (int k = 0; k < 2; ++k) \
;         acc[ai][bj][m][n] = __builtin_amdgcn_mfma_f32_16x16x32_bf16(Bt[n][k], At[m][k], acc[ai][bj][m][n], 0, 0, 0); __builtin_amdgcn_s_setprio(0); } while (0)
; #define PG8_WAIT_V(n) asm volatile("s_waitcnt vmcnt(" #n ")" ::: "memory")
; #define PG8_WAIT_L(n) asm volatile("s_waitcnt lgkmcnt(" #n ")" ::: "memory")
; #define PG8_BAR __builtin_amdgcn_s_barrier()
; #define PG8_SCHED __builtin_amdgcn_sched_barrier(0)
; template <class Epi, class Sched, bool ALIGN_EPI = false, bool SP2 = false>
; __device__ __forceinline__ void gemm_phase(PG8_LAS unsigned char* lds, const Gemm g, const Sched& S, const Epi& E) {
;     ...
;             PG8_LDB(B0, 1, 0); PG8_LDB(B1, 1, 1); PG8_SCHED; PG8_LDA(At, 1, 0); PG8_STAGE(PG8_SA(0, 1), a2 + hstep, voffA);
;             PG8_WAIT_V(8); PG8_WAIT_L(0); PG8_BAR; PG8_MMA(0, 0, At, B0); PG8_MMA(0, 1, At, B1); PG8_BAR; PG8_SCHED;
;             PG8_LDA(At, 1, 1); PG8_STAGE(PG8_SB(1, 0), b3, voffB); PG8_STAGE(PG8_SB(1, 1), b3 + hstep, voffB); PG8_STAGE(PG8_SA(1, 0), a3, voffA);
;             PG8_WAIT_V(8); PG8_WAIT_L(0); PG8_BAR; PG8_MMA(1, 0, At, B0); PG8_MMA(1, 1, At, B1); PG8_BAR; PG8_SCHED;
	s_add_i32 vcc_hi, 0, 0x18000
	s_add_i32 s14, 0, 0x1c000
	v_add_u32_e32 v158, vcc_hi, v163
	v_add_u32_e32 v202, s14, v163
	ds_read_b128 v[128:131], v158
	ds_read_b128 v[148:151], v158 offset:1024
	ds_read_b128 v[152:155], v158 offset:2048
	ds_read_b128 v[158:161], v158 offset:3072
	ds_read_b128 v[190:193], v202
	ds_read_b128 v[194:197], v202 offset:1024
	ds_read_b128 v[198:201], v202 offset:2048
	ds_read_b128 v[202:205], v202 offset:3072
	s_add_u32 s34, s68, 0x40000
	s_addc_u32 s35, s69, 0
	s_mov_b32 m0, s74
	ds_read_b128 v[206:209], v186 offset:32768
	ds_read_b128 v[210:213], v186 offset:33792
	ds_read_b128 v[214:217], v186 offset:34816
	ds_read_b128 v[218:221], v186 offset:35840
	ds_read_b128 v[222:225], v186 offset:36864
	ds_read_b128 v[226:229], v186 offset:37888
	ds_read_b128 v[230:233], v186 offset:38912
	ds_read_b128 v[234:237], v186 offset:39936
	global_load_lds_dwordx4 v132, s[34:35]
	s_mov_b32 m0, s75
	s_nop 0
	global_load_lds_dwordx4 v136, s[34:35]
	s_waitcnt vmcnt(8)
	s_waitcnt lgkmcnt(0)
	s_barrier
	s_setprio 1
	s_waitcnt lgkmcnt(0)
	v_mfma_f32_16x16x32_bf16 v[124:127], v[128:131], v[206:209], v[124:127]
	v_mfma_f32_16x16x32_bf16 v[124:127], v[148:151], v[210:213], v[124:127]
	v_mfma_f32_16x16x32_bf16 v[120:123], v[152:155], v[206:209], v[120:123]
	v_mfma_f32_16x16x32_bf16 v[120:123], v[158:161], v[210:213], v[120:123]
	v_mfma_f32_16x16x32_bf16 v[104:107], v[152:155], v[214:217], v[104:107]
	v_mfma_f32_16x16x32_bf16 v[104:107], v[158:161], v[218:221], v[104:107]
	v_mfma_f32_16x16x32_bf16 v[108:111], v[128:131], v[214:217], v[108:111]
	v_mfma_f32_16x16x32_bf16 v[108:111], v[148:151], v[218:221], v[108:111]
	v_mfma_f32_16x16x32_bf16 v[92:95], v[128:131], v[222:225], v[92:95]
	v_mfma_f32_16x16x32_bf16 v[92:95], v[148:151], v[226:229], v[92:95]
	v_mfma_f32_16x16x32_bf16 v[88:91], v[152:155], v[222:225], v[88:91]
	v_mfma_f32_16x16x32_bf16 v[88:91], v[158:161], v[226:229], v[88:91]
	v_mfma_f32_16x16x32_bf16 v[72:75], v[152:155], v[230:233], v[72:75]
	v_mfma_f32_16x16x32_bf16 v[72:75], v[158:161], v[234:237], v[72:75]
	v_mfma_f32_16x16x32_bf16 v[76:79], v[128:131], v[230:233], v[76:79]
	v_mfma_f32_16x16x32_bf16 v[76:79], v[148:151], v[234:237], v[76:79]
	s_setprio 0
	s_setprio 1
	v_mfma_f32_16x16x32_bf16 v[116:119], v[190:193], v[206:209], v[116:119]
	v_mfma_f32_16x16x32_bf16 v[116:119], v[194:197], v[210:213], v[116:119]
	v_mfma_f32_16x16x32_bf16 v[112:115], v[198:201], v[206:209], v[112:115]
	v_mfma_f32_16x16x32_bf16 v[112:115], v[202:205], v[210:213], v[112:115]
	v_mfma_f32_16x16x32_bf16 v[96:99], v[198:201], v[214:217], v[96:99]
	v_mfma_f32_16x16x32_bf16 v[96:99], v[202:205], v[218:221], v[96:99]
	v_mfma_f32_16x16x32_bf16 v[100:103], v[190:193], v[214:217], v[100:103]
	v_mfma_f32_16x16x32_bf16 v[100:103], v[194:197], v[218:221], v[100:103]
	v_mfma_f32_16x16x32_bf16 v[84:87], v[190:193], v[222:225], v[84:87]
	v_mfma_f32_16x16x32_bf16 v[84:87], v[194:197], v[226:229], v[84:87]
	v_mfma_f32_16x16x32_bf16 v[80:83], v[198:201], v[222:225], v[80:83]
	v_mfma_f32_16x16x32_bf16 v[80:83], v[202:205], v[226:229], v[80:83]
	v_mfma_f32_16x16x32_bf16 v[64:67], v[198:201], v[230:233], v[64:67]
	v_mfma_f32_16x16x32_bf16 v[64:67], v[202:205], v[234:237], v[64:67]
	v_mfma_f32_16x16x32_bf16 v[68:71], v[190:193], v[230:233], v[68:71]
	v_mfma_f32_16x16x32_bf16 v[68:71], v[194:197], v[234:237], v[68:71]
	s_setprio 0
	s_barrier
	s_add_i32 s15, vcc_hi, s71
	s_add_u32 s98, s66, s42
	s_addc_u32 s99, s67, s43
	s_add_u32 s100, s68, s42
	s_addc_u32 s101, s69, s43
	s_mov_b32 m0, s15
	ds_read_b128 v[206:209], v186 offset:49152
	ds_read_b128 v[210:213], v186 offset:50176
	ds_read_b128 v[214:217], v186 offset:51200
	ds_read_b128 v[218:221], v186 offset:52224
	ds_read_b128 v[222:225], v186 offset:53248
	ds_read_b128 v[226:229], v186 offset:54272
	ds_read_b128 v[230:233], v186 offset:55296
	ds_read_b128 v[234:237], v186 offset:56320
	global_load_lds_dwordx4 v134, s[98:99]
	s_add_i32 m0, s15, 0x2000
	s_add_u32 s34, s66, 0x40080
	s_addc_u32 s35, s67, 0
	s_add_i32 s14, s14, s71
	global_load_lds_dwordx4 v138, s[98:99]
	s_mov_b32 m0, s14
	s_nop 0
	global_load_lds_dwordx4 v134, s[34:35]
	s_add_i32 m0, s14, 0x2000
	s_nop 0
	global_load_lds_dwordx4 v138, s[34:35]
	s_mov_b32 m0, s78
	s_nop 0
	global_load_lds_dwordx4 v132, s[100:101]
	s_mov_b32 m0, s79
	s_nop 0
	global_load_lds_dwordx4 v136, s[100:101]
	s_waitcnt vmcnt(8)
	s_waitcnt lgkmcnt(0)
	s_barrier
	s_setprio 1
	s_waitcnt lgkmcnt(0)
	v_mfma_f32_16x16x32_bf16 v[60:63], v[128:131], v[206:209], v[60:63]
	v_mfma_f32_16x16x32_bf16 v[60:63], v[148:151], v[210:213], v[60:63]
	v_mfma_f32_16x16x32_bf16 v[56:59], v[152:155], v[206:209], v[56:59]
	v_mfma_f32_16x16x32_bf16 v[56:59], v[158:161], v[210:213], v[56:59]
	v_mfma_f32_16x16x32_bf16 v[40:43], v[152:155], v[214:217], v[40:43]
	v_mfma_f32_16x16x32_bf16 v[40:43], v[158:161], v[218:221], v[40:43]
	v_mfma_f32_16x16x32_bf16 v[44:47], v[128:131], v[214:217], v[44:47]
	v_mfma_f32_16x16x32_bf16 v[44:47], v[148:151], v[218:221], v[44:47]
	v_mfma_f32_16x16x32_bf16 v[28:31], v[128:131], v[222:225], v[28:31]
	v_mfma_f32_16x16x32_bf16 v[28:31], v[148:151], v[226:229], v[28:31]
	v_mfma_f32_16x16x32_bf16 v[24:27], v[152:155], v[222:225], v[24:27]
	v_mfma_f32_16x16x32_bf16 v[24:27], v[158:161], v[226:229], v[24:27]
	v_mfma_f32_16x16x32_bf16 v[8:11], v[152:155], v[230:233], v[8:11]
	v_mfma_f32_16x16x32_bf16 v[8:11], v[158:161], v[234:237], v[8:11]
	v_mfma_f32_16x16x32_bf16 v[12:15], v[128:131], v[230:233], v[12:15]
	v_mfma_f32_16x16x32_bf16 v[12:15], v[148:151], v[234:237], v[12:15]
	s_setprio 0
	s_setprio 1
	v_mfma_f32_16x16x32_bf16 v[52:55], v[190:193], v[206:209], v[52:55]
	v_mfma_f32_16x16x32_bf16 v[52:55], v[194:197], v[210:213], v[52:55]
	v_mfma_f32_16x16x32_bf16 v[48:51], v[198:201], v[206:209], v[48:51]
	v_mfma_f32_16x16x32_bf16 v[48:51], v[202:205], v[210:213], v[48:51]
	v_mfma_f32_16x16x32_bf16 v[32:35], v[198:201], v[214:217], v[32:35]
	v_mfma_f32_16x16x32_bf16 v[32:35], v[202:205], v[218:221], v[32:35]
	v_mfma_f32_16x16x32_bf16 v[36:39], v[190:193], v[214:217], v[36:39]
	v_mfma_f32_16x16x32_bf16 v[36:39], v[194:197], v[218:221], v[36:39]
	v_mfma_f32_16x16x32_bf16 v[20:23], v[190:193], v[222:225], v[20:23]
	v_mfma_f32_16x16x32_bf16 v[20:23], v[194:197], v[226:229], v[20:23]
	v_mfma_f32_16x16x32_bf16 v[16:19], v[198:201], v[222:225], v[16:19]
	v_mfma_f32_16x16x32_bf16 v[16:19], v[202:205], v[226:229], v[16:19]
	v_mfma_f32_16x16x32_bf16 v[0:3], v[198:201], v[230:233], v[0:3]
	v_mfma_f32_16x16x32_bf16 v[0:3], v[202:205], v[234:237], v[0:3]
	v_mfma_f32_16x16x32_bf16 v[4:7], v[190:193], v[230:233], v[4:7]
	v_mfma_f32_16x16x32_bf16 v[4:7], v[194:197], v[234:237], v[4:7]
	s_setprio 0
	s_barrier
	s_add_i32 vcc_lo, vcc_lo, 2
	s_add_u32 s96, s96, 0x100
	s_addc_u32 s97, s97, 0
	s_add_u32 s10, s10, 0x100
	s_addc_u32 s11, s11, 0
	s_cmp_gt_u32 vcc_lo, 13
	s_cbranch_scc0 .LBB0_510
	s_and_b64 vcc, exec, s[44:45]
	s_cbranch_vccz .LBB0_513
	s_barrier

; #define PG8_STAGE(bufoff, gbase, voff) do { _Pragma("unroll") for (int _i = 0; _i < 2; ++_i) \
;         __builtin_amdgcn_global_load_lds((const unsigned*)((const char*)(gbase) + (voff)[_i]), (PG8_LAS unsigned*)(lds + (bufoff) + ldsw + _i * 8192), 16, 0, 0); } while (0)
; #define PG8_LDA(dst, b, h) do { _Pragma("unroll") for (int m = 0; m < 4; ++m) _Pragma("unroll") for (int k = 0; k < 2; ++k) dst[m][k] = *(const PG8_LAS bf16x8*)(lds + PG8_SA(b, h) + aoff + m * 2048 + k * 1024); } while (0)
; #define PG8_LDB(dst, b, h) do { _Pragma("unroll") for (int n = 0; n < 2; ++n) _Pragma("unroll") for (int k = 0; k < 2; ++k) dst[n][k] = *(const PG8_LAS bf16x8*)(lds + PG8_SB(b, h) + boff + n * 2048 + k * 1024); } while (0)
; #define PG8_MMA(ai, bj, At, Bt) do { __builtin_amdgcn_s_setprio(1); _Pragma("unroll") for (int m = 0; m < 4; ++m) _Pragma("unroll") for (int n = 0; n < 2; ++n) _Pragma("unroll") for (int k = 0; k < 2; ++k) \
;         acc[ai][bj][m][n] = __builtin_amdgcn_mfma_f32_16x16x32_bf16(Bt[n][k], At[m][k], acc[ai][bj][m][n], 0, 0, 0); __builtin_amdgcn_s_setprio(0); } while (0)
; #define PG8_WAIT_V(n) asm volatile("s_waitcnt vmcnt(" #n ")" ::: "memory")
; #define PG8_WAIT_L(n) asm volatile("s_waitcnt lgkmcnt(" #n ")" ::: "memory")
; #define PG8_BAR __builtin_amdgcn_s_barrier()
; #define PG8_SCHED __builtin_amdgcn_sched_barrier(0)
; template <class Epi, class Sched, bool ALIGN_EPI = false, bool SP2 = false>
; __device__ __forceinline__ void gemm_phase(PG8_LAS unsigned char* lds, const Gemm g, const Sched& S, const Epi& E) {
;     ...
;             PG8_LDB(B0, 0, 0); PG8_LDB(B1, 0, 1); PG8_SCHED; PG8_LDA(At, 0, 0); PG8_STAGE(PG8_SA(1, 1), a1 + hstep, voffA);
;             PG8_WAIT_V(8); PG8_WAIT_L(0); PG8_BAR; PG8_MMA(0, 0, At, B0); PG8_MMA(0, 1, At, B1); PG8_BAR; PG8_SCHED;
;             PG8_LDA(At, 0, 1); PG8_STAGE(PG8_SB(0, 0), b2, voffB); PG8_STAGE(PG8_SB(0, 1), b2 + hstep, voffB); PG8_STAGE(PG8_SA(0, 0), a2, voffA);
;             PG8_WAIT_V(8); PG8_WAIT_L(0); PG8_BAR; PG8_MMA(1, 0, At, B0); PG8_MMA(1, 1, At, B1); PG8_BAR; PG8_SCHED;
.LBB0_710:
	ds_read_b128 v[128:131], v169
	ds_read_b128 v[132:135], v169 offset:1024
	ds_read_b128 v[136:139], v169 offset:2048
	ds_read_b128 v[140:143], v169 offset:3072
	ds_read_b128 v[162:165], v170
	ds_read_b128 v[172:175], v170 offset:1024
	ds_read_b128 v[176:179], v170 offset:2048
	ds_read_b128 v[184:187], v170 offset:3072
	s_add_u32 s14, s54, 0xfffc0080
	s_addc_u32 s15, s55, -1
	s_cmp_eq_u32 s84, 12
	s_cselect_b32 s59, s45, s15
	s_cselect_b32 s58, s51, s14
	s_cselect_b32 s57, s43, s83
	s_cselect_b32 s56, s53, s82
	s_add_i32 m0, s64, 0xc000
	ds_read_b128 v[188:191], v171
	ds_read_b128 v[192:195], v171 offset:1024
	ds_read_b128 v[196:199], v171 offset:2048
	ds_read_b128 v[200:203], v171 offset:3072
	ds_read_b128 v[204:207], v171 offset:4096
	ds_read_b128 v[208:211], v171 offset:5120
	ds_read_b128 v[212:215], v171 offset:6144
	ds_read_b128 v[216:219], v171 offset:7168
	global_load_lds_dwordx4 v154, s[54:55]
	s_add_i32 m0, s64, 0xe000
	s_nop 0
	global_load_lds_dwordx4 v152, s[54:55]
	s_waitcnt vmcnt(8)
	s_waitcnt lgkmcnt(0)
	s_barrier
	s_setprio 1
	s_waitcnt lgkmcnt(0)
	v_mfma_f32_16x16x32_bf16 v[124:127], v[128:131], v[188:191], v[124:127]
	v_mfma_f32_16x16x32_bf16 v[124:127], v[132:135], v[192:195], v[124:127]
	v_mfma_f32_16x16x32_bf16 v[120:123], v[136:139], v[188:191], v[120:123]
	v_mfma_f32_16x16x32_bf16 v[120:123], v[140:143], v[192:195], v[120:123]
	v_mfma_f32_16x16x32_bf16 v[108:111], v[136:139], v[196:199], v[108:111]
	v_mfma_f32_16x16x32_bf16 v[108:111], v[140:143], v[200:203], v[108:111]
	v_mfma_f32_16x16x32_bf16 v[116:119], v[128:131], v[196:199], v[116:119]
	v_mfma_f32_16x16x32_bf16 v[116:119], v[132:135], v[200:203], v[116:119]
	v_mfma_f32_16x16x32_bf16 v[100:103], v[128:131], v[204:207], v[100:103]
	v_mfma_f32_16x16x32_bf16 v[100:103], v[132:135], v[208:211], v[100:103]
	v_mfma_f32_16x16x32_bf16 v[92:95], v[136:139], v[204:207], v[92:95]
	v_mfma_f32_16x16x32_bf16 v[92:95], v[140:143], v[208:211], v[92:95]
	v_mfma_f32_16x16x32_bf16 v[76:79], v[136:139], v[212:215], v[76:79]
	v_mfma_f32_16x16x32_bf16 v[76:79], v[140:143], v[216:219], v[76:79]
	v_mfma_f32_16x16x32_bf16 v[84:87], v[128:131], v[212:215], v[84:87]
	v_mfma_f32_16x16x32_bf16 v[84:87], v[132:135], v[216:219], v[84:87]
	s_setprio 0
	s_setprio 1
	v_mfma_f32_16x16x32_bf16 v[112:115], v[162:165], v[188:191], v[112:115]
	v_mfma_f32_16x16x32_bf16 v[112:115], v[172:175], v[192:195], v[112:115]
	v_mfma_f32_16x16x32_bf16 v[104:107], v[176:179], v[188:191], v[104:107]
	v_mfma_f32_16x16x32_bf16 v[104:107], v[184:187], v[192:195], v[104:107]
	v_mfma_f32_16x16x32_bf16 v[88:91], v[176:179], v[196:199], v[88:91]
	v_mfma_f32_16x16x32_bf16 v[88:91], v[184:187], v[200:203], v[88:91]
	v_mfma_f32_16x16x32_bf16 v[96:99], v[162:165], v[196:199], v[96:99]
	v_mfma_f32_16x16x32_bf16 v[96:99], v[172:175], v[200:203], v[96:99]
	v_mfma_f32_16x16x32_bf16 v[80:83], v[162:165], v[204:207], v[80:83]
	v_mfma_f32_16x16x32_bf16 v[80:83], v[172:175], v[208:211], v[80:83]
	v_mfma_f32_16x16x32_bf16 v[72:75], v[176:179], v[204:207], v[72:75]
	v_mfma_f32_16x16x32_bf16 v[72:75], v[184:187], v[208:211], v[72:75]
	v_mfma_f32_16x16x32_bf16 v[64:67], v[176:179], v[212:215], v[64:67]
	v_mfma_f32_16x16x32_bf16 v[64:67], v[184:187], v[216:219], v[64:67]
	v_mfma_f32_16x16x32_bf16 v[68:71], v[162:165], v[212:215], v[68:71]
	v_mfma_f32_16x16x32_bf16 v[68:71], v[172:175], v[216:219], v[68:71]
	s_setprio 0
	s_barrier
	s_add_i32 s14, s80, s63
	s_mov_b32 m0, s14
	ds_read_b128 v[188:191], v171 offset:16384
	ds_read_b128 v[192:195], v171 offset:17408
	ds_read_b128 v[196:199], v171 offset:18432
	ds_read_b128 v[200:203], v171 offset:19456
	ds_read_b128 v[204:207], v171 offset:20480
	ds_read_b128 v[208:211], v171 offset:21504
	ds_read_b128 v[212:215], v171 offset:22528
	ds_read_b128 v[216:219], v171 offset:23552
	global_load_lds_dwordx4 v146, s[56:57]
	s_add_i32 m0, s14, 0x2000
	s_add_u32 s34, s56, 0x40000
	s_addc_u32 s35, s57, 0
	s_add_i32 s14, s81, s63
	global_load_lds_dwordx4 v150, s[56:57]
	s_mov_b32 m0, s14
	s_nop 0
	global_load_lds_dwordx4 v146, s[34:35]
	s_add_i32 m0, s14, 0x2000
	s_nop 0
	global_load_lds_dwordx4 v150, s[34:35]
	s_mov_b32 m0, s64
	s_nop 0
	global_load_lds_dwordx4 v144, s[58:59]
	s_mov_b32 m0, s65
	s_nop 0
	global_load_lds_dwordx4 v148, s[58:59]
	s_waitcnt vmcnt(8)
	s_waitcnt lgkmcnt(0)
	s_barrier
	s_setprio 1
	s_waitcnt lgkmcnt(0)
	v_mfma_f32_16x16x32_bf16 v[60:63], v[128:131], v[188:191], v[60:63]
	v_mfma_f32_16x16x32_bf16 v[60:63], v[132:135], v[192:195], v[60:63]
	v_mfma_f32_16x16x32_bf16 v[56:59], v[136:139], v[188:191], v[56:59]
	v_mfma_f32_16x16x32_bf16 v[56:59], v[140:143], v[192:195], v[56:59]
	v_mfma_f32_16x16x32_bf16 v[44:47], v[136:139], v[196:199], v[44:47]
	v_mfma_f32_16x16x32_bf16 v[44:47], v[140:143], v[200:203], v[44:47]
	v_mfma_f32_16x16x32_bf16 v[48:51], v[128:131], v[196:199], v[48:51]
	v_mfma_f32_16x16x32_bf16 v[48:51], v[132:135], v[200:203], v[48:51]
	v_mfma_f32_16x16x32_bf16 v[36:39], v[128:131], v[204:207], v[36:39]
	v_mfma_f32_16x16x32_bf16 v[36:39], v[132:135], v[208:211], v[36:39]
	v_mfma_f32_16x16x32_bf16 v[28:31], v[136:139], v[204:207], v[28:31]
	v_mfma_f32_16x16x32_bf16 v[28:31], v[140:143], v[208:211], v[28:31]
	v_mfma_f32_16x16x32_bf16 v[12:15], v[136:139], v[212:215], v[12:15]
	v_mfma_f32_16x16x32_bf16 v[12:15], v[140:143], v[216:219], v[12:15]
	v_mfma_f32_16x16x32_bf16 v[20:23], v[128:131], v[212:215], v[20:23]
	v_mfma_f32_16x16x32_bf16 v[20:23], v[132:135], v[216:219], v[20:23]
	s_setprio 0
	s_setprio 1
	v_mfma_f32_16x16x32_bf16 v[52:55], v[162:165], v[188:191], v[52:55]
	v_mfma_f32_16x16x32_bf16 v[52:55], v[172:175], v[192:195], v[52:55]
	v_mfma_f32_16x16x32_bf16 v[40:43], v[176:179], v[188:191], v[40:43]
	v_mfma_f32_16x16x32_bf16 v[40:43], v[184:187], v[192:195], v[40:43]
	v_mfma_f32_16x16x32_bf16 v[24:27], v[176:179], v[196:199], v[24:27]
	v_mfma_f32_16x16x32_bf16 v[24:27], v[184:187], v[200:203], v[24:27]
	v_mfma_f32_16x16x32_bf16 v[32:35], v[162:165], v[196:199], v[32:35]
	v_mfma_f32_16x16x32_bf16 v[32:35], v[172:175], v[200:203], v[32:35]
	v_mfma_f32_16x16x32_bf16 v[16:19], v[162:165], v[204:207], v[16:19]
	v_mfma_f32_16x16x32_bf16 v[16:19], v[172:175], v[208:211], v[16:19]
	v_mfma_f32_16x16x32_bf16 v[8:11], v[176:179], v[204:207], v[8:11]
	v_mfma_f32_16x16x32_bf16 v[8:11], v[184:187], v[208:211], v[8:11]
	v_mfma_f32_16x16x32_bf16 v[0:3], v[176:179], v[212:215], v[0:3]
	v_mfma_f32_16x16x32_bf16 v[0:3], v[184:187], v[216:219], v[0:3]
	v_mfma_f32_16x16x32_bf16 v[4:7], v[162:165], v[212:215], v[4:7]
	v_mfma_f32_16x16x32_bf16 v[4:7], v[172:175], v[216:219], v[4:7]
	s_setprio 0
	s_barrier
; #define PG8_STAGE(bufoff, gbase, voff) do { _Pragma("unroll") for (int _i = 0; _i < 2; ++_i) \
;         __builtin_amdgcn_global_load_lds((const unsigned*)((const char*)(gbase) + (voff)[_i]), (PG8_LAS unsigned*)(lds + (bufoff) + ldsw + _i * 8192), 16, 0, 0); } while (0)
; #define PG8_LDA(dst, b, h) do { _Pragma("unroll") for (int m = 0; m < 4; ++m) _Pragma("unroll") for (int k = 0; k < 2; ++k) dst[m][k] = *(const PG8_LAS bf16x8*)(lds + PG8_SA(b, h) + aoff + m * 2048 + k * 1024); } while (0)
; #define PG8_LDB(dst, b, h) do { _Pragma("unroll") for (int n = 0; n < 2; ++n) _Pragma("unroll") for (int k = 0; k < 2; ++k) dst[n][k] = *(const PG8_LAS bf16x8*)(lds + PG8_SB(b, h) + boff + n * 2048 + k * 1024); } while (0)
; #define PG8_MMA(ai, bj, At, Bt) do { __builtin_amdgcn_s_setprio(1); _Pragma("unroll") for (int m = 0; m < 4; ++m) _Pragma("unroll") for (int n = 0; n < 2; ++n) _Pragma("unroll") for (int k = 0; k < 2; ++k) \
;         acc[ai][bj][m][n] = __builtin_amdgcn_mfma_f32_16x16x32_bf16(Bt[n][k], At[m][k], acc[ai][bj][m][n], 0, 0, 0); __builtin_amdgcn_s_setprio(0); } while (0)
; #define PG8_WAIT_V(n) asm volatile("s_waitcnt vmcnt(" #n ")" ::: "memory")
; #define PG8_WAIT_L(n) asm volatile("s_waitcnt lgkmcnt(" #n ")" ::: "memory")
; #define PG8_BAR __builtin_amdgcn_s_barrier()
; #define PG8_SCHED __builtin_amdgcn_sched_barrier(0)
; template <class Epi, class Sched, bool ALIGN_EPI = false, bool SP2 = false>
; __device__ __forceinline__ void gemm_phase(PG8_LAS unsigned char* lds, const Gemm g, const Sched& S, const Epi& E) {
;     ...
;             PG8_LDB(B0, 1, 0); PG8_LDB(B1, 1, 1); PG8_SCHED; PG8_LDA(At, 1, 0); PG8_STAGE(PG8_SA(0, 1), a2 + hstep, voffA);
;             PG8_WAIT_V(8); PG8_WAIT_L(0); PG8_BAR; PG8_MMA(0, 0, At, B0); PG8_MMA(0, 1, At, B1); PG8_BAR; PG8_SCHED;
;             PG8_LDA(At, 1, 1); PG8_STAGE(PG8_SB(1, 0), b3, voffB); PG8_STAGE(PG8_SB(1, 1), b3 + hstep, voffB); PG8_STAGE(PG8_SA(1, 0), a3, voffA);
;             PG8_WAIT_V(8); PG8_WAIT_L(0); PG8_BAR; PG8_MMA(1, 0, At, B0); PG8_MMA(1, 1, At, B1); PG8_BAR; PG8_SCHED;
	s_add_i32 s14, 0, 0x18000
	s_add_i32 s15, 0, 0x1c000
	v_add_u32_e32 v140, s14, v167
	v_add_u32_e32 v183, s15, v167
	ds_read_b128 v[128:131], v140
	ds_read_b128 v[132:135], v140 offset:1024
	ds_read_b128 v[136:139], v140 offset:2048
	ds_read_b128 v[140:143], v140 offset:3072
	ds_read_b128 v[162:165], v183
	ds_read_b128 v[172:175], v183 offset:1024
	ds_read_b128 v[176:179], v183 offset:2048
	ds_read_b128 v[184:187], v183 offset:3072
	s_add_u32 s34, s58, 0x40000
	s_addc_u32 s35, s59, 0
	s_mov_b32 m0, s66
	ds_read_b128 v[188:191], v171 offset:32768
	ds_read_b128 v[192:195], v171 offset:33792
	ds_read_b128 v[196:199], v171 offset:34816
	ds_read_b128 v[200:203], v171 offset:35840
	ds_read_b128 v[204:207], v171 offset:36864
	ds_read_b128 v[208:211], v171 offset:37888
	ds_read_b128 v[212:215], v171 offset:38912
	ds_read_b128 v[216:219], v171 offset:39936
	global_load_lds_dwordx4 v144, s[34:35]
	s_mov_b32 m0, s67
	s_nop 0
	global_load_lds_dwordx4 v148, s[34:35]
	s_waitcnt vmcnt(8)
	s_waitcnt lgkmcnt(0)
	s_barrier
	s_setprio 1
	s_waitcnt lgkmcnt(0)
	v_mfma_f32_16x16x32_bf16 v[124:127], v[128:131], v[188:191], v[124:127]
	v_mfma_f32_16x16x32_bf16 v[124:127], v[132:135], v[192:195], v[124:127]
	v_mfma_f32_16x16x32_bf16 v[120:123], v[136:139], v[188:191], v[120:123]
	v_mfma_f32_16x16x32_bf16 v[120:123], v[140:143], v[192:195], v[120:123]
	v_mfma_f32_16x16x32_bf16 v[108:111], v[136:139], v[196:199], v[108:111]
	v_mfma_f32_16x16x32_bf16 v[108:111], v[140:143], v[200:203], v[108:111]
	v_mfma_f32_16x16x32_bf16 v[116:119], v[128:131], v[196:199], v[116:119]
	v_mfma_f32_16x16x32_bf16 v[116:119], v[132:135], v[200:203], v[116:119]
	v_mfma_f32_16x16x32_bf16 v[100:103], v[128:131], v[204:207], v[100:103]
	v_mfma_f32_16x16x32_bf16 v[100:103], v[132:135], v[208:211], v[100:103]
	v_mfma_f32_16x16x32_bf16 v[92:95], v[136:139], v[204:207], v[92:95]
	v_mfma_f32_16x16x32_bf16 v[92:95], v[140:143], v[208:211], v[92:95]
	v_mfma_f32_16x16x32_bf16 v[76:79], v[136:139], v[212:215], v[76:79]
	v_mfma_f32_16x16x32_bf16 v[76:79], v[140:143], v[216:219], v[76:79]
	v_mfma_f32_16x16x32_bf16 v[84:87], v[128:131], v[212:215], v[84:87]
	v_mfma_f32_16x16x32_bf16 v[84:87], v[132:135], v[216:219], v[84:87]
	s_setprio 0
	s_setprio 1
	v_mfma_f32_16x16x32_bf16 v[112:115], v[162:165], v[188:191], v[112:115]
	v_mfma_f32_16x16x32_bf16 v[112:115], v[172:175], v[192:195], v[112:115]
	v_mfma_f32_16x16x32_bf16 v[104:107], v[176:179], v[188:191], v[104:107]
	v_mfma_f32_16x16x32_bf16 v[104:107], v[184:187], v[192:195], v[104:107]
	v_mfma_f32_16x16x32_bf16 v[88:91], v[176:179], v[196:199], v[88:91]
	v_mfma_f32_16x16x32_bf16 v[88:91], v[184:187], v[200:203], v[88:91]
	v_mfma_f32_16x16x32_bf16 v[96:99], v[162:165], v[196:199], v[96:99]
	v_mfma_f32_16x16x32_bf16 v[96:99], v[172:175], v[200:203], v[96:99]
	v_mfma_f32_16x16x32_bf16 v[80:83], v[162:165], v[204:207], v[80:83]
	v_mfma_f32_16x16x32_bf16 v[80:83], v[172:175], v[208:211], v[80:83]
	v_mfma_f32_16x16x32_bf16 v[72:75], v[176:179], v[204:207], v[72:75]
	v_mfma_f32_16x16x32_bf16 v[72:75], v[184:187], v[208:211], v[72:75]
	v_mfma_f32_16x16x32_bf16 v[64:67], v[176:179], v[212:215], v[64:67]
	v_mfma_f32_16x16x32_bf16 v[64:67], v[184:187], v[216:219], v[64:67]
	v_mfma_f32_16x16x32_bf16 v[68:71], v[162:165], v[212:215], v[68:71]
	v_mfma_f32_16x16x32_bf16 v[68:71], v[172:175], v[216:219], v[68:71]
	s_setprio 0
	s_barrier
	s_add_i32 s14, s14, s63
	s_add_u32 s98, s56, s36
	s_addc_u32 s99, s57, s37
	s_add_u32 s100, s58, s36
	s_addc_u32 s101, s59, s37
	s_mov_b32 m0, s14
	ds_read_b128 v[188:191], v171 offset:49152
	ds_read_b128 v[192:195], v171 offset:50176
	ds_read_b128 v[196:199], v171 offset:51200
	ds_read_b128 v[200:203], v171 offset:52224
	ds_read_b128 v[204:207], v171 offset:53248
	ds_read_b128 v[208:211], v171 offset:54272
	ds_read_b128 v[212:215], v171 offset:55296
	ds_read_b128 v[216:219], v171 offset:56320
	global_load_lds_dwordx4 v146, s[98:99]
	s_add_i32 m0, s14, 0x2000
	s_add_u32 s34, s56, 0x40080
	s_addc_u32 s35, s57, 0
	s_add_i32 s14, s15, s63
	global_load_lds_dwordx4 v150, s[98:99]
	s_mov_b32 m0, s14
	s_nop 0
	global_load_lds_dwordx4 v146, s[34:35]
	s_add_i32 m0, s14, 0x2000
	s_nop 0
	global_load_lds_dwordx4 v150, s[34:35]
	s_mov_b32 m0, s74
	s_nop 0
	global_load_lds_dwordx4 v144, s[100:101]
	s_mov_b32 m0, s75
	s_nop 0
	global_load_lds_dwordx4 v148, s[100:101]
	s_waitcnt vmcnt(8)
	s_waitcnt lgkmcnt(0)
	s_barrier
	s_setprio 1
	s_waitcnt lgkmcnt(0)
	v_mfma_f32_16x16x32_bf16 v[60:63], v[128:131], v[188:191], v[60:63]
	v_mfma_f32_16x16x32_bf16 v[60:63], v[132:135], v[192:195], v[60:63]
	v_mfma_f32_16x16x32_bf16 v[56:59], v[136:139], v[188:191], v[56:59]
	v_mfma_f32_16x16x32_bf16 v[56:59], v[140:143], v[192:195], v[56:59]
	v_mfma_f32_16x16x32_bf16 v[44:47], v[136:139], v[196:199], v[44:47]
	v_mfma_f32_16x16x32_bf16 v[44:47], v[140:143], v[200:203], v[44:47]
	v_mfma_f32_16x16x32_bf16 v[48:51], v[128:131], v[196:199], v[48:51]
	v_mfma_f32_16x16x32_bf16 v[48:51], v[132:135], v[200:203], v[48:51]
	v_mfma_f32_16x16x32_bf16 v[36:39], v[128:131], v[204:207], v[36:39]
	v_mfma_f32_16x16x32_bf16 v[36:39], v[132:135], v[208:211], v[36:39]
	v_mfma_f32_16x16x32_bf16 v[28:31], v[136:139], v[204:207], v[28:31]
	v_mfma_f32_16x16x32_bf16 v[28:31], v[140:143], v[208:211], v[28:31]
	v_mfma_f32_16x16x32_bf16 v[12:15], v[136:139], v[212:215], v[12:15]
	v_mfma_f32_16x16x32_bf16 v[12:15], v[140:143], v[216:219], v[12:15]
	v_mfma_f32_16x16x32_bf16 v[20:23], v[128:131], v[212:215], v[20:23]
	v_mfma_f32_16x16x32_bf16 v[20:23], v[132:135], v[216:219], v[20:23]
	s_setprio 0
	s_setprio 1
	v_mfma_f32_16x16x32_bf16 v[52:55], v[162:165], v[188:191], v[52:55]
	v_mfma_f32_16x16x32_bf16 v[52:55], v[172:175], v[192:195], v[52:55]
	v_mfma_f32_16x16x32_bf16 v[40:43], v[176:179], v[188:191], v[40:43]
	v_mfma_f32_16x16x32_bf16 v[40:43], v[184:187], v[192:195], v[40:43]
	v_mfma_f32_16x16x32_bf16 v[24:27], v[176:179], v[196:199], v[24:27]
	v_mfma_f32_16x16x32_bf16 v[24:27], v[184:187], v[200:203], v[24:27]
	v_mfma_f32_16x16x32_bf16 v[32:35], v[162:165], v[196:199], v[32:35]
	v_mfma_f32_16x16x32_bf16 v[32:35], v[172:175], v[200:203], v[32:35]
	v_mfma_f32_16x16x32_bf16 v[16:19], v[162:165], v[204:207], v[16:19]
	v_mfma_f32_16x16x32_bf16 v[16:19], v[172:175], v[208:211], v[16:19]
	v_mfma_f32_16x16x32_bf16 v[8:11], v[176:179], v[204:207], v[8:11]
	v_mfma_f32_16x16x32_bf16 v[8:11], v[184:187], v[208:211], v[8:11]
	v_mfma_f32_16x16x32_bf16 v[0:3], v[176:179], v[212:215], v[0:3]
	v_mfma_f32_16x16x32_bf16 v[0:3], v[184:187], v[216:219], v[0:3]
	v_mfma_f32_16x16x32_bf16 v[4:7], v[162:165], v[212:215], v[4:7]
	v_mfma_f32_16x16x32_bf16 v[4:7], v[172:175], v[216:219], v[4:7]
	s_setprio 0
	s_barrier
	s_add_i32 s84, s84, 2
	s_add_u32 s82, s82, 0x100
	s_addc_u32 s83, s83, 0
	s_add_u32 s54, s54, 0x100
	s_addc_u32 s55, s55, 0
	s_cmp_gt_u32 s84, 13
	s_cbranch_scc0 .LBB0_710
	s_and_b64 vcc, exec, s[40:41]
	s_cbranch_vccz .LBB0_713
	s_barrier

; #define PG8_STAGE(bufoff, gbase, voff) do { _Pragma("unroll") for (int _i = 0; _i < 2; ++_i) \
;         __builtin_amdgcn_global_load_lds((const unsigned*)((const char*)(gbase) + (voff)[_i]), (PG8_LAS unsigned*)(lds + (bufoff) + ldsw + _i * 8192), 16, 0, 0); } while (0)
; #define PG8_LDA(dst, b, h) do { _Pragma("unroll") for (int m = 0; m < 4; ++m) _Pragma("unroll") for (int k = 0; k < 2; ++k) dst[m][k] = *(const PG8_LAS bf16x8*)(lds + PG8_SA(b, h) + aoff + m * 2048 + k * 1024); } while (0)
; #define PG8_LDB(dst, b, h) do { _Pragma("unroll") for (int n = 0; n < 2; ++n) _Pragma("unroll") for (int k = 0; k < 2; ++k) dst[n][k] = *(const PG8_LAS bf16x8*)(lds + PG8_SB(b, h) + boff + n * 2048 + k * 1024); } while (0)
; #define PG8_MMA(ai, bj, At, Bt) do { __builtin_amdgcn_s_setprio(1); _Pragma("unroll") for (int m = 0; m < 4; ++m) _Pragma("unroll") for (int n = 0; n < 2; ++n) _Pragma("unroll") for (int k = 0; k < 2; ++k) \
;         acc[ai][bj][m][n] = __builtin_amdgcn_mfma_f32_16x16x32_bf16(Bt[n][k], At[m][k], acc[ai][bj][m][n], 0, 0, 0); __builtin_amdgcn_s_setprio(0); } while (0)
; #define PG8_WAIT_V(n) asm volatile("s_waitcnt vmcnt(" #n ")" ::: "memory")
; #define PG8_WAIT_L(n) asm volatile("s_waitcnt lgkmcnt(" #n ")" ::: "memory")
; #define PG8_BAR __builtin_amdgcn_s_barrier()
; #define PG8_SCHED __builtin_amdgcn_sched_barrier(0)
; template <class Epi, class Sched, bool ALIGN_EPI = false, bool SP2 = false>
; __device__ __forceinline__ void gemm_phase(PG8_LAS unsigned char* lds, const Gemm g, const Sched& S, const Epi& E) {
;     ...
;             PG8_LDB(B0, 0, 0); PG8_LDB(B1, 0, 1); PG8_SCHED; PG8_LDA(At, 0, 0); PG8_STAGE(PG8_SA(1, 1), a1 + hstep, voffA);
;             PG8_WAIT_V(8); PG8_WAIT_L(0); PG8_BAR; PG8_MMA(0, 0, At, B0); PG8_MMA(0, 1, At, B1); PG8_BAR; PG8_SCHED;
;             PG8_LDA(At, 0, 1); PG8_STAGE(PG8_SB(0, 0), b2, voffB); PG8_STAGE(PG8_SB(0, 1), b2 + hstep, voffB); PG8_STAGE(PG8_SA(0, 0), a2, voffA);
;             PG8_WAIT_V(8); PG8_WAIT_L(0); PG8_BAR; PG8_MMA(1, 0, At, B0); PG8_MMA(1, 1, At, B1); PG8_BAR; PG8_SCHED;
.LBB0_796:
	v_add_u32_e32 v130, s76, v165
	ds_read_b128 v[118:121], v130
	ds_read_b128 v[122:125], v130 offset:1024
	ds_read_b128 v[126:129], v130 offset:2048
	ds_read_b128 v[172:175], v130 offset:3072
	v_add_u32_e32 v130, s77, v165
	ds_read_b128 v[176:179], v130
	ds_read_b128 v[184:187], v130 offset:1024
	ds_read_b128 v[188:191], v130 offset:2048
	ds_read_b128 v[192:195], v130 offset:3072
	s_add_u32 s12, s52, 0xfffc0080
	s_addc_u32 s13, s53, -1
	s_and_b64 s[34:35], s[54:55], exec
	s_cselect_b32 s57, s43, s13
	s_cselect_b32 s56, s78, s12
	s_cselect_b32 s55, s41, s51
	s_cselect_b32 s54, s79, s49
	s_add_i32 m0, s62, 0xc000
	ds_read_b128 v[196:199], v170
	ds_read_b128 v[200:203], v170 offset:1024
	ds_read_b128 v[204:207], v170 offset:2048
	ds_read_b128 v[208:211], v170 offset:3072
	ds_read_b128 v[212:215], v170 offset:4096
	ds_read_b128 v[216:219], v170 offset:5120
	ds_read_b128 v[220:223], v170 offset:6144
	ds_read_b128 v[224:227], v170 offset:7168
	global_load_lds_dwordx4 v154, s[52:53]
	s_add_i32 m0, s62, 0xe000
	s_nop 0
	global_load_lds_dwordx4 v152, s[52:53]
	s_waitcnt vmcnt(8)
	s_waitcnt lgkmcnt(0)
	s_barrier
	s_setprio 1
	s_waitcnt lgkmcnt(0)
	v_mfma_f32_16x16x32_bf16 v[140:143], v[118:121], v[196:199], v[140:143]
	v_mfma_f32_16x16x32_bf16 v[140:143], v[122:125], v[200:203], v[140:143]
	v_mfma_f32_16x16x32_bf16 v[136:139], v[126:129], v[196:199], v[136:139]
	v_mfma_f32_16x16x32_bf16 v[136:139], v[172:175], v[200:203], v[136:139]
	v_mfma_f32_16x16x32_bf16 v[104:107], v[126:129], v[204:207], v[104:107]
	v_mfma_f32_16x16x32_bf16 v[104:107], v[172:175], v[208:211], v[104:107]
	v_mfma_f32_16x16x32_bf16 v[108:111], v[118:121], v[204:207], v[108:111]
	v_mfma_f32_16x16x32_bf16 v[108:111], v[122:125], v[208:211], v[108:111]
	v_mfma_f32_16x16x32_bf16 v[92:95], v[118:121], v[212:215], v[92:95]
	v_mfma_f32_16x16x32_bf16 v[92:95], v[122:125], v[216:219], v[92:95]
	v_mfma_f32_16x16x32_bf16 v[88:91], v[126:129], v[212:215], v[88:91]
	v_mfma_f32_16x16x32_bf16 v[88:91], v[172:175], v[216:219], v[88:91]
	v_mfma_f32_16x16x32_bf16 v[72:75], v[126:129], v[220:223], v[72:75]
	v_mfma_f32_16x16x32_bf16 v[72:75], v[172:175], v[224:227], v[72:75]
	v_mfma_f32_16x16x32_bf16 v[76:79], v[118:121], v[220:223], v[76:79]
	v_mfma_f32_16x16x32_bf16 v[76:79], v[122:125], v[224:227], v[76:79]
	s_setprio 0
	s_setprio 1
	v_mfma_f32_16x16x32_bf16 v[130:133], v[176:179], v[196:199], v[132:135]
	v_mfma_f32_16x16x32_bf16 v[130:133], v[184:187], v[200:203], v[130:133]
	v_mfma_f32_16x16x32_bf16 v[112:115], v[188:191], v[196:199], v[112:115]
	v_mfma_f32_16x16x32_bf16 v[112:115], v[192:195], v[200:203], v[112:115]
	v_mfma_f32_16x16x32_bf16 v[96:99], v[188:191], v[204:207], v[96:99]
	v_mfma_f32_16x16x32_bf16 v[96:99], v[192:195], v[208:211], v[96:99]
	v_mfma_f32_16x16x32_bf16 v[100:103], v[176:179], v[204:207], v[100:103]
	v_mfma_f32_16x16x32_bf16 v[100:103], v[184:187], v[208:211], v[100:103]
	v_mfma_f32_16x16x32_bf16 v[84:87], v[176:179], v[212:215], v[84:87]
	v_mfma_f32_16x16x32_bf16 v[84:87], v[184:187], v[216:219], v[84:87]
	v_mfma_f32_16x16x32_bf16 v[80:83], v[188:191], v[212:215], v[80:83]
	v_mfma_f32_16x16x32_bf16 v[80:83], v[192:195], v[216:219], v[80:83]
	v_mfma_f32_16x16x32_bf16 v[64:67], v[188:191], v[220:223], v[64:67]
	v_mfma_f32_16x16x32_bf16 v[64:67], v[192:195], v[224:227], v[64:67]
	v_mfma_f32_16x16x32_bf16 v[68:71], v[176:179], v[220:223], v[68:71]
	v_mfma_f32_16x16x32_bf16 v[68:71], v[184:187], v[224:227], v[68:71]
	s_setprio 0
	s_barrier
	s_add_i32 s12, s76, s59
	s_mov_b32 m0, s12
	ds_read_b128 v[196:199], v170 offset:16384
	ds_read_b128 v[200:203], v170 offset:17408
	ds_read_b128 v[204:207], v170 offset:18432
	ds_read_b128 v[208:211], v170 offset:19456
	ds_read_b128 v[212:215], v170 offset:20480
	ds_read_b128 v[216:219], v170 offset:21504
	ds_read_b128 v[220:223], v170 offset:22528
	ds_read_b128 v[224:227], v170 offset:23552
	global_load_lds_dwordx4 v148, s[54:55]
	s_add_i32 m0, s12, 0x2000
	s_add_u32 s34, s54, 0x40000
	s_addc_u32 s35, s55, 0
	s_add_i32 s12, s77, s59
	global_load_lds_dwordx4 v144, s[54:55]
	s_mov_b32 m0, s12
	s_nop 0
	global_load_lds_dwordx4 v148, s[34:35]
	s_add_i32 m0, s12, 0x2000
	s_nop 0
	global_load_lds_dwordx4 v144, s[34:35]
	s_mov_b32 m0, s62
	s_nop 0
	global_load_lds_dwordx4 v150, s[56:57]
	s_mov_b32 m0, s63
	s_nop 0
	global_load_lds_dwordx4 v146, s[56:57]
	s_waitcnt vmcnt(8)
	s_waitcnt lgkmcnt(0)
	s_barrier
	s_setprio 1
	s_waitcnt lgkmcnt(0)
	v_mfma_f32_16x16x32_bf16 v[60:63], v[118:121], v[196:199], v[60:63]
	v_mfma_f32_16x16x32_bf16 v[60:63], v[122:125], v[200:203], v[60:63]
	v_mfma_f32_16x16x32_bf16 v[56:59], v[126:129], v[196:199], v[56:59]
	v_mfma_f32_16x16x32_bf16 v[56:59], v[172:175], v[200:203], v[56:59]
	v_mfma_f32_16x16x32_bf16 v[40:43], v[126:129], v[204:207], v[40:43]
	v_mfma_f32_16x16x32_bf16 v[40:43], v[172:175], v[208:211], v[40:43]
	v_mfma_f32_16x16x32_bf16 v[44:47], v[118:121], v[204:207], v[44:47]
	v_mfma_f32_16x16x32_bf16 v[44:47], v[122:125], v[208:211], v[44:47]
	v_mfma_f32_16x16x32_bf16 v[28:31], v[118:121], v[212:215], v[28:31]
	v_mfma_f32_16x16x32_bf16 v[28:31], v[122:125], v[216:219], v[28:31]
	v_mfma_f32_16x16x32_bf16 v[24:27], v[126:129], v[212:215], v[24:27]
	v_mfma_f32_16x16x32_bf16 v[24:27], v[172:175], v[216:219], v[24:27]
	v_mfma_f32_16x16x32_bf16 v[8:11], v[126:129], v[220:223], v[8:11]
	v_mfma_f32_16x16x32_bf16 v[8:11], v[172:175], v[224:227], v[8:11]
	v_mfma_f32_16x16x32_bf16 v[12:15], v[118:121], v[220:223], v[12:15]
	v_mfma_f32_16x16x32_bf16 v[12:15], v[122:125], v[224:227], v[12:15]
	s_setprio 0
	s_setprio 1
	v_mfma_f32_16x16x32_bf16 v[52:55], v[176:179], v[196:199], v[52:55]
	v_mfma_f32_16x16x32_bf16 v[52:55], v[184:187], v[200:203], v[52:55]
	v_mfma_f32_16x16x32_bf16 v[48:51], v[188:191], v[196:199], v[48:51]
	v_mfma_f32_16x16x32_bf16 v[48:51], v[192:195], v[200:203], v[48:51]
	v_mfma_f32_16x16x32_bf16 v[32:35], v[188:191], v[204:207], v[32:35]
	v_mfma_f32_16x16x32_bf16 v[32:35], v[192:195], v[208:211], v[32:35]
	v_mfma_f32_16x16x32_bf16 v[36:39], v[176:179], v[204:207], v[36:39]
	v_mfma_f32_16x16x32_bf16 v[36:39], v[184:187], v[208:211], v[36:39]
	v_mfma_f32_16x16x32_bf16 v[20:23], v[176:179], v[212:215], v[20:23]
	v_mfma_f32_16x16x32_bf16 v[20:23], v[184:187], v[216:219], v[20:23]
	v_mfma_f32_16x16x32_bf16 v[16:19], v[188:191], v[212:215], v[16:19]
	v_mfma_f32_16x16x32_bf16 v[16:19], v[192:195], v[216:219], v[16:19]
	v_mfma_f32_16x16x32_bf16 v[0:3], v[188:191], v[220:223], v[0:3]
	v_mfma_f32_16x16x32_bf16 v[0:3], v[192:195], v[224:227], v[0:3]
	v_mfma_f32_16x16x32_bf16 v[4:7], v[176:179], v[220:223], v[4:7]
	v_mfma_f32_16x16x32_bf16 v[4:7], v[184:187], v[224:227], v[4:7]
	s_setprio 0
	s_barrier
; #define PG8_STAGE(bufoff, gbase, voff) do { _Pragma("unroll") for (int _i = 0; _i < 2; ++_i) \
;         __builtin_amdgcn_global_load_lds((const unsigned*)((const char*)(gbase) + (voff)[_i]), (PG8_LAS unsigned*)(lds + (bufoff) + ldsw + _i * 8192), 16, 0, 0); } while (0)
; #define PG8_LDA(dst, b, h) do { _Pragma("unroll") for (int m = 0; m < 4; ++m) _Pragma("unroll") for (int k = 0; k < 2; ++k) dst[m][k] = *(const PG8_LAS bf16x8*)(lds + PG8_SA(b, h) + aoff + m * 2048 + k * 1024); } while (0)
; #define PG8_LDB(dst, b, h) do { _Pragma("unroll") for (int n = 0; n < 2; ++n) _Pragma("unroll") for (int k = 0; k < 2; ++k) dst[n][k] = *(const PG8_LAS bf16x8*)(lds + PG8_SB(b, h) + boff + n * 2048 + k * 1024); } while (0)
; #define PG8_MMA(ai, bj, At, Bt) do { __builtin_amdgcn_s_setprio(1); _Pragma("unroll") for (int m = 0; m < 4; ++m) _Pragma("unroll") for (int n = 0; n < 2; ++n) _Pragma("unroll") for (int k = 0; k < 2; ++k) \
;         acc[ai][bj][m][n] = __builtin_amdgcn_mfma_f32_16x16x32_bf16(Bt[n][k], At[m][k], acc[ai][bj][m][n], 0, 0, 0); __builtin_amdgcn_s_setprio(0); } while (0)
; #define PG8_WAIT_V(n) asm volatile("s_waitcnt vmcnt(" #n ")" ::: "memory")
; #define PG8_WAIT_L(n) asm volatile("s_waitcnt lgkmcnt(" #n ")" ::: "memory")
; #define PG8_BAR __builtin_amdgcn_s_barrier()
; #define PG8_SCHED __builtin_amdgcn_sched_barrier(0)
; template <class Epi, class Sched, bool ALIGN_EPI = false, bool SP2 = false>
; __device__ __forceinline__ void gemm_phase(PG8_LAS unsigned char* lds, const Gemm g, const Sched& S, const Epi& E) {
;     ...
;             PG8_LDB(B0, 1, 0); PG8_LDB(B1, 1, 1); PG8_SCHED; PG8_LDA(At, 1, 0); PG8_STAGE(PG8_SA(0, 1), a2 + hstep, voffA);
;             PG8_WAIT_V(8); PG8_WAIT_L(0); PG8_BAR; PG8_MMA(0, 0, At, B0); PG8_MMA(0, 1, At, B1); PG8_BAR; PG8_SCHED;
;             PG8_LDA(At, 1, 1); PG8_STAGE(PG8_SB(1, 0), b3, voffB); PG8_STAGE(PG8_SB(1, 1), b3 + hstep, voffB); PG8_STAGE(PG8_SA(1, 0), a3, voffA);
;             PG8_WAIT_V(8); PG8_WAIT_L(0); PG8_BAR; PG8_MMA(1, 0, At, B0); PG8_MMA(1, 1, At, B1); PG8_BAR; PG8_SCHED;
	s_add_i32 s12, 0, 0x18000
	v_add_u32_e32 v134, s12, v165
	s_add_i32 s13, 0, 0x1c000
	ds_read_b128 v[118:121], v134
	ds_read_b128 v[122:125], v134 offset:1024
	ds_read_b128 v[126:129], v134 offset:2048
	ds_read_b128 v[172:175], v134 offset:3072
	v_add_u32_e32 v134, s13, v165
	ds_read_b128 v[176:179], v134
	ds_read_b128 v[184:187], v134 offset:1024
	ds_read_b128 v[188:191], v134 offset:2048
	ds_read_b128 v[192:195], v134 offset:3072
	s_add_u32 s34, s56, 0x40000
	s_addc_u32 s35, s57, 0
	s_mov_b32 m0, s64
	ds_read_b128 v[196:199], v170 offset:32768
	ds_read_b128 v[200:203], v170 offset:33792
	ds_read_b128 v[204:207], v170 offset:34816
	ds_read_b128 v[208:211], v170 offset:35840
	ds_read_b128 v[212:215], v170 offset:36864
	ds_read_b128 v[216:219], v170 offset:37888
	ds_read_b128 v[220:223], v170 offset:38912
	ds_read_b128 v[224:227], v170 offset:39936
	global_load_lds_dwordx4 v150, s[34:35]
	s_mov_b32 m0, s65
	s_nop 0
	global_load_lds_dwordx4 v146, s[34:35]
	s_waitcnt vmcnt(8)
	s_waitcnt lgkmcnt(0)
	s_barrier
	s_setprio 1
	s_waitcnt lgkmcnt(0)
	v_mfma_f32_16x16x32_bf16 v[140:143], v[118:121], v[196:199], v[140:143]
	v_mfma_f32_16x16x32_bf16 v[140:143], v[122:125], v[200:203], v[140:143]
	v_mfma_f32_16x16x32_bf16 v[134:137], v[126:129], v[196:199], v[136:139]
	v_mfma_f32_16x16x32_bf16 v[136:139], v[172:175], v[200:203], v[134:137]
	v_mfma_f32_16x16x32_bf16 v[104:107], v[126:129], v[204:207], v[104:107]
	v_mfma_f32_16x16x32_bf16 v[104:107], v[172:175], v[208:211], v[104:107]
	v_mfma_f32_16x16x32_bf16 v[108:111], v[118:121], v[204:207], v[108:111]
	v_mfma_f32_16x16x32_bf16 v[108:111], v[122:125], v[208:211], v[108:111]
	v_mfma_f32_16x16x32_bf16 v[92:95], v[118:121], v[212:215], v[92:95]
	v_mfma_f32_16x16x32_bf16 v[92:95], v[122:125], v[216:219], v[92:95]
	v_mfma_f32_16x16x32_bf16 v[88:91], v[126:129], v[212:215], v[88:91]
	v_mfma_f32_16x16x32_bf16 v[88:91], v[172:175], v[216:219], v[88:91]
	v_mfma_f32_16x16x32_bf16 v[72:75], v[126:129], v[220:223], v[72:75]
	v_mfma_f32_16x16x32_bf16 v[72:75], v[172:175], v[224:227], v[72:75]
	v_mfma_f32_16x16x32_bf16 v[76:79], v[118:121], v[220:223], v[76:79]
	v_mfma_f32_16x16x32_bf16 v[76:79], v[122:125], v[224:227], v[76:79]
	s_setprio 0
	s_setprio 1
	v_mfma_f32_16x16x32_bf16 v[130:133], v[176:179], v[196:199], v[130:133]
	v_mfma_f32_16x16x32_bf16 v[132:135], v[184:187], v[200:203], v[130:133]
	v_mfma_f32_16x16x32_bf16 v[112:115], v[188:191], v[196:199], v[112:115]
	v_mfma_f32_16x16x32_bf16 v[112:115], v[192:195], v[200:203], v[112:115]
	v_mfma_f32_16x16x32_bf16 v[96:99], v[188:191], v[204:207], v[96:99]
	v_mfma_f32_16x16x32_bf16 v[96:99], v[192:195], v[208:211], v[96:99]
	v_mfma_f32_16x16x32_bf16 v[100:103], v[176:179], v[204:207], v[100:103]
	v_mfma_f32_16x16x32_bf16 v[100:103], v[184:187], v[208:211], v[100:103]
	v_mfma_f32_16x16x32_bf16 v[84:87], v[176:179], v[212:215], v[84:87]
	v_mfma_f32_16x16x32_bf16 v[84:87], v[184:187], v[216:219], v[84:87]
	v_mfma_f32_16x16x32_bf16 v[80:83], v[188:191], v[212:215], v[80:83]
	v_mfma_f32_16x16x32_bf16 v[80:83], v[192:195], v[216:219], v[80:83]
	v_mfma_f32_16x16x32_bf16 v[64:67], v[188:191], v[220:223], v[64:67]
	v_mfma_f32_16x16x32_bf16 v[64:67], v[192:195], v[224:227], v[64:67]
	v_mfma_f32_16x16x32_bf16 v[68:71], v[176:179], v[220:223], v[68:71]
	v_mfma_f32_16x16x32_bf16 v[68:71], v[184:187], v[224:227], v[68:71]
	s_setprio 0
	s_barrier
	s_add_i32 s12, s12, s59
	s_add_u32 s98, s54, s18
	s_addc_u32 s99, s55, s19
	s_add_u32 s100, s56, s18
	s_addc_u32 s101, s57, s19
	s_mov_b32 m0, s12
	ds_read_b128 v[196:199], v170 offset:49152
	ds_read_b128 v[200:203], v170 offset:50176
	ds_read_b128 v[204:207], v170 offset:51200
	ds_read_b128 v[208:211], v170 offset:52224
	ds_read_b128 v[212:215], v170 offset:53248
	ds_read_b128 v[216:219], v170 offset:54272
	ds_read_b128 v[220:223], v170 offset:55296
	ds_read_b128 v[224:227], v170 offset:56320
	global_load_lds_dwordx4 v148, s[98:99]
	s_add_i32 m0, s12, 0x2000
	s_add_u32 s34, s54, 0x40080
	s_addc_u32 s35, s55, 0
	s_add_i32 s12, s13, s59
	global_load_lds_dwordx4 v144, s[98:99]
	s_mov_b32 m0, s12
	s_nop 0
	global_load_lds_dwordx4 v148, s[34:35]
	s_add_i32 m0, s12, 0x2000
	s_nop 0
	global_load_lds_dwordx4 v144, s[34:35]
	s_mov_b32 m0, s68
	s_nop 0
	global_load_lds_dwordx4 v150, s[100:101]
	s_mov_b32 m0, s69
	s_nop 0
	global_load_lds_dwordx4 v146, s[100:101]
	s_waitcnt vmcnt(8)
	s_waitcnt lgkmcnt(0)
	s_barrier
	s_setprio 1
	s_waitcnt lgkmcnt(0)
	v_mfma_f32_16x16x32_bf16 v[60:63], v[118:121], v[196:199], v[60:63]
	v_mfma_f32_16x16x32_bf16 v[60:63], v[122:125], v[200:203], v[60:63]
	v_mfma_f32_16x16x32_bf16 v[56:59], v[126:129], v[196:199], v[56:59]
	v_mfma_f32_16x16x32_bf16 v[56:59], v[172:175], v[200:203], v[56:59]
	v_mfma_f32_16x16x32_bf16 v[40:43], v[126:129], v[204:207], v[40:43]
	v_mfma_f32_16x16x32_bf16 v[40:43], v[172:175], v[208:211], v[40:43]
	v_mfma_f32_16x16x32_bf16 v[44:47], v[118:121], v[204:207], v[44:47]
	v_mfma_f32_16x16x32_bf16 v[44:47], v[122:125], v[208:211], v[44:47]
	v_mfma_f32_16x16x32_bf16 v[28:31], v[118:121], v[212:215], v[28:31]
	v_mfma_f32_16x16x32_bf16 v[28:31], v[122:125], v[216:219], v[28:31]
	v_mfma_f32_16x16x32_bf16 v[24:27], v[126:129], v[212:215], v[24:27]
	v_mfma_f32_16x16x32_bf16 v[24:27], v[172:175], v[216:219], v[24:27]
	v_mfma_f32_16x16x32_bf16 v[8:11], v[126:129], v[220:223], v[8:11]
	v_mfma_f32_16x16x32_bf16 v[8:11], v[172:175], v[224:227], v[8:11]
	v_mfma_f32_16x16x32_bf16 v[12:15], v[118:121], v[220:223], v[12:15]
	v_mfma_f32_16x16x32_bf16 v[12:15], v[122:125], v[224:227], v[12:15]
	s_setprio 0
	s_setprio 1
	v_mfma_f32_16x16x32_bf16 v[52:55], v[176:179], v[196:199], v[52:55]
	v_mfma_f32_16x16x32_bf16 v[52:55], v[184:187], v[200:203], v[52:55]
	v_mfma_f32_16x16x32_bf16 v[48:51], v[188:191], v[196:199], v[48:51]
	v_mfma_f32_16x16x32_bf16 v[48:51], v[192:195], v[200:203], v[48:51]
	v_mfma_f32_16x16x32_bf16 v[32:35], v[188:191], v[204:207], v[32:35]
	v_mfma_f32_16x16x32_bf16 v[32:35], v[192:195], v[208:211], v[32:35]
	v_mfma_f32_16x16x32_bf16 v[36:39], v[176:179], v[204:207], v[36:39]
	v_mfma_f32_16x16x32_bf16 v[36:39], v[184:187], v[208:211], v[36:39]
	v_mfma_f32_16x16x32_bf16 v[20:23], v[176:179], v[212:215], v[20:23]
	v_mfma_f32_16x16x32_bf16 v[20:23], v[184:187], v[216:219], v[20:23]
	v_mfma_f32_16x16x32_bf16 v[16:19], v[188:191], v[212:215], v[16:19]
	v_mfma_f32_16x16x32_bf16 v[16:19], v[192:195], v[216:219], v[16:19]
	v_mfma_f32_16x16x32_bf16 v[0:3], v[188:191], v[220:223], v[0:3]
	v_mfma_f32_16x16x32_bf16 v[0:3], v[192:195], v[224:227], v[0:3]
	v_mfma_f32_16x16x32_bf16 v[4:7], v[176:179], v[220:223], v[4:7]
	v_mfma_f32_16x16x32_bf16 v[4:7], v[184:187], v[224:227], v[4:7]
	s_setprio 0
	s_barrier
	s_add_i32 s80, s80, 2
	s_add_u32 s49, s49, 0x100
	s_addc_u32 s51, s51, 0
	s_add_u32 s52, s52, 0x100
	s_addc_u32 s53, s53, 0
	s_cmp_gt_u32 s80, 13
	s_cbranch_scc1 .LBB0_799

; #define PG8_STAGE(bufoff, gbase, voff) do { _Pragma("unroll") for (int _i = 0; _i < 2; ++_i) \
;         __builtin_amdgcn_global_load_lds((const unsigned*)((const char*)(gbase) + (voff)[_i]), (PG8_LAS unsigned*)(lds + (bufoff) + ldsw + _i * 8192), 16, 0, 0); } while (0)
; #define PG8_LDA(dst, b, h) do { _Pragma("unroll") for (int m = 0; m < 4; ++m) _Pragma("unroll") for (int k = 0; k < 2; ++k) dst[m][k] = *(const PG8_LAS bf16x8*)(lds + PG8_SA(b, h) + aoff + m * 2048 + k * 1024); } while (0)
; #define PG8_LDB(dst, b, h) do { _Pragma("unroll") for (int n = 0; n < 2; ++n) _Pragma("unroll") for (int k = 0; k < 2; ++k) dst[n][k] = *(const PG8_LAS bf16x8*)(lds + PG8_SB(b, h) + boff + n * 2048 + k * 1024); } while (0)
; #define PG8_MMA(ai, bj, At, Bt) do { __builtin_amdgcn_s_setprio(1); _Pragma("unroll") for (int m = 0; m < 4; ++m) _Pragma("unroll") for (int n = 0; n < 2; ++n) _Pragma("unroll") for (int k = 0; k < 2; ++k) \
;         acc[ai][bj][m][n] = __builtin_amdgcn_mfma_f32_16x16x32_bf16(Bt[n][k], At[m][k], acc[ai][bj][m][n], 0, 0, 0); __builtin_amdgcn_s_setprio(0); } while (0)
; #define PG8_WAIT_V(n) asm volatile("s_waitcnt vmcnt(" #n ")" ::: "memory")
; #define PG8_WAIT_L(n) asm volatile("s_waitcnt lgkmcnt(" #n ")" ::: "memory")
; #define PG8_BAR __builtin_amdgcn_s_barrier()
; #define PG8_SCHED __builtin_amdgcn_sched_barrier(0)
; template <class Epi, class Sched, bool ALIGN_EPI = false, bool SP2 = false>
; __device__ __forceinline__ void gemm_phase(PG8_LAS unsigned char* lds, const Gemm g, const Sched& S, const Epi& E) {
;     ...
;             PG8_LDB(B0, 0, 0); PG8_LDB(B1, 0, 1); PG8_SCHED; PG8_LDA(At, 0, 0); PG8_STAGE(PG8_SA(1, 1), a1 + hstep, voffA);
;             PG8_WAIT_V(8); PG8_WAIT_L(0); PG8_BAR; PG8_MMA(0, 0, At, B0); PG8_MMA(0, 1, At, B1); PG8_BAR; PG8_SCHED;
;             PG8_LDA(At, 0, 1); PG8_STAGE(PG8_SB(0, 0), b2, voffB); PG8_STAGE(PG8_SB(0, 1), b2 + hstep, voffB); PG8_STAGE(PG8_SA(0, 0), a2, voffA);
;             PG8_WAIT_V(8); PG8_WAIT_L(0); PG8_BAR; PG8_MMA(1, 0, At, B0); PG8_MMA(1, 1, At, B1); PG8_BAR; PG8_SCHED;
.LBB0_872:
	ds_read_b128 v[128:131], v169
	ds_read_b128 v[132:135], v169 offset:1024
	ds_read_b128 v[136:139], v169 offset:2048
	ds_read_b128 v[140:143], v169 offset:3072
	ds_read_b128 v[162:165], v170
	ds_read_b128 v[172:175], v170 offset:1024
	ds_read_b128 v[176:179], v170 offset:2048
	ds_read_b128 v[184:187], v170 offset:3072
	s_add_u32 s42, s40, 0x100
	s_addc_u32 s43, s41, 0
	s_cmp_eq_u32 s74, 40
	s_cselect_b32 s47, s11, s43
	s_cselect_b32 s46, s10, s42
	s_cselect_b32 s45, s37, s73
	s_cselect_b32 s44, s36, s71
	v_lshl_add_u64 v[180:181], s[40:41], 0, v[154:155]
	s_add_i32 m0, s50, 0xc000
	ds_read_b128 v[188:191], v171
	ds_read_b128 v[192:195], v171 offset:1024
	ds_read_b128 v[196:199], v171 offset:2048
	ds_read_b128 v[200:203], v171 offset:3072
	ds_read_b128 v[204:207], v171 offset:4096
	ds_read_b128 v[208:211], v171 offset:5120
	ds_read_b128 v[212:215], v171 offset:6144
	ds_read_b128 v[216:219], v171 offset:7168
	global_load_lds_dwordx4 v[180:181], off
	v_lshl_add_u64 v[180:181], s[40:41], 0, v[152:153]
	s_add_i32 m0, s50, 0xe000
	s_nop 0
	global_load_lds_dwordx4 v[180:181], off
	s_waitcnt vmcnt(8)
	s_waitcnt lgkmcnt(0)
	s_barrier
	s_setprio 1
	s_waitcnt lgkmcnt(0)
	v_mfma_f32_16x16x32_bf16 v[124:127], v[128:131], v[188:191], v[124:127]
	v_mfma_f32_16x16x32_bf16 v[124:127], v[132:135], v[192:195], v[124:127]
	v_mfma_f32_16x16x32_bf16 v[120:123], v[136:139], v[188:191], v[120:123]
	v_mfma_f32_16x16x32_bf16 v[120:123], v[140:143], v[192:195], v[120:123]
	v_mfma_f32_16x16x32_bf16 v[108:111], v[136:139], v[196:199], v[108:111]
	v_mfma_f32_16x16x32_bf16 v[108:111], v[140:143], v[200:203], v[108:111]
	v_mfma_f32_16x16x32_bf16 v[116:119], v[128:131], v[196:199], v[116:119]
	v_mfma_f32_16x16x32_bf16 v[116:119], v[132:135], v[200:203], v[116:119]
	v_mfma_f32_16x16x32_bf16 v[100:103], v[128:131], v[204:207], v[100:103]
	v_mfma_f32_16x16x32_bf16 v[100:103], v[132:135], v[208:211], v[100:103]
	v_mfma_f32_16x16x32_bf16 v[92:95], v[136:139], v[204:207], v[92:95]
	v_mfma_f32_16x16x32_bf16 v[92:95], v[140:143], v[208:211], v[92:95]
	v_mfma_f32_16x16x32_bf16 v[76:79], v[136:139], v[212:215], v[76:79]
	v_mfma_f32_16x16x32_bf16 v[76:79], v[140:143], v[216:219], v[76:79]
	v_mfma_f32_16x16x32_bf16 v[84:87], v[128:131], v[212:215], v[84:87]
	v_mfma_f32_16x16x32_bf16 v[84:87], v[132:135], v[216:219], v[84:87]
	s_setprio 0
	s_setprio 1
	v_mfma_f32_16x16x32_bf16 v[112:115], v[162:165], v[188:191], v[112:115]
	v_mfma_f32_16x16x32_bf16 v[112:115], v[172:175], v[192:195], v[112:115]
	v_mfma_f32_16x16x32_bf16 v[104:107], v[176:179], v[188:191], v[104:107]
	v_mfma_f32_16x16x32_bf16 v[104:107], v[184:187], v[192:195], v[104:107]
	v_mfma_f32_16x16x32_bf16 v[88:91], v[176:179], v[196:199], v[88:91]
	v_mfma_f32_16x16x32_bf16 v[88:91], v[184:187], v[200:203], v[88:91]
	v_mfma_f32_16x16x32_bf16 v[96:99], v[162:165], v[196:199], v[96:99]
	v_mfma_f32_16x16x32_bf16 v[96:99], v[172:175], v[200:203], v[96:99]
	v_mfma_f32_16x16x32_bf16 v[80:83], v[162:165], v[204:207], v[80:83]
	v_mfma_f32_16x16x32_bf16 v[80:83], v[172:175], v[208:211], v[80:83]
	v_mfma_f32_16x16x32_bf16 v[72:75], v[176:179], v[204:207], v[72:75]
	v_mfma_f32_16x16x32_bf16 v[72:75], v[184:187], v[208:211], v[72:75]
	v_mfma_f32_16x16x32_bf16 v[64:67], v[176:179], v[212:215], v[64:67]
	v_mfma_f32_16x16x32_bf16 v[64:67], v[184:187], v[216:219], v[64:67]
	v_mfma_f32_16x16x32_bf16 v[68:71], v[162:165], v[212:215], v[68:71]
	v_mfma_f32_16x16x32_bf16 v[68:71], v[172:175], v[216:219], v[68:71]
	s_setprio 0
	s_barrier
	s_add_i32 s12, s65, s49
	s_mov_b32 m0, s12
	ds_read_b128 v[188:191], v171 offset:16384
	ds_read_b128 v[192:195], v171 offset:17408
	ds_read_b128 v[196:199], v171 offset:18432
	ds_read_b128 v[200:203], v171 offset:19456
	ds_read_b128 v[204:207], v171 offset:20480
	ds_read_b128 v[208:211], v171 offset:21504
	ds_read_b128 v[212:215], v171 offset:22528
	ds_read_b128 v[216:219], v171 offset:23552
	global_load_lds_dwordx4 v146, s[44:45]
	s_add_i32 m0, s12, 0x2000
	s_add_u32 s40, s44, 0xb0000
	s_addc_u32 s41, s45, 0
	s_add_i32 s12, s66, s49
	global_load_lds_dwordx4 v150, s[44:45]
	s_mov_b32 m0, s12
	s_nop 0
	global_load_lds_dwordx4 v146, s[40:41]
	s_add_i32 m0, s12, 0x2000
	s_nop 0
	global_load_lds_dwordx4 v150, s[40:41]
	s_mov_b32 m0, s50
	s_nop 0
	global_load_lds_dwordx4 v144, s[46:47]
	s_mov_b32 m0, s51
	s_nop 0
	global_load_lds_dwordx4 v148, s[46:47]
	s_waitcnt vmcnt(8)
	s_waitcnt lgkmcnt(0)
	s_barrier
	s_setprio 1
	s_waitcnt lgkmcnt(0)
	v_mfma_f32_16x16x32_bf16 v[60:63], v[128:131], v[188:191], v[60:63]
	v_mfma_f32_16x16x32_bf16 v[60:63], v[132:135], v[192:195], v[60:63]
	v_mfma_f32_16x16x32_bf16 v[56:59], v[136:139], v[188:191], v[56:59]
	v_mfma_f32_16x16x32_bf16 v[56:59], v[140:143], v[192:195], v[56:59]
	v_mfma_f32_16x16x32_bf16 v[44:47], v[136:139], v[196:199], v[44:47]
	v_mfma_f32_16x16x32_bf16 v[44:47], v[140:143], v[200:203], v[44:47]
	v_mfma_f32_16x16x32_bf16 v[48:51], v[128:131], v[196:199], v[48:51]
	v_mfma_f32_16x16x32_bf16 v[48:51], v[132:135], v[200:203], v[48:51]
	v_mfma_f32_16x16x32_bf16 v[36:39], v[128:131], v[204:207], v[36:39]
	v_mfma_f32_16x16x32_bf16 v[36:39], v[132:135], v[208:211], v[36:39]
	v_mfma_f32_16x16x32_bf16 v[28:31], v[136:139], v[204:207], v[28:31]
	v_mfma_f32_16x16x32_bf16 v[28:31], v[140:143], v[208:211], v[28:31]
	v_mfma_f32_16x16x32_bf16 v[12:15], v[136:139], v[212:215], v[12:15]
	v_mfma_f32_16x16x32_bf16 v[12:15], v[140:143], v[216:219], v[12:15]
	v_mfma_f32_16x16x32_bf16 v[20:23], v[128:131], v[212:215], v[20:23]
	v_mfma_f32_16x16x32_bf16 v[20:23], v[132:135], v[216:219], v[20:23]
	s_setprio 0
	s_setprio 1
	v_mfma_f32_16x16x32_bf16 v[52:55], v[162:165], v[188:191], v[52:55]
	v_mfma_f32_16x16x32_bf16 v[52:55], v[172:175], v[192:195], v[52:55]
	v_mfma_f32_16x16x32_bf16 v[40:43], v[176:179], v[188:191], v[40:43]
	v_mfma_f32_16x16x32_bf16 v[40:43], v[184:187], v[192:195], v[40:43]
	v_mfma_f32_16x16x32_bf16 v[24:27], v[176:179], v[196:199], v[24:27]
	v_mfma_f32_16x16x32_bf16 v[24:27], v[184:187], v[200:203], v[24:27]
	v_mfma_f32_16x16x32_bf16 v[32:35], v[162:165], v[196:199], v[32:35]
	v_mfma_f32_16x16x32_bf16 v[32:35], v[172:175], v[200:203], v[32:35]
	v_mfma_f32_16x16x32_bf16 v[16:19], v[162:165], v[204:207], v[16:19]
	v_mfma_f32_16x16x32_bf16 v[16:19], v[172:175], v[208:211], v[16:19]
	v_mfma_f32_16x16x32_bf16 v[8:11], v[176:179], v[204:207], v[8:11]
	v_mfma_f32_16x16x32_bf16 v[8:11], v[184:187], v[208:211], v[8:11]
	v_mfma_f32_16x16x32_bf16 v[0:3], v[176:179], v[212:215], v[0:3]
	v_mfma_f32_16x16x32_bf16 v[0:3], v[184:187], v[216:219], v[0:3]
	v_mfma_f32_16x16x32_bf16 v[4:7], v[162:165], v[212:215], v[4:7]
	v_mfma_f32_16x16x32_bf16 v[4:7], v[172:175], v[216:219], v[4:7]
	s_setprio 0
	s_barrier
; #define PG8_STAGE(bufoff, gbase, voff) do { _Pragma("unroll") for (int _i = 0; _i < 2; ++_i) \
;         __builtin_amdgcn_global_load_lds((const unsigned*)((const char*)(gbase) + (voff)[_i]), (PG8_LAS unsigned*)(lds + (bufoff) + ldsw + _i * 8192), 16, 0, 0); } while (0)
; #define PG8_LDA(dst, b, h) do { _Pragma("unroll") for (int m = 0; m < 4; ++m) _Pragma("unroll") for (int k = 0; k < 2; ++k) dst[m][k] = *(const PG8_LAS bf16x8*)(lds + PG8_SA(b, h) + aoff + m * 2048 + k * 1024); } while (0)
; #define PG8_LDB(dst, b, h) do { _Pragma("unroll") for (int n = 0; n < 2; ++n) _Pragma("unroll") for (int k = 0; k < 2; ++k) dst[n][k] = *(const PG8_LAS bf16x8*)(lds + PG8_SB(b, h) + boff + n * 2048 + k * 1024); } while (0)
; #define PG8_MMA(ai, bj, At, Bt) do { __builtin_amdgcn_s_setprio(1); _Pragma("unroll") for (int m = 0; m < 4; ++m) _Pragma("unroll") for (int n = 0; n < 2; ++n) _Pragma("unroll") for (int k = 0; k < 2; ++k) \
;         acc[ai][bj][m][n] = __builtin_amdgcn_mfma_f32_16x16x32_bf16(Bt[n][k], At[m][k], acc[ai][bj][m][n], 0, 0, 0); __builtin_amdgcn_s_setprio(0); } while (0)
; #define PG8_WAIT_V(n) asm volatile("s_waitcnt vmcnt(" #n ")" ::: "memory")
; #define PG8_WAIT_L(n) asm volatile("s_waitcnt lgkmcnt(" #n ")" ::: "memory")
; #define PG8_BAR __builtin_amdgcn_s_barrier()
; #define PG8_SCHED __builtin_amdgcn_sched_barrier(0)
; template <class Epi, class Sched, bool ALIGN_EPI = false, bool SP2 = false>
; __device__ __forceinline__ void gemm_phase(PG8_LAS unsigned char* lds, const Gemm g, const Sched& S, const Epi& E) {
;     ...
;             PG8_LDB(B0, 1, 0); PG8_LDB(B1, 1, 1); PG8_SCHED; PG8_LDA(At, 1, 0); PG8_STAGE(PG8_SA(0, 1), a2 + hstep, voffA);
;             PG8_WAIT_V(8); PG8_WAIT_L(0); PG8_BAR; PG8_MMA(0, 0, At, B0); PG8_MMA(0, 1, At, B1); PG8_BAR; PG8_SCHED;
;             PG8_LDA(At, 1, 1); PG8_STAGE(PG8_SB(1, 0), b3, voffB); PG8_STAGE(PG8_SB(1, 1), b3 + hstep, voffB); PG8_STAGE(PG8_SA(1, 0), a3, voffA);
;             PG8_WAIT_V(8); PG8_WAIT_L(0); PG8_BAR; PG8_MMA(1, 0, At, B0); PG8_MMA(1, 1, At, B1); PG8_BAR; PG8_SCHED;
	s_add_i32 s12, 0, 0x18000
	s_add_i32 s13, 0, 0x1c000
	v_add_u32_e32 v140, s12, v167
	v_add_u32_e32 v183, s13, v167
	ds_read_b128 v[128:131], v140
	ds_read_b128 v[132:135], v140 offset:1024
	ds_read_b128 v[136:139], v140 offset:2048
	ds_read_b128 v[140:143], v140 offset:3072
	ds_read_b128 v[162:165], v183
	ds_read_b128 v[172:175], v183 offset:1024
	ds_read_b128 v[176:179], v183 offset:2048
	ds_read_b128 v[184:187], v183 offset:3072
	s_add_u32 s40, s46, 0xb0000
	s_addc_u32 s41, s47, 0
	s_mov_b32 m0, s52
	ds_read_b128 v[188:191], v171 offset:32768
	ds_read_b128 v[192:195], v171 offset:33792
	ds_read_b128 v[196:199], v171 offset:34816
	ds_read_b128 v[200:203], v171 offset:35840
	ds_read_b128 v[204:207], v171 offset:36864
	ds_read_b128 v[208:211], v171 offset:37888
	ds_read_b128 v[212:215], v171 offset:38912
	ds_read_b128 v[216:219], v171 offset:39936
	global_load_lds_dwordx4 v144, s[40:41]
	s_mov_b32 m0, s53
	s_nop 0
	global_load_lds_dwordx4 v148, s[40:41]
	s_waitcnt vmcnt(8)
	s_waitcnt lgkmcnt(0)
	s_barrier
	s_setprio 1
	s_waitcnt lgkmcnt(0)
	v_mfma_f32_16x16x32_bf16 v[124:127], v[128:131], v[188:191], v[124:127]
	v_mfma_f32_16x16x32_bf16 v[124:127], v[132:135], v[192:195], v[124:127]
	v_mfma_f32_16x16x32_bf16 v[120:123], v[136:139], v[188:191], v[120:123]
	v_mfma_f32_16x16x32_bf16 v[120:123], v[140:143], v[192:195], v[120:123]
	v_mfma_f32_16x16x32_bf16 v[108:111], v[136:139], v[196:199], v[108:111]
	v_mfma_f32_16x16x32_bf16 v[108:111], v[140:143], v[200:203], v[108:111]
	v_mfma_f32_16x16x32_bf16 v[116:119], v[128:131], v[196:199], v[116:119]
	v_mfma_f32_16x16x32_bf16 v[116:119], v[132:135], v[200:203], v[116:119]
	v_mfma_f32_16x16x32_bf16 v[100:103], v[128:131], v[204:207], v[100:103]
	v_mfma_f32_16x16x32_bf16 v[100:103], v[132:135], v[208:211], v[100:103]
	v_mfma_f32_16x16x32_bf16 v[92:95], v[136:139], v[204:207], v[92:95]
	v_mfma_f32_16x16x32_bf16 v[92:95], v[140:143], v[208:211], v[92:95]
	v_mfma_f32_16x16x32_bf16 v[76:79], v[136:139], v[212:215], v[76:79]
	v_mfma_f32_16x16x32_bf16 v[76:79], v[140:143], v[216:219], v[76:79]
	v_mfma_f32_16x16x32_bf16 v[84:87], v[128:131], v[212:215], v[84:87]
	v_mfma_f32_16x16x32_bf16 v[84:87], v[132:135], v[216:219], v[84:87]
	s_setprio 0
	s_setprio 1
	v_mfma_f32_16x16x32_bf16 v[112:115], v[162:165], v[188:191], v[112:115]
	v_mfma_f32_16x16x32_bf16 v[112:115], v[172:175], v[192:195], v[112:115]
	v_mfma_f32_16x16x32_bf16 v[104:107], v[176:179], v[188:191], v[104:107]
	v_mfma_f32_16x16x32_bf16 v[104:107], v[184:187], v[192:195], v[104:107]
	v_mfma_f32_16x16x32_bf16 v[88:91], v[176:179], v[196:199], v[88:91]
	v_mfma_f32_16x16x32_bf16 v[88:91], v[184:187], v[200:203], v[88:91]
	v_mfma_f32_16x16x32_bf16 v[96:99], v[162:165], v[196:199], v[96:99]
	v_mfma_f32_16x16x32_bf16 v[96:99], v[172:175], v[200:203], v[96:99]
	v_mfma_f32_16x16x32_bf16 v[80:83], v[162:165], v[204:207], v[80:83]
	v_mfma_f32_16x16x32_bf16 v[80:83], v[172:175], v[208:211], v[80:83]
	v_mfma_f32_16x16x32_bf16 v[72:75], v[176:179], v[204:207], v[72:75]
	v_mfma_f32_16x16x32_bf16 v[72:75], v[184:187], v[208:211], v[72:75]
	v_mfma_f32_16x16x32_bf16 v[64:67], v[176:179], v[212:215], v[64:67]
	v_mfma_f32_16x16x32_bf16 v[64:67], v[184:187], v[216:219], v[64:67]
	v_mfma_f32_16x16x32_bf16 v[68:71], v[162:165], v[212:215], v[68:71]
	v_mfma_f32_16x16x32_bf16 v[68:71], v[172:175], v[216:219], v[68:71]
	s_setprio 0
	s_barrier
	s_add_i32 s12, s12, s49
	s_add_u32 s98, s44, s30
	s_addc_u32 s99, s45, s31
	s_add_u32 s100, s46, s30
	s_addc_u32 s101, s47, s31
	s_mov_b32 m0, s12
	ds_read_b128 v[188:191], v171 offset:49152
	ds_read_b128 v[192:195], v171 offset:50176
	ds_read_b128 v[196:199], v171 offset:51200
	ds_read_b128 v[200:203], v171 offset:52224
	ds_read_b128 v[204:207], v171 offset:53248
	ds_read_b128 v[208:211], v171 offset:54272
	ds_read_b128 v[212:215], v171 offset:55296
	ds_read_b128 v[216:219], v171 offset:56320
	global_load_lds_dwordx4 v146, s[98:99]
	s_add_i32 m0, s12, 0x2000
	s_add_u32 s40, s44, 0xb0080
	s_addc_u32 s41, s45, 0
	s_add_i32 s12, s13, s49
	global_load_lds_dwordx4 v150, s[98:99]
	s_mov_b32 m0, s12
	s_nop 0
	global_load_lds_dwordx4 v146, s[40:41]
	s_add_i32 m0, s12, 0x2000
	s_nop 0
	global_load_lds_dwordx4 v150, s[40:41]
	s_mov_b32 m0, s59
	s_nop 0
	global_load_lds_dwordx4 v144, s[100:101]
	s_mov_b32 m0, s60
	s_nop 0
	global_load_lds_dwordx4 v148, s[100:101]
	s_waitcnt vmcnt(8)
	s_waitcnt lgkmcnt(0)
	s_barrier
	s_setprio 1
	s_waitcnt lgkmcnt(0)
	v_mfma_f32_16x16x32_bf16 v[60:63], v[128:131], v[188:191], v[60:63]
	v_mfma_f32_16x16x32_bf16 v[60:63], v[132:135], v[192:195], v[60:63]
	v_mfma_f32_16x16x32_bf16 v[56:59], v[136:139], v[188:191], v[56:59]
	v_mfma_f32_16x16x32_bf16 v[56:59], v[140:143], v[192:195], v[56:59]
	v_mfma_f32_16x16x32_bf16 v[44:47], v[136:139], v[196:199], v[44:47]
	v_mfma_f32_16x16x32_bf16 v[44:47], v[140:143], v[200:203], v[44:47]
	v_mfma_f32_16x16x32_bf16 v[48:51], v[128:131], v[196:199], v[48:51]
	v_mfma_f32_16x16x32_bf16 v[48:51], v[132:135], v[200:203], v[48:51]
	v_mfma_f32_16x16x32_bf16 v[36:39], v[128:131], v[204:207], v[36:39]
	v_mfma_f32_16x16x32_bf16 v[36:39], v[132:135], v[208:211], v[36:39]
	v_mfma_f32_16x16x32_bf16 v[28:31], v[136:139], v[204:207], v[28:31]
	v_mfma_f32_16x16x32_bf16 v[28:31], v[140:143], v[208:211], v[28:31]
	v_mfma_f32_16x16x32_bf16 v[12:15], v[136:139], v[212:215], v[12:15]
	v_mfma_f32_16x16x32_bf16 v[12:15], v[140:143], v[216:219], v[12:15]
	v_mfma_f32_16x16x32_bf16 v[20:23], v[128:131], v[212:215], v[20:23]
	v_mfma_f32_16x16x32_bf16 v[20:23], v[132:135], v[216:219], v[20:23]
	s_setprio 0
	s_setprio 1
	v_mfma_f32_16x16x32_bf16 v[52:55], v[162:165], v[188:191], v[52:55]
	v_mfma_f32_16x16x32_bf16 v[52:55], v[172:175], v[192:195], v[52:55]
	v_mfma_f32_16x16x32_bf16 v[40:43], v[176:179], v[188:191], v[40:43]
	v_mfma_f32_16x16x32_bf16 v[40:43], v[184:187], v[192:195], v[40:43]
	v_mfma_f32_16x16x32_bf16 v[24:27], v[176:179], v[196:199], v[24:27]
	v_mfma_f32_16x16x32_bf16 v[24:27], v[184:187], v[200:203], v[24:27]
	v_mfma_f32_16x16x32_bf16 v[32:35], v[162:165], v[196:199], v[32:35]
	v_mfma_f32_16x16x32_bf16 v[32:35], v[172:175], v[200:203], v[32:35]
	v_mfma_f32_16x16x32_bf16 v[16:19], v[162:165], v[204:207], v[16:19]
	v_mfma_f32_16x16x32_bf16 v[16:19], v[172:175], v[208:211], v[16:19]
	v_mfma_f32_16x16x32_bf16 v[8:11], v[176:179], v[204:207], v[8:11]
	v_mfma_f32_16x16x32_bf16 v[8:11], v[184:187], v[208:211], v[8:11]
	v_mfma_f32_16x16x32_bf16 v[0:3], v[176:179], v[212:215], v[0:3]
	v_mfma_f32_16x16x32_bf16 v[0:3], v[184:187], v[216:219], v[0:3]
	v_mfma_f32_16x16x32_bf16 v[4:7], v[162:165], v[212:215], v[4:7]
	v_mfma_f32_16x16x32_bf16 v[4:7], v[172:175], v[216:219], v[4:7]
	s_setprio 0
	s_barrier
	s_add_i32 s74, s74, 2
	s_add_u32 s71, s71, 0x100
	s_addc_u32 s73, s73, 0
	s_cmp_gt_u32 s74, 41
	s_mov_b64 s[40:41], s[42:43]
	s_cbranch_scc0 .LBB0_872
	s_and_b64 vcc, exec, s[34:35]
	s_cbranch_vccz .LBB0_875
	s_barrier

; #define PG8_STAGE(bufoff, gbase, voff) do { _Pragma("unroll") for (int _i = 0; _i < 2; ++_i) \
;         __builtin_amdgcn_global_load_lds((const unsigned*)((const char*)(gbase) + (voff)[_i]), (PG8_LAS unsigned*)(lds + (bufoff) + ldsw + _i * 8192), 16, 0, 0); } while (0)
; #define PG8_LDA(dst, b, h) do { _Pragma("unroll") for (int m = 0; m < 4; ++m) _Pragma("unroll") for (int k = 0; k < 2; ++k) dst[m][k] = *(const PG8_LAS bf16x8*)(lds + PG8_SA(b, h) + aoff + m * 2048 + k * 1024); } while (0)
; #define PG8_LDB(dst, b, h) do { _Pragma("unroll") for (int n = 0; n < 2; ++n) _Pragma("unroll") for (int k = 0; k < 2; ++k) dst[n][k] = *(const PG8_LAS bf16x8*)(lds + PG8_SB(b, h) + boff + n * 2048 + k * 1024); } while (0)
; #define PG8_MMA(ai, bj, At, Bt) do { __builtin_amdgcn_s_setprio(1); _Pragma("unroll") for (int m = 0; m < 4; ++m) _Pragma("unroll") for (int n = 0; n < 2; ++n) _Pragma("unroll") for (int k = 0; k < 2; ++k) \
;         acc[ai][bj][m][n] = __builtin_amdgcn_mfma_f32_16x16x32_bf16(Bt[n][k], At[m][k], acc[ai][bj][m][n], 0, 0, 0); __builtin_amdgcn_s_setprio(0); } while (0)
; #define PG8_WAIT_V(n) asm volatile("s_waitcnt vmcnt(" #n ")" ::: "memory")
; #define PG8_WAIT_L(n) asm volatile("s_waitcnt lgkmcnt(" #n ")" ::: "memory")
; #define PG8_BAR __builtin_amdgcn_s_barrier()
; #define PG8_SCHED __builtin_amdgcn_sched_barrier(0)
; template <class Epi, class Sched, bool ALIGN_EPI = false, bool SP2 = false>
; __device__ __forceinline__ void gemm_phase(PG8_LAS unsigned char* lds, const Gemm g, const Sched& S, const Epi& E) {
;     ...
;             PG8_LDB(B0, 0, 0); PG8_LDB(B1, 0, 1); PG8_SCHED; PG8_LDA(At, 0, 0); PG8_STAGE(PG8_SA(1, 1), a1 + hstep, voffA);
;             PG8_WAIT_V(8); PG8_WAIT_L(0); PG8_BAR; PG8_MMA(0, 0, At, B0); PG8_MMA(0, 1, At, B1); PG8_BAR; PG8_SCHED;
;             PG8_LDA(At, 0, 1); PG8_STAGE(PG8_SB(0, 0), b2, voffB); PG8_STAGE(PG8_SB(0, 1), b2 + hstep, voffB); PG8_STAGE(PG8_SA(0, 0), a2, voffA);
;             PG8_WAIT_V(8); PG8_WAIT_L(0); PG8_BAR; PG8_MMA(1, 0, At, B0); PG8_MMA(1, 1, At, B1); PG8_BAR; PG8_SCHED;
;             PG8_LDB(B0, 1, 0); PG8_LDB(B1, 1, 1); PG8_SCHED; PG8_LDA(At, 1, 0); PG8_STAGE(PG8_SA(0, 1), a2 + hstep, voffA);
.LBB0_960:
	v_add_u32_e32 v130, s89, v169
	ds_read_b128 v[150:153], v130
	ds_read_b128 v[158:161], v130 offset:1024
	ds_read_b128 v[162:165], v130 offset:2048
	ds_read_b128 v[196:199], v130 offset:3072
	v_add_u32_e32 v130, s90, v169
	ds_read_b128 v[200:203], v130
	ds_read_b128 v[204:207], v130 offset:1024
	ds_read_b128 v[208:211], v130 offset:2048
	ds_read_b128 v[212:215], v130 offset:3072
	s_add_u32 s12, s10, 0xfffc0080
	s_addc_u32 s13, s11, -1
	s_and_b64 s[66:67], s[66:67], exec
	s_cselect_b32 s69, s57, s13
	s_cselect_b32 s68, s63, s12
	s_cselect_b32 s67, s55, s71
	s_cselect_b32 s66, s70, s65
	s_add_i32 m0, s75, 0xc000
	ds_read_b128 v[216:219], v191
	ds_read_b128 v[220:223], v191 offset:1024
	ds_read_b128 v[224:227], v191 offset:2048
	ds_read_b128 v[228:231], v191 offset:3072
	ds_read_b128 v[232:235], v191 offset:4096
	ds_read_b128 v[236:239], v191 offset:5120
	ds_read_b128 v[240:243], v191 offset:6144
	ds_read_b128 v[244:247], v191 offset:7168
	global_load_lds_dwordx4 v142, s[10:11]
	s_add_i32 m0, s75, 0xe000
	s_nop 0
	global_load_lds_dwordx4 v140, s[10:11]
	s_waitcnt vmcnt(8)
	s_waitcnt lgkmcnt(0)
	s_barrier
	s_setprio 1
	s_waitcnt lgkmcnt(0)
	v_mfma_f32_16x16x32_bf16 v[124:127], v[150:153], v[216:219], v[124:127]
	v_mfma_f32_16x16x32_bf16 v[124:127], v[158:161], v[220:223], v[124:127]
	v_mfma_f32_16x16x32_bf16 v[120:123], v[162:165], v[216:219], v[120:123]
	v_mfma_f32_16x16x32_bf16 v[120:123], v[196:199], v[220:223], v[120:123]
	v_mfma_f32_16x16x32_bf16 v[104:107], v[162:165], v[224:227], v[104:107]
	v_mfma_f32_16x16x32_bf16 v[104:107], v[196:199], v[228:231], v[104:107]
	v_mfma_f32_16x16x32_bf16 v[112:115], v[150:153], v[224:227], v[112:115]
	v_mfma_f32_16x16x32_bf16 v[112:115], v[158:161], v[228:231], v[112:115]
	v_mfma_f32_16x16x32_bf16 v[100:103], v[150:153], v[232:235], v[100:103]
	v_mfma_f32_16x16x32_bf16 v[100:103], v[158:161], v[236:239], v[100:103]
	v_mfma_f32_16x16x32_bf16 v[96:99], v[162:165], v[232:235], v[96:99]
	v_mfma_f32_16x16x32_bf16 v[96:99], v[196:199], v[236:239], v[96:99]
	v_mfma_f32_16x16x32_bf16 v[72:75], v[162:165], v[240:243], v[72:75]
	v_mfma_f32_16x16x32_bf16 v[72:75], v[196:199], v[244:247], v[72:75]
	v_mfma_f32_16x16x32_bf16 v[80:83], v[150:153], v[240:243], v[80:83]
	v_mfma_f32_16x16x32_bf16 v[80:83], v[158:161], v[244:247], v[80:83]
	s_setprio 0
	s_setprio 1
	v_mfma_f32_16x16x32_bf16 v[116:119], v[200:203], v[216:219], v[116:119]
	v_mfma_f32_16x16x32_bf16 v[116:119], v[204:207], v[220:223], v[116:119]
	v_mfma_f32_16x16x32_bf16 v[108:111], v[208:211], v[216:219], v[108:111]
	v_mfma_f32_16x16x32_bf16 v[108:111], v[212:215], v[220:223], v[108:111]
	v_mfma_f32_16x16x32_bf16 v[88:91], v[208:211], v[224:227], v[88:91]
	v_mfma_f32_16x16x32_bf16 v[88:91], v[212:215], v[228:231], v[88:91]
	v_mfma_f32_16x16x32_bf16 v[92:95], v[200:203], v[224:227], v[92:95]
	v_mfma_f32_16x16x32_bf16 v[92:95], v[204:207], v[228:231], v[92:95]
	v_mfma_f32_16x16x32_bf16 v[84:87], v[200:203], v[232:235], v[84:87]
	v_mfma_f32_16x16x32_bf16 v[84:87], v[204:207], v[236:239], v[84:87]
	v_mfma_f32_16x16x32_bf16 v[76:79], v[208:211], v[232:235], v[76:79]
	v_mfma_f32_16x16x32_bf16 v[76:79], v[212:215], v[236:239], v[76:79]
	v_mfma_f32_16x16x32_bf16 v[64:67], v[208:211], v[240:243], v[64:67]
	v_mfma_f32_16x16x32_bf16 v[64:67], v[212:215], v[244:247], v[64:67]
	v_mfma_f32_16x16x32_bf16 v[68:71], v[200:203], v[240:243], v[68:71]
	v_mfma_f32_16x16x32_bf16 v[68:71], v[204:207], v[244:247], v[68:71]
	s_setprio 0
	s_barrier
	s_add_i32 s12, s89, s74
	s_mov_b32 m0, s12
	ds_read_b128 v[216:219], v191 offset:16384
	ds_read_b128 v[220:223], v191 offset:17408
	ds_read_b128 v[224:227], v191 offset:18432
	ds_read_b128 v[228:231], v191 offset:19456
	ds_read_b128 v[232:235], v191 offset:20480
	ds_read_b128 v[236:239], v191 offset:21504
	ds_read_b128 v[240:243], v191 offset:22528
	ds_read_b128 v[244:247], v191 offset:23552
	global_load_lds_dwordx4 v134, s[66:67]
	s_add_i32 m0, s12, 0x2000
	s_add_u32 vcc_lo, s66, 0x40000
	v_lshl_add_u64 v[154:155], s[66:67], 0, v[138:139]
	s_addc_u32 vcc_hi, s67, 0
	s_add_i32 s12, s90, s74
	global_load_lds_dwordx4 v138, s[66:67]
	v_lshl_add_u64 v[166:167], vcc, 0, v[134:135]
	s_mov_b32 m0, s12
	v_lshl_add_u64 v[248:249], s[68:69], 0, v[136:137]
	global_load_lds_dwordx4 v[166:167], off
	v_lshl_add_u64 v[166:167], vcc, 0, v[138:139]
	s_add_i32 m0, s12, 0x2000
	s_nop 0
	global_load_lds_dwordx4 v[166:167], off
	v_lshl_add_u64 v[166:167], s[68:69], 0, v[132:133]
	s_mov_b32 m0, s75
	s_nop 0
	global_load_lds_dwordx4 v132, s[68:69]
	s_mov_b32 m0, s76
	s_nop 0
	global_load_lds_dwordx4 v136, s[68:69]
	s_waitcnt vmcnt(8)
	s_waitcnt lgkmcnt(0)
	s_barrier
; #define PG8_STAGE(bufoff, gbase, voff) do { _Pragma("unroll") for (int _i = 0; _i < 2; ++_i) \
;         __builtin_amdgcn_global_load_lds((const unsigned*)((const char*)(gbase) + (voff)[_i]), (PG8_LAS unsigned*)(lds + (bufoff) + ldsw + _i * 8192), 16, 0, 0); } while (0)
; #define PG8_LDA(dst, b, h) do { _Pragma("unroll") for (int m = 0; m < 4; ++m) _Pragma("unroll") for (int k = 0; k < 2; ++k) dst[m][k] = *(const PG8_LAS bf16x8*)(lds + PG8_SA(b, h) + aoff + m * 2048 + k * 1024); } while (0)
; #define PG8_LDB(dst, b, h) do { _Pragma("unroll") for (int n = 0; n < 2; ++n) _Pragma("unroll") for (int k = 0; k < 2; ++k) dst[n][k] = *(const PG8_LAS bf16x8*)(lds + PG8_SB(b, h) + boff + n * 2048 + k * 1024); } while (0)
; #define PG8_MMA(ai, bj, At, Bt) do { __builtin_amdgcn_s_setprio(1); _Pragma("unroll") for (int m = 0; m < 4; ++m) _Pragma("unroll") for (int n = 0; n < 2; ++n) _Pragma("unroll") for (int k = 0; k < 2; ++k) \
;         acc[ai][bj][m][n] = __builtin_amdgcn_mfma_f32_16x16x32_bf16(Bt[n][k], At[m][k], acc[ai][bj][m][n], 0, 0, 0); __builtin_amdgcn_s_setprio(0); } while (0)
; #define PG8_WAIT_V(n) asm volatile("s_waitcnt vmcnt(" #n ")" ::: "memory")
; #define PG8_WAIT_L(n) asm volatile("s_waitcnt lgkmcnt(" #n ")" ::: "memory")
; #define PG8_BAR __builtin_amdgcn_s_barrier()
; #define PG8_SCHED __builtin_amdgcn_sched_barrier(0)
; template <class Epi, class Sched, bool ALIGN_EPI = false, bool SP2 = false>
; __device__ __forceinline__ void gemm_phase(PG8_LAS unsigned char* lds, const Gemm g, const Sched& S, const Epi& E) {
;     ...
;             PG8_WAIT_V(8); PG8_WAIT_L(0); PG8_BAR; PG8_MMA(1, 0, At, B0); PG8_MMA(1, 1, At, B1); PG8_BAR; PG8_SCHED;
;             PG8_LDB(B0, 1, 0); PG8_LDB(B1, 1, 1); PG8_SCHED; PG8_LDA(At, 1, 0); PG8_STAGE(PG8_SA(0, 1), a2 + hstep, voffA);
;             PG8_WAIT_V(8); PG8_WAIT_L(0); PG8_BAR; PG8_MMA(0, 0, At, B0); PG8_MMA(0, 1, At, B1); PG8_BAR; PG8_SCHED;
;             PG8_LDA(At, 1, 1); PG8_STAGE(PG8_SB(1, 0), b3, voffB); PG8_STAGE(PG8_SB(1, 1), b3 + hstep, voffB); PG8_STAGE(PG8_SA(1, 0), a3, voffA);
	s_setprio 1
	s_waitcnt lgkmcnt(0)
	v_mfma_f32_16x16x32_bf16 v[60:63], v[150:153], v[216:219], v[60:63]
	v_mfma_f32_16x16x32_bf16 v[60:63], v[158:161], v[220:223], v[60:63]
	v_mfma_f32_16x16x32_bf16 v[56:59], v[162:165], v[216:219], v[56:59]
	v_mfma_f32_16x16x32_bf16 v[56:59], v[196:199], v[220:223], v[56:59]
	v_mfma_f32_16x16x32_bf16 v[40:43], v[162:165], v[224:227], v[40:43]
	v_mfma_f32_16x16x32_bf16 v[40:43], v[196:199], v[228:231], v[40:43]
	v_mfma_f32_16x16x32_bf16 v[48:51], v[150:153], v[224:227], v[48:51]
	v_mfma_f32_16x16x32_bf16 v[48:51], v[158:161], v[228:231], v[48:51]
	v_mfma_f32_16x16x32_bf16 v[36:39], v[150:153], v[232:235], v[36:39]
	v_mfma_f32_16x16x32_bf16 v[36:39], v[158:161], v[236:239], v[36:39]
	v_mfma_f32_16x16x32_bf16 v[32:35], v[162:165], v[232:235], v[32:35]
	v_mfma_f32_16x16x32_bf16 v[32:35], v[196:199], v[236:239], v[32:35]
	v_mfma_f32_16x16x32_bf16 v[16:19], v[162:165], v[240:243], v[16:19]
	v_mfma_f32_16x16x32_bf16 v[16:19], v[196:199], v[244:247], v[16:19]
	v_mfma_f32_16x16x32_bf16 v[20:23], v[150:153], v[240:243], v[20:23]
	v_mfma_f32_16x16x32_bf16 v[20:23], v[158:161], v[244:247], v[20:23]
	s_setprio 0
	s_setprio 1
	v_mfma_f32_16x16x32_bf16 v[52:55], v[200:203], v[216:219], v[52:55]
	v_mfma_f32_16x16x32_bf16 v[52:55], v[204:207], v[220:223], v[52:55]
	v_mfma_f32_16x16x32_bf16 v[44:47], v[208:211], v[216:219], v[44:47]
	v_mfma_f32_16x16x32_bf16 v[44:47], v[212:215], v[220:223], v[44:47]
	v_mfma_f32_16x16x32_bf16 v[24:27], v[208:211], v[224:227], v[24:27]
	v_mfma_f32_16x16x32_bf16 v[24:27], v[212:215], v[228:231], v[24:27]
	v_mfma_f32_16x16x32_bf16 v[28:31], v[200:203], v[224:227], v[28:31]
	v_mfma_f32_16x16x32_bf16 v[28:31], v[204:207], v[228:231], v[28:31]
	v_mfma_f32_16x16x32_bf16 v[12:15], v[200:203], v[232:235], v[12:15]
	v_mfma_f32_16x16x32_bf16 v[12:15], v[204:207], v[236:239], v[12:15]
	v_mfma_f32_16x16x32_bf16 v[8:11], v[208:211], v[232:235], v[8:11]
	v_mfma_f32_16x16x32_bf16 v[8:11], v[212:215], v[236:239], v[8:11]
	v_mfma_f32_16x16x32_bf16 v[0:3], v[208:211], v[240:243], v[0:3]
	v_mfma_f32_16x16x32_bf16 v[0:3], v[212:215], v[244:247], v[0:3]
	v_mfma_f32_16x16x32_bf16 v[4:7], v[200:203], v[240:243], v[4:7]
	v_mfma_f32_16x16x32_bf16 v[4:7], v[204:207], v[244:247], v[4:7]
	s_setprio 0
	s_barrier
	s_add_i32 s12, 0, 0x18000
	v_add_u32_e32 v195, s12, v169
	s_add_i32 s13, 0, 0x1c000
	ds_read_b128 v[150:153], v195
	ds_read_b128 v[158:161], v195 offset:1024
	ds_read_b128 v[162:165], v195 offset:2048
	ds_read_b128 v[196:199], v195 offset:3072
	v_add_u32_e32 v195, s13, v169
	ds_read_b128 v[200:203], v195
	ds_read_b128 v[204:207], v195 offset:1024
	ds_read_b128 v[208:211], v195 offset:2048
	ds_read_b128 v[212:215], v195 offset:3072
	s_add_u32 s68, s68, 0x40000
	s_addc_u32 s69, s69, 0
	s_mov_b32 m0, s77
	ds_read_b128 v[216:219], v191 offset:32768
	ds_read_b128 v[220:223], v191 offset:33792
	ds_read_b128 v[224:227], v191 offset:34816
	ds_read_b128 v[228:231], v191 offset:35840
	ds_read_b128 v[232:235], v191 offset:36864
	ds_read_b128 v[236:239], v191 offset:37888
	ds_read_b128 v[240:243], v191 offset:38912
	ds_read_b128 v[244:247], v191 offset:39936
	global_load_lds_dwordx4 v132, s[68:69]
	s_mov_b32 m0, s78
	s_nop 0
	global_load_lds_dwordx4 v136, s[68:69]
	s_waitcnt vmcnt(8)
	s_waitcnt lgkmcnt(0)
	s_barrier
	s_setprio 1
	s_waitcnt lgkmcnt(0)
	v_mfma_f32_16x16x32_bf16 v[124:127], v[150:153], v[216:219], v[124:127]
	v_mfma_f32_16x16x32_bf16 v[124:127], v[158:161], v[220:223], v[124:127]
	v_mfma_f32_16x16x32_bf16 v[120:123], v[162:165], v[216:219], v[120:123]
	v_mfma_f32_16x16x32_bf16 v[120:123], v[196:199], v[220:223], v[120:123]
	v_mfma_f32_16x16x32_bf16 v[104:107], v[162:165], v[224:227], v[104:107]
	v_mfma_f32_16x16x32_bf16 v[104:107], v[196:199], v[228:231], v[104:107]
	v_mfma_f32_16x16x32_bf16 v[112:115], v[150:153], v[224:227], v[112:115]
	v_mfma_f32_16x16x32_bf16 v[112:115], v[158:161], v[228:231], v[112:115]
	v_mfma_f32_16x16x32_bf16 v[100:103], v[150:153], v[232:235], v[100:103]
	v_mfma_f32_16x16x32_bf16 v[100:103], v[158:161], v[236:239], v[100:103]
	v_mfma_f32_16x16x32_bf16 v[96:99], v[162:165], v[232:235], v[96:99]
	v_mfma_f32_16x16x32_bf16 v[96:99], v[196:199], v[236:239], v[96:99]
	v_mfma_f32_16x16x32_bf16 v[72:75], v[162:165], v[240:243], v[72:75]
	v_mfma_f32_16x16x32_bf16 v[72:75], v[196:199], v[244:247], v[72:75]
	v_mfma_f32_16x16x32_bf16 v[80:83], v[150:153], v[240:243], v[80:83]
	v_mfma_f32_16x16x32_bf16 v[80:83], v[158:161], v[244:247], v[80:83]
	s_setprio 0
	s_setprio 1
	v_mfma_f32_16x16x32_bf16 v[116:119], v[200:203], v[216:219], v[116:119]
	v_mfma_f32_16x16x32_bf16 v[116:119], v[204:207], v[220:223], v[116:119]
	v_mfma_f32_16x16x32_bf16 v[108:111], v[208:211], v[216:219], v[108:111]
	v_mfma_f32_16x16x32_bf16 v[108:111], v[212:215], v[220:223], v[108:111]
	v_mfma_f32_16x16x32_bf16 v[88:91], v[208:211], v[224:227], v[88:91]
	v_mfma_f32_16x16x32_bf16 v[88:91], v[212:215], v[228:231], v[88:91]
	v_mfma_f32_16x16x32_bf16 v[92:95], v[200:203], v[224:227], v[92:95]
	v_mfma_f32_16x16x32_bf16 v[92:95], v[204:207], v[228:231], v[92:95]
	v_mfma_f32_16x16x32_bf16 v[84:87], v[200:203], v[232:235], v[84:87]
	v_mfma_f32_16x16x32_bf16 v[84:87], v[204:207], v[236:239], v[84:87]
	v_mfma_f32_16x16x32_bf16 v[76:79], v[208:211], v[232:235], v[76:79]
	v_mfma_f32_16x16x32_bf16 v[76:79], v[212:215], v[236:239], v[76:79]
	v_mfma_f32_16x16x32_bf16 v[64:67], v[208:211], v[240:243], v[64:67]
	v_mfma_f32_16x16x32_bf16 v[64:67], v[212:215], v[244:247], v[64:67]
	v_mfma_f32_16x16x32_bf16 v[68:71], v[200:203], v[240:243], v[68:71]
	v_mfma_f32_16x16x32_bf16 v[68:71], v[204:207], v[244:247], v[68:71]
	s_setprio 0
	s_barrier
; #define PG8_STAGE(bufoff, gbase, voff) do { _Pragma("unroll") for (int _i = 0; _i < 2; ++_i) \
;         __builtin_amdgcn_global_load_lds((const unsigned*)((const char*)(gbase) + (voff)[_i]), (PG8_LAS unsigned*)(lds + (bufoff) + ldsw + _i * 8192), 16, 0, 0); } while (0)
; #define PG8_LDA(dst, b, h) do { _Pragma("unroll") for (int m = 0; m < 4; ++m) _Pragma("unroll") for (int k = 0; k < 2; ++k) dst[m][k] = *(const PG8_LAS bf16x8*)(lds + PG8_SA(b, h) + aoff + m * 2048 + k * 1024); } while (0)
; #define PG8_MMA(ai, bj, At, Bt) do { __builtin_amdgcn_s_setprio(1); _Pragma("unroll") for (int m = 0; m < 4; ++m) _Pragma("unroll") for (int n = 0; n < 2; ++n) _Pragma("unroll") for (int k = 0; k < 2; ++k) \
;         acc[ai][bj][m][n] = __builtin_amdgcn_mfma_f32_16x16x32_bf16(Bt[n][k], At[m][k], acc[ai][bj][m][n], 0, 0, 0); __builtin_amdgcn_s_setprio(0); } while (0)
; #define PG8_WAIT_V(n) asm volatile("s_waitcnt vmcnt(" #n ")" ::: "memory")
; #define PG8_WAIT_L(n) asm volatile("s_waitcnt lgkmcnt(" #n ")" ::: "memory")
; #define PG8_BAR __builtin_amdgcn_s_barrier()
; #define PG8_SCHED __builtin_amdgcn_sched_barrier(0)
; template <class Epi, class Sched, bool ALIGN_EPI = false, bool SP2 = false>
; __device__ __forceinline__ void gemm_phase(PG8_LAS unsigned char* lds, const Gemm g, const Sched& S, const Epi& E) {
;     ...
;             PG8_LDA(At, 1, 1); PG8_STAGE(PG8_SB(1, 0), b3, voffB); PG8_STAGE(PG8_SB(1, 1), b3 + hstep, voffB); PG8_STAGE(PG8_SA(1, 0), a3, voffA);
;             PG8_WAIT_V(8); PG8_WAIT_L(0); PG8_BAR; PG8_MMA(1, 0, At, B0); PG8_MMA(1, 1, At, B1); PG8_BAR; PG8_SCHED;
	s_add_i32 s12, s12, s74
	s_add_u32 s98, s66, s42
	s_addc_u32 s99, s67, s43
	s_mov_b32 m0, s12
	ds_read_b128 v[216:219], v191 offset:49152
	ds_read_b128 v[220:223], v191 offset:50176
	ds_read_b128 v[224:227], v191 offset:51200
	ds_read_b128 v[228:231], v191 offset:52224
	ds_read_b128 v[232:235], v191 offset:53248
	ds_read_b128 v[236:239], v191 offset:54272
	ds_read_b128 v[240:243], v191 offset:55296
	ds_read_b128 v[244:247], v191 offset:56320
	global_load_lds_dwordx4 v134, s[98:99]
	s_add_i32 m0, s12, 0x2000
	s_add_u32 s66, s66, 0x40080
	v_lshl_add_u64 v[130:131], v[154:155], 0, s[42:43]
	s_addc_u32 s67, s67, 0
	s_add_i32 s12, s13, s74
	global_load_lds_dwordx4 v[130:131], off
	s_mov_b32 m0, s12
	s_nop 0
	global_load_lds_dwordx4 v134, s[66:67]
	s_add_i32 m0, s12, 0x2000
	s_nop 0
	global_load_lds_dwordx4 v138, s[66:67]
	v_lshl_add_u64 v[130:131], v[166:167], 0, s[42:43]
	s_mov_b32 m0, s79
	s_nop 0
	global_load_lds_dwordx4 v[130:131], off
	v_lshl_add_u64 v[130:131], v[248:249], 0, s[42:43]
	s_mov_b32 m0, s80
	s_nop 0
	global_load_lds_dwordx4 v[130:131], off
	s_waitcnt vmcnt(8)
	s_waitcnt lgkmcnt(0)
	s_barrier
	s_setprio 1
	s_waitcnt lgkmcnt(0)
	v_mfma_f32_16x16x32_bf16 v[60:63], v[150:153], v[216:219], v[60:63]
	v_mfma_f32_16x16x32_bf16 v[60:63], v[158:161], v[220:223], v[60:63]
	v_mfma_f32_16x16x32_bf16 v[56:59], v[162:165], v[216:219], v[56:59]
	v_mfma_f32_16x16x32_bf16 v[56:59], v[196:199], v[220:223], v[56:59]
	v_mfma_f32_16x16x32_bf16 v[40:43], v[162:165], v[224:227], v[40:43]
	v_mfma_f32_16x16x32_bf16 v[40:43], v[196:199], v[228:231], v[40:43]
	v_mfma_f32_16x16x32_bf16 v[48:51], v[150:153], v[224:227], v[48:51]
	v_mfma_f32_16x16x32_bf16 v[48:51], v[158:161], v[228:231], v[48:51]
	v_mfma_f32_16x16x32_bf16 v[36:39], v[150:153], v[232:235], v[36:39]
	v_mfma_f32_16x16x32_bf16 v[36:39], v[158:161], v[236:239], v[36:39]
	v_mfma_f32_16x16x32_bf16 v[32:35], v[162:165], v[232:235], v[32:35]
	v_mfma_f32_16x16x32_bf16 v[32:35], v[196:199], v[236:239], v[32:35]
	v_mfma_f32_16x16x32_bf16 v[16:19], v[162:165], v[240:243], v[16:19]
	v_mfma_f32_16x16x32_bf16 v[16:19], v[196:199], v[244:247], v[16:19]
	v_mfma_f32_16x16x32_bf16 v[20:23], v[150:153], v[240:243], v[20:23]
	v_mfma_f32_16x16x32_bf16 v[20:23], v[158:161], v[244:247], v[20:23]
	s_setprio 0
	s_setprio 1
	v_mfma_f32_16x16x32_bf16 v[52:55], v[200:203], v[216:219], v[52:55]
	v_mfma_f32_16x16x32_bf16 v[52:55], v[204:207], v[220:223], v[52:55]
	v_mfma_f32_16x16x32_bf16 v[44:47], v[208:211], v[216:219], v[44:47]
	v_mfma_f32_16x16x32_bf16 v[44:47], v[212:215], v[220:223], v[44:47]
	v_mfma_f32_16x16x32_bf16 v[24:27], v[208:211], v[224:227], v[24:27]
	v_mfma_f32_16x16x32_bf16 v[24:27], v[212:215], v[228:231], v[24:27]
	v_mfma_f32_16x16x32_bf16 v[28:31], v[200:203], v[224:227], v[28:31]
	v_mfma_f32_16x16x32_bf16 v[28:31], v[204:207], v[228:231], v[28:31]
	v_mfma_f32_16x16x32_bf16 v[12:15], v[200:203], v[232:235], v[12:15]
	v_mfma_f32_16x16x32_bf16 v[12:15], v[204:207], v[236:239], v[12:15]
	v_mfma_f32_16x16x32_bf16 v[8:11], v[208:211], v[232:235], v[8:11]
	v_mfma_f32_16x16x32_bf16 v[8:11], v[212:215], v[236:239], v[8:11]
	v_mfma_f32_16x16x32_bf16 v[0:3], v[208:211], v[240:243], v[0:3]
	v_mfma_f32_16x16x32_bf16 v[0:3], v[212:215], v[244:247], v[0:3]
	v_mfma_f32_16x16x32_bf16 v[4:7], v[200:203], v[240:243], v[4:7]
	v_mfma_f32_16x16x32_bf16 v[4:7], v[204:207], v[244:247], v[4:7]
	s_setprio 0
	s_barrier
	s_add_i32 s96, s96, 2
	s_add_u32 s65, s65, 0x100
	s_addc_u32 s71, s71, 0
	s_add_u32 s10, s10, 0x100
	s_addc_u32 s11, s11, 0
	s_cmp_gt_u32 s96, 13
	s_cbranch_scc1 .LBB0_963

; #define PG8_STAGE(bufoff, gbase, voff) do { _Pragma("unroll") for (int _i = 0; _i < 2; ++_i) \
;         __builtin_amdgcn_global_load_lds((const unsigned*)((const char*)(gbase) + (voff)[_i]), (PG8_LAS unsigned*)(lds + (bufoff) + ldsw + _i * 8192), 16, 0, 0); } while (0)
; #define PG8_LDA(dst, b, h) do { _Pragma("unroll") for (int m = 0; m < 4; ++m) _Pragma("unroll") for (int k = 0; k < 2; ++k) dst[m][k] = *(const PG8_LAS bf16x8*)(lds + PG8_SA(b, h) + aoff + m * 2048 + k * 1024); } while (0)
; #define PG8_LDB(dst, b, h) do { _Pragma("unroll") for (int n = 0; n < 2; ++n) _Pragma("unroll") for (int k = 0; k < 2; ++k) dst[n][k] = *(const PG8_LAS bf16x8*)(lds + PG8_SB(b, h) + boff + n * 2048 + k * 1024); } while (0)
; #define PG8_MMA(ai, bj, At, Bt) do { __builtin_amdgcn_s_setprio(1); _Pragma("unroll") for (int m = 0; m < 4; ++m) _Pragma("unroll") for (int n = 0; n < 2; ++n) _Pragma("unroll") for (int k = 0; k < 2; ++k) \
;         acc[ai][bj][m][n] = __builtin_amdgcn_mfma_f32_16x16x32_bf16(Bt[n][k], At[m][k], acc[ai][bj][m][n], 0, 0, 0); __builtin_amdgcn_s_setprio(0); } while (0)
; #define PG8_WAIT_V(n) asm volatile("s_waitcnt vmcnt(" #n ")" ::: "memory")
; #define PG8_WAIT_L(n) asm volatile("s_waitcnt lgkmcnt(" #n ")" ::: "memory")
; #define PG8_BAR __builtin_amdgcn_s_barrier()
; #define PG8_SCHED __builtin_amdgcn_sched_barrier(0)
; template <class Epi, class Sched, bool ALIGN_EPI = false, bool SP2 = false>
; __device__ __forceinline__ void gemm_phase(PG8_LAS unsigned char* lds, const Gemm g, const Sched& S, const Epi& E) {
;     ...
;             PG8_LDB(B0, 0, 0); PG8_LDB(B1, 0, 1); PG8_SCHED; PG8_LDA(At, 0, 0); PG8_STAGE(PG8_SA(1, 1), a1 + hstep, voffA);
;             PG8_WAIT_V(8); PG8_WAIT_L(0); PG8_BAR; PG8_MMA(0, 0, At, B0); PG8_MMA(0, 1, At, B1); PG8_BAR; PG8_SCHED;
;             PG8_LDA(At, 0, 1); PG8_STAGE(PG8_SB(0, 0), b2, voffB); PG8_STAGE(PG8_SB(0, 1), b2 + hstep, voffB); PG8_STAGE(PG8_SA(0, 0), a2, voffA);
;             PG8_WAIT_V(8); PG8_WAIT_L(0); PG8_BAR; PG8_MMA(1, 0, At, B0); PG8_MMA(1, 1, At, B1); PG8_BAR; PG8_SCHED;
.LBB0_1272:
	ds_read_b128 v[128:131], v167
	ds_read_b128 v[132:135], v167 offset:1024
	ds_read_b128 v[136:139], v167 offset:2048
	ds_read_b128 v[140:143], v167 offset:3072
	ds_read_b128 v[160:163], v168
	ds_read_b128 v[170:173], v168 offset:1024
	ds_read_b128 v[174:177], v168 offset:2048
	ds_read_b128 v[178:181], v168 offset:3072
	s_add_u32 s12, s50, 0xfffc0080
	s_addc_u32 s13, s51, -1
	s_cmp_eq_u32 s79, 12
	s_cselect_b32 s55, s41, s13
	s_cselect_b32 s54, s47, s12
	s_cselect_b32 s53, s39, s78
	s_cselect_b32 s52, s49, s77
	s_add_i32 m0, s60, 0xc000
	ds_read_b128 v[188:191], v169
	ds_read_b128 v[192:195], v169 offset:1024
	ds_read_b128 v[196:199], v169 offset:2048
	ds_read_b128 v[200:203], v169 offset:3072
	ds_read_b128 v[204:207], v169 offset:4096
	ds_read_b128 v[208:211], v169 offset:5120
	ds_read_b128 v[212:215], v169 offset:6144
	ds_read_b128 v[216:219], v169 offset:7168
	global_load_lds_dwordx4 v154, s[50:51]
	s_add_i32 m0, s60, 0xe000
	s_nop 0
	global_load_lds_dwordx4 v152, s[50:51]
	s_waitcnt vmcnt(8)
	s_waitcnt lgkmcnt(0)
	s_barrier
	s_setprio 1
	s_waitcnt lgkmcnt(0)
	v_mfma_f32_16x16x32_bf16 v[124:127], v[128:131], v[188:191], v[124:127]
	v_mfma_f32_16x16x32_bf16 v[124:127], v[132:135], v[192:195], v[124:127]
	v_mfma_f32_16x16x32_bf16 v[120:123], v[136:139], v[188:191], v[120:123]
	v_mfma_f32_16x16x32_bf16 v[120:123], v[140:143], v[192:195], v[120:123]
	v_mfma_f32_16x16x32_bf16 v[108:111], v[136:139], v[196:199], v[108:111]
	v_mfma_f32_16x16x32_bf16 v[108:111], v[140:143], v[200:203], v[108:111]
	v_mfma_f32_16x16x32_bf16 v[116:119], v[128:131], v[196:199], v[116:119]
	v_mfma_f32_16x16x32_bf16 v[116:119], v[132:135], v[200:203], v[116:119]
	v_mfma_f32_16x16x32_bf16 v[100:103], v[128:131], v[204:207], v[100:103]
	v_mfma_f32_16x16x32_bf16 v[100:103], v[132:135], v[208:211], v[100:103]
	v_mfma_f32_16x16x32_bf16 v[92:95], v[136:139], v[204:207], v[92:95]
	v_mfma_f32_16x16x32_bf16 v[92:95], v[140:143], v[208:211], v[92:95]
	v_mfma_f32_16x16x32_bf16 v[76:79], v[136:139], v[212:215], v[76:79]
	v_mfma_f32_16x16x32_bf16 v[76:79], v[140:143], v[216:219], v[76:79]
	v_mfma_f32_16x16x32_bf16 v[84:87], v[128:131], v[212:215], v[84:87]
	v_mfma_f32_16x16x32_bf16 v[84:87], v[132:135], v[216:219], v[84:87]
	s_setprio 0
	s_setprio 1
	v_mfma_f32_16x16x32_bf16 v[112:115], v[160:163], v[188:191], v[112:115]
	v_mfma_f32_16x16x32_bf16 v[112:115], v[170:173], v[192:195], v[112:115]
	v_mfma_f32_16x16x32_bf16 v[104:107], v[174:177], v[188:191], v[104:107]
	v_mfma_f32_16x16x32_bf16 v[104:107], v[178:181], v[192:195], v[104:107]
	v_mfma_f32_16x16x32_bf16 v[88:91], v[174:177], v[196:199], v[88:91]
	v_mfma_f32_16x16x32_bf16 v[88:91], v[178:181], v[200:203], v[88:91]
	v_mfma_f32_16x16x32_bf16 v[96:99], v[160:163], v[196:199], v[96:99]
	v_mfma_f32_16x16x32_bf16 v[96:99], v[170:173], v[200:203], v[96:99]
	v_mfma_f32_16x16x32_bf16 v[80:83], v[160:163], v[204:207], v[80:83]
	v_mfma_f32_16x16x32_bf16 v[80:83], v[170:173], v[208:211], v[80:83]
	v_mfma_f32_16x16x32_bf16 v[72:75], v[174:177], v[204:207], v[72:75]
	v_mfma_f32_16x16x32_bf16 v[72:75], v[178:181], v[208:211], v[72:75]
	v_mfma_f32_16x16x32_bf16 v[64:67], v[174:177], v[212:215], v[64:67]
	v_mfma_f32_16x16x32_bf16 v[64:67], v[178:181], v[216:219], v[64:67]
	v_mfma_f32_16x16x32_bf16 v[68:71], v[160:163], v[212:215], v[68:71]
	v_mfma_f32_16x16x32_bf16 v[68:71], v[170:173], v[216:219], v[68:71]
	s_setprio 0
	s_barrier
	s_add_i32 s12, s75, s59
	s_mov_b32 m0, s12
	ds_read_b128 v[188:191], v169 offset:16384
	ds_read_b128 v[192:195], v169 offset:17408
	ds_read_b128 v[196:199], v169 offset:18432
	ds_read_b128 v[200:203], v169 offset:19456
	ds_read_b128 v[204:207], v169 offset:20480
	ds_read_b128 v[208:211], v169 offset:21504
	ds_read_b128 v[212:215], v169 offset:22528
	ds_read_b128 v[216:219], v169 offset:23552
	global_load_lds_dwordx4 v146, s[52:53]
	s_add_i32 m0, s12, 0x2000
	s_add_u32 s80, s52, 0x40000
	v_lshl_add_u64 v[220:221], s[52:53], 0, v[150:151]
	s_addc_u32 s81, s53, 0
	s_add_i32 s12, s76, s59
	global_load_lds_dwordx4 v150, s[52:53]
	s_mov_b32 m0, s12
	v_lshl_add_u64 v[224:225], s[54:55], 0, v[148:149]
	global_load_lds_dwordx4 v146, s[80:81]
	s_add_i32 m0, s12, 0x2000
	s_nop 0
	global_load_lds_dwordx4 v150, s[80:81]
	v_lshl_add_u64 v[222:223], s[54:55], 0, v[144:145]
	s_mov_b32 m0, s60
	s_nop 0
	global_load_lds_dwordx4 v144, s[54:55]
	s_mov_b32 m0, s61
	s_nop 0
	global_load_lds_dwordx4 v148, s[54:55]
	s_waitcnt vmcnt(8)
	s_waitcnt lgkmcnt(0)
	s_barrier
	s_setprio 1
	s_waitcnt lgkmcnt(0)
	v_mfma_f32_16x16x32_bf16 v[60:63], v[128:131], v[188:191], v[60:63]
	v_mfma_f32_16x16x32_bf16 v[60:63], v[132:135], v[192:195], v[60:63]
	v_mfma_f32_16x16x32_bf16 v[56:59], v[136:139], v[188:191], v[56:59]
	v_mfma_f32_16x16x32_bf16 v[56:59], v[140:143], v[192:195], v[56:59]
	v_mfma_f32_16x16x32_bf16 v[44:47], v[136:139], v[196:199], v[44:47]
	v_mfma_f32_16x16x32_bf16 v[44:47], v[140:143], v[200:203], v[44:47]
	v_mfma_f32_16x16x32_bf16 v[48:51], v[128:131], v[196:199], v[48:51]
	v_mfma_f32_16x16x32_bf16 v[48:51], v[132:135], v[200:203], v[48:51]
	v_mfma_f32_16x16x32_bf16 v[36:39], v[128:131], v[204:207], v[36:39]
	v_mfma_f32_16x16x32_bf16 v[36:39], v[132:135], v[208:211], v[36:39]
	v_mfma_f32_16x16x32_bf16 v[28:31], v[136:139], v[204:207], v[28:31]
	v_mfma_f32_16x16x32_bf16 v[28:31], v[140:143], v[208:211], v[28:31]
	v_mfma_f32_16x16x32_bf16 v[12:15], v[136:139], v[212:215], v[12:15]
	v_mfma_f32_16x16x32_bf16 v[12:15], v[140:143], v[216:219], v[12:15]
	v_mfma_f32_16x16x32_bf16 v[20:23], v[128:131], v[212:215], v[20:23]
	v_mfma_f32_16x16x32_bf16 v[20:23], v[132:135], v[216:219], v[20:23]
	s_setprio 0
	s_setprio 1
	v_mfma_f32_16x16x32_bf16 v[52:55], v[160:163], v[188:191], v[52:55]
	v_mfma_f32_16x16x32_bf16 v[52:55], v[170:173], v[192:195], v[52:55]
	v_mfma_f32_16x16x32_bf16 v[40:43], v[174:177], v[188:191], v[40:43]
	v_mfma_f32_16x16x32_bf16 v[40:43], v[178:181], v[192:195], v[40:43]
	v_mfma_f32_16x16x32_bf16 v[24:27], v[174:177], v[196:199], v[24:27]
	v_mfma_f32_16x16x32_bf16 v[24:27], v[178:181], v[200:203], v[24:27]
	v_mfma_f32_16x16x32_bf16 v[32:35], v[160:163], v[196:199], v[32:35]
	v_mfma_f32_16x16x32_bf16 v[32:35], v[170:173], v[200:203], v[32:35]
	v_mfma_f32_16x16x32_bf16 v[16:19], v[160:163], v[204:207], v[16:19]
	v_mfma_f32_16x16x32_bf16 v[16:19], v[170:173], v[208:211], v[16:19]
	v_mfma_f32_16x16x32_bf16 v[8:11], v[174:177], v[204:207], v[8:11]
	v_mfma_f32_16x16x32_bf16 v[8:11], v[178:181], v[208:211], v[8:11]
	v_mfma_f32_16x16x32_bf16 v[0:3], v[174:177], v[212:215], v[0:3]
	v_mfma_f32_16x16x32_bf16 v[0:3], v[178:181], v[216:219], v[0:3]
	v_mfma_f32_16x16x32_bf16 v[4:7], v[160:163], v[212:215], v[4:7]
	v_mfma_f32_16x16x32_bf16 v[4:7], v[170:173], v[216:219], v[4:7]
	s_setprio 0
	s_barrier
; #define PG8_STAGE(bufoff, gbase, voff) do { _Pragma("unroll") for (int _i = 0; _i < 2; ++_i) \
;         __builtin_amdgcn_global_load_lds((const unsigned*)((const char*)(gbase) + (voff)[_i]), (PG8_LAS unsigned*)(lds + (bufoff) + ldsw + _i * 8192), 16, 0, 0); } while (0)
; #define PG8_LDA(dst, b, h) do { _Pragma("unroll") for (int m = 0; m < 4; ++m) _Pragma("unroll") for (int k = 0; k < 2; ++k) dst[m][k] = *(const PG8_LAS bf16x8*)(lds + PG8_SA(b, h) + aoff + m * 2048 + k * 1024); } while (0)
; #define PG8_LDB(dst, b, h) do { _Pragma("unroll") for (int n = 0; n < 2; ++n) _Pragma("unroll") for (int k = 0; k < 2; ++k) dst[n][k] = *(const PG8_LAS bf16x8*)(lds + PG8_SB(b, h) + boff + n * 2048 + k * 1024); } while (0)
; #define PG8_MMA(ai, bj, At, Bt) do { __builtin_amdgcn_s_setprio(1); _Pragma("unroll") for (int m = 0; m < 4; ++m) _Pragma("unroll") for (int n = 0; n < 2; ++n) _Pragma("unroll") for (int k = 0; k < 2; ++k) \
;         acc[ai][bj][m][n] = __builtin_amdgcn_mfma_f32_16x16x32_bf16(Bt[n][k], At[m][k], acc[ai][bj][m][n], 0, 0, 0); __builtin_amdgcn_s_setprio(0); } while (0)
; #define PG8_WAIT_V(n) asm volatile("s_waitcnt vmcnt(" #n ")" ::: "memory")
; #define PG8_WAIT_L(n) asm volatile("s_waitcnt lgkmcnt(" #n ")" ::: "memory")
; #define PG8_BAR __builtin_amdgcn_s_barrier()
; #define PG8_SCHED __builtin_amdgcn_sched_barrier(0)
; template <class Epi, class Sched, bool ALIGN_EPI = false, bool SP2 = false>
; __device__ __forceinline__ void gemm_phase(PG8_LAS unsigned char* lds, const Gemm g, const Sched& S, const Epi& E) {
;     ...
;             PG8_LDB(B0, 1, 0); PG8_LDB(B1, 1, 1); PG8_SCHED; PG8_LDA(At, 1, 0); PG8_STAGE(PG8_SA(0, 1), a2 + hstep, voffA);
;             PG8_WAIT_V(8); PG8_WAIT_L(0); PG8_BAR; PG8_MMA(0, 0, At, B0); PG8_MMA(0, 1, At, B1); PG8_BAR; PG8_SCHED;
;             PG8_LDA(At, 1, 1); PG8_STAGE(PG8_SB(1, 0), b3, voffB); PG8_STAGE(PG8_SB(1, 1), b3 + hstep, voffB); PG8_STAGE(PG8_SA(1, 0), a3, voffA);
;             PG8_WAIT_V(8); PG8_WAIT_L(0); PG8_BAR; PG8_MMA(1, 0, At, B0); PG8_MMA(1, 1, At, B1); PG8_BAR; PG8_SCHED;
	s_add_i32 s12, 0, 0x18000
	s_add_i32 s13, 0, 0x1c000
	v_add_u32_e32 v140, s12, v165
	v_add_u32_e32 v178, s13, v165
	ds_read_b128 v[128:131], v140
	ds_read_b128 v[132:135], v140 offset:1024
	ds_read_b128 v[136:139], v140 offset:2048
	ds_read_b128 v[140:143], v140 offset:3072
	ds_read_b128 v[160:163], v178
	ds_read_b128 v[170:173], v178 offset:1024
	ds_read_b128 v[174:177], v178 offset:2048
	ds_read_b128 v[178:181], v178 offset:3072
	s_add_u32 s54, s54, 0x40000
	s_addc_u32 s55, s55, 0
	s_mov_b32 m0, s62
	ds_read_b128 v[188:191], v169 offset:32768
	ds_read_b128 v[192:195], v169 offset:33792
	ds_read_b128 v[196:199], v169 offset:34816
	ds_read_b128 v[200:203], v169 offset:35840
	ds_read_b128 v[204:207], v169 offset:36864
	ds_read_b128 v[208:211], v169 offset:37888
	ds_read_b128 v[212:215], v169 offset:38912
	ds_read_b128 v[216:219], v169 offset:39936
	global_load_lds_dwordx4 v144, s[54:55]
	s_mov_b32 m0, s63
	s_nop 0
	global_load_lds_dwordx4 v148, s[54:55]
	s_waitcnt vmcnt(8)
	s_waitcnt lgkmcnt(0)
	s_barrier
	s_setprio 1
	s_waitcnt lgkmcnt(0)
	v_mfma_f32_16x16x32_bf16 v[124:127], v[128:131], v[188:191], v[124:127]
	v_mfma_f32_16x16x32_bf16 v[124:127], v[132:135], v[192:195], v[124:127]
	v_mfma_f32_16x16x32_bf16 v[120:123], v[136:139], v[188:191], v[120:123]
	v_mfma_f32_16x16x32_bf16 v[120:123], v[140:143], v[192:195], v[120:123]
	v_mfma_f32_16x16x32_bf16 v[108:111], v[136:139], v[196:199], v[108:111]
	v_mfma_f32_16x16x32_bf16 v[108:111], v[140:143], v[200:203], v[108:111]
	v_mfma_f32_16x16x32_bf16 v[116:119], v[128:131], v[196:199], v[116:119]
	v_mfma_f32_16x16x32_bf16 v[116:119], v[132:135], v[200:203], v[116:119]
	v_mfma_f32_16x16x32_bf16 v[100:103], v[128:131], v[204:207], v[100:103]
	v_mfma_f32_16x16x32_bf16 v[100:103], v[132:135], v[208:211], v[100:103]
	v_mfma_f32_16x16x32_bf16 v[92:95], v[136:139], v[204:207], v[92:95]
	v_mfma_f32_16x16x32_bf16 v[92:95], v[140:143], v[208:211], v[92:95]
	v_mfma_f32_16x16x32_bf16 v[76:79], v[136:139], v[212:215], v[76:79]
	v_mfma_f32_16x16x32_bf16 v[76:79], v[140:143], v[216:219], v[76:79]
	v_mfma_f32_16x16x32_bf16 v[84:87], v[128:131], v[212:215], v[84:87]
	v_mfma_f32_16x16x32_bf16 v[84:87], v[132:135], v[216:219], v[84:87]
	s_setprio 0
	s_setprio 1
	v_mfma_f32_16x16x32_bf16 v[112:115], v[160:163], v[188:191], v[112:115]
	v_mfma_f32_16x16x32_bf16 v[112:115], v[170:173], v[192:195], v[112:115]
	v_mfma_f32_16x16x32_bf16 v[104:107], v[174:177], v[188:191], v[104:107]
	v_mfma_f32_16x16x32_bf16 v[104:107], v[178:181], v[192:195], v[104:107]
	v_mfma_f32_16x16x32_bf16 v[88:91], v[174:177], v[196:199], v[88:91]
	v_mfma_f32_16x16x32_bf16 v[88:91], v[178:181], v[200:203], v[88:91]
	v_mfma_f32_16x16x32_bf16 v[96:99], v[160:163], v[196:199], v[96:99]
	v_mfma_f32_16x16x32_bf16 v[96:99], v[170:173], v[200:203], v[96:99]
	v_mfma_f32_16x16x32_bf16 v[80:83], v[160:163], v[204:207], v[80:83]
	v_mfma_f32_16x16x32_bf16 v[80:83], v[170:173], v[208:211], v[80:83]
	v_mfma_f32_16x16x32_bf16 v[72:75], v[174:177], v[204:207], v[72:75]
	v_mfma_f32_16x16x32_bf16 v[72:75], v[178:181], v[208:211], v[72:75]
	v_mfma_f32_16x16x32_bf16 v[64:67], v[174:177], v[212:215], v[64:67]
	v_mfma_f32_16x16x32_bf16 v[64:67], v[178:181], v[216:219], v[64:67]
	v_mfma_f32_16x16x32_bf16 v[68:71], v[160:163], v[212:215], v[68:71]
	v_mfma_f32_16x16x32_bf16 v[68:71], v[170:173], v[216:219], v[68:71]
	s_setprio 0
	s_barrier
	s_add_i32 s12, s12, s59
	s_add_u32 s98, s52, s22
	s_addc_u32 s99, s53, s23
	s_mov_b32 m0, s12
	ds_read_b128 v[188:191], v169 offset:49152
	ds_read_b128 v[192:195], v169 offset:50176
	ds_read_b128 v[196:199], v169 offset:51200
	ds_read_b128 v[200:203], v169 offset:52224
	ds_read_b128 v[204:207], v169 offset:53248
	ds_read_b128 v[208:211], v169 offset:54272
	ds_read_b128 v[212:215], v169 offset:55296
	ds_read_b128 v[216:219], v169 offset:56320
	global_load_lds_dwordx4 v146, s[98:99]
	s_add_i32 m0, s12, 0x2000
	s_add_u32 s52, s52, 0x40080
	v_lshl_add_u64 v[184:185], v[220:221], 0, s[22:23]
	s_addc_u32 s53, s53, 0
	s_add_i32 s12, s13, s59
	global_load_lds_dwordx4 v[184:185], off
	s_mov_b32 m0, s12
	s_nop 0
	global_load_lds_dwordx4 v146, s[52:53]
	s_add_i32 m0, s12, 0x2000
	s_nop 0
	global_load_lds_dwordx4 v150, s[52:53]
	v_lshl_add_u64 v[184:185], v[222:223], 0, s[22:23]
	s_mov_b32 m0, s69
	s_nop 0
	global_load_lds_dwordx4 v[184:185], off
	v_lshl_add_u64 v[184:185], v[224:225], 0, s[22:23]
	s_mov_b32 m0, s70
	s_nop 0
	global_load_lds_dwordx4 v[184:185], off
	s_waitcnt vmcnt(8)
	s_waitcnt lgkmcnt(0)
	s_barrier
	s_setprio 1
	s_waitcnt lgkmcnt(0)
	v_mfma_f32_16x16x32_bf16 v[60:63], v[128:131], v[188:191], v[60:63]
	v_mfma_f32_16x16x32_bf16 v[60:63], v[132:135], v[192:195], v[60:63]
	v_mfma_f32_16x16x32_bf16 v[56:59], v[136:139], v[188:191], v[56:59]
	v_mfma_f32_16x16x32_bf16 v[56:59], v[140:143], v[192:195], v[56:59]
	v_mfma_f32_16x16x32_bf16 v[44:47], v[136:139], v[196:199], v[44:47]
	v_mfma_f32_16x16x32_bf16 v[44:47], v[140:143], v[200:203], v[44:47]
	v_mfma_f32_16x16x32_bf16 v[48:51], v[128:131], v[196:199], v[48:51]
	v_mfma_f32_16x16x32_bf16 v[48:51], v[132:135], v[200:203], v[48:51]
	v_mfma_f32_16x16x32_bf16 v[36:39], v[128:131], v[204:207], v[36:39]
	v_mfma_f32_16x16x32_bf16 v[36:39], v[132:135], v[208:211], v[36:39]
	v_mfma_f32_16x16x32_bf16 v[28:31], v[136:139], v[204:207], v[28:31]
	v_mfma_f32_16x16x32_bf16 v[28:31], v[140:143], v[208:211], v[28:31]
	v_mfma_f32_16x16x32_bf16 v[12:15], v[136:139], v[212:215], v[12:15]
	v_mfma_f32_16x16x32_bf16 v[12:15], v[140:143], v[216:219], v[12:15]
	v_mfma_f32_16x16x32_bf16 v[20:23], v[128:131], v[212:215], v[20:23]
	v_mfma_f32_16x16x32_bf16 v[20:23], v[132:135], v[216:219], v[20:23]
	s_setprio 0
	s_setprio 1
	v_mfma_f32_16x16x32_bf16 v[52:55], v[160:163], v[188:191], v[52:55]
	v_mfma_f32_16x16x32_bf16 v[52:55], v[170:173], v[192:195], v[52:55]
	v_mfma_f32_16x16x32_bf16 v[40:43], v[174:177], v[188:191], v[40:43]
	v_mfma_f32_16x16x32_bf16 v[40:43], v[178:181], v[192:195], v[40:43]
	v_mfma_f32_16x16x32_bf16 v[24:27], v[174:177], v[196:199], v[24:27]
	v_mfma_f32_16x16x32_bf16 v[24:27], v[178:181], v[200:203], v[24:27]
	v_mfma_f32_16x16x32_bf16 v[32:35], v[160:163], v[196:199], v[32:35]
	v_mfma_f32_16x16x32_bf16 v[32:35], v[170:173], v[200:203], v[32:35]
	v_mfma_f32_16x16x32_bf16 v[16:19], v[160:163], v[204:207], v[16:19]
	v_mfma_f32_16x16x32_bf16 v[16:19], v[170:173], v[208:211], v[16:19]
	v_mfma_f32_16x16x32_bf16 v[8:11], v[174:177], v[204:207], v[8:11]
	v_mfma_f32_16x16x32_bf16 v[8:11], v[178:181], v[208:211], v[8:11]
	v_mfma_f32_16x16x32_bf16 v[0:3], v[174:177], v[212:215], v[0:3]
	v_mfma_f32_16x16x32_bf16 v[0:3], v[178:181], v[216:219], v[0:3]
	v_mfma_f32_16x16x32_bf16 v[4:7], v[160:163], v[212:215], v[4:7]
	v_mfma_f32_16x16x32_bf16 v[4:7], v[170:173], v[216:219], v[4:7]
	s_setprio 0
	s_barrier
	s_add_i32 s79, s79, 2
	s_add_u32 s77, s77, 0x100
	s_addc_u32 s78, s78, 0
	s_add_u32 s50, s50, 0x100
	s_addc_u32 s51, s51, 0
	s_cmp_gt_u32 s79, 13
	s_cbranch_scc0 .LBB0_1272
	s_and_b64 vcc, exec, s[36:37]
	s_cbranch_vccz .LBB0_1275
	s_barrier

; #define PG8_STAGE(bufoff, gbase, voff) do { _Pragma("unroll") for (int _i = 0; _i < 2; ++_i) \
;         __builtin_amdgcn_global_load_lds((const unsigned*)((const char*)(gbase) + (voff)[_i]), (PG8_LAS unsigned*)(lds + (bufoff) + ldsw + _i * 8192), 16, 0, 0); } while (0)
; #define PG8_LDA(dst, b, h) do { _Pragma("unroll") for (int m = 0; m < 4; ++m) _Pragma("unroll") for (int k = 0; k < 2; ++k) dst[m][k] = *(const PG8_LAS bf16x8*)(lds + PG8_SA(b, h) + aoff + m * 2048 + k * 1024); } while (0)
; #define PG8_LDB(dst, b, h) do { _Pragma("unroll") for (int n = 0; n < 2; ++n) _Pragma("unroll") for (int k = 0; k < 2; ++k) dst[n][k] = *(const PG8_LAS bf16x8*)(lds + PG8_SB(b, h) + boff + n * 2048 + k * 1024); } while (0)
; #define PG8_MMA(ai, bj, At, Bt) do { __builtin_amdgcn_s_setprio(1); _Pragma("unroll") for (int m = 0; m < 4; ++m) _Pragma("unroll") for (int n = 0; n < 2; ++n) _Pragma("unroll") for (int k = 0; k < 2; ++k) \
;         acc[ai][bj][m][n] = __builtin_amdgcn_mfma_f32_16x16x32_bf16(Bt[n][k], At[m][k], acc[ai][bj][m][n], 0, 0, 0); __builtin_amdgcn_s_setprio(0); } while (0)
; #define PG8_WAIT_V(n) asm volatile("s_waitcnt vmcnt(" #n ")" ::: "memory")
; #define PG8_WAIT_L(n) asm volatile("s_waitcnt lgkmcnt(" #n ")" ::: "memory")
; #define PG8_BAR __builtin_amdgcn_s_barrier()
; #define PG8_SCHED __builtin_amdgcn_sched_barrier(0)
; template <class Epi, class Sched, bool ALIGN_EPI = false, bool SP2 = false>
; __device__ __forceinline__ void gemm_phase(PG8_LAS unsigned char* lds, const Gemm g, const Sched& S, const Epi& E) {
;     ...
;             PG8_LDB(B0, 0, 0); PG8_LDB(B1, 0, 1); PG8_SCHED; PG8_LDA(At, 0, 0); PG8_STAGE(PG8_SA(1, 1), a1 + hstep, voffA);
;             PG8_WAIT_V(8); PG8_WAIT_L(0); PG8_BAR; PG8_MMA(0, 0, At, B0); PG8_MMA(0, 1, At, B1); PG8_BAR; PG8_SCHED;
;             PG8_LDA(At, 0, 1); PG8_STAGE(PG8_SB(0, 0), b2, voffB); PG8_STAGE(PG8_SB(0, 1), b2 + hstep, voffB); PG8_STAGE(PG8_SA(0, 0), a2, voffA);
;             PG8_WAIT_V(8); PG8_WAIT_L(0); PG8_BAR; PG8_MMA(1, 0, At, B0); PG8_MMA(1, 1, At, B1); PG8_BAR; PG8_SCHED;
.LBB0_1358:
	v_add_u32_e32 v130, s71, v163
	ds_read_b128 v[118:121], v130
	ds_read_b128 v[122:125], v130 offset:1024
	ds_read_b128 v[126:129], v130 offset:2048
	ds_read_b128 v[170:173], v130 offset:3072
	v_add_u32_e32 v130, s72, v163
	ds_read_b128 v[174:177], v130
	ds_read_b128 v[178:181], v130 offset:1024
	ds_read_b128 v[184:187], v130 offset:2048
	ds_read_b128 v[188:191], v130 offset:3072
	s_add_u32 s14, s48, 0xfffc0080
	s_addc_u32 s15, s49, -1
	s_and_b64 s[50:51], s[50:51], exec
	s_cselect_b32 s53, s39, s15
	s_cselect_b32 s52, s73, s14
	s_cselect_b32 s51, s37, s47
	s_cselect_b32 s50, s74, s45
	s_add_i32 m0, s58, 0xc000
	ds_read_b128 v[192:195], v168
	ds_read_b128 v[196:199], v168 offset:1024
	ds_read_b128 v[200:203], v168 offset:2048
	ds_read_b128 v[204:207], v168 offset:3072
	ds_read_b128 v[208:211], v168 offset:4096
	ds_read_b128 v[212:215], v168 offset:5120
	ds_read_b128 v[216:219], v168 offset:6144
	ds_read_b128 v[220:223], v168 offset:7168
	global_load_lds_dwordx4 v154, s[48:49]
	s_add_i32 m0, s58, 0xe000
	s_nop 0
	global_load_lds_dwordx4 v152, s[48:49]
	s_waitcnt vmcnt(8)
	s_waitcnt lgkmcnt(0)
	s_barrier
	s_setprio 1
	s_waitcnt lgkmcnt(0)
	v_mfma_f32_16x16x32_bf16 v[140:143], v[118:121], v[192:195], v[140:143]
	v_mfma_f32_16x16x32_bf16 v[140:143], v[122:125], v[196:199], v[140:143]
	v_mfma_f32_16x16x32_bf16 v[136:139], v[126:129], v[192:195], v[136:139]
	v_mfma_f32_16x16x32_bf16 v[136:139], v[170:173], v[196:199], v[136:139]
	v_mfma_f32_16x16x32_bf16 v[104:107], v[126:129], v[200:203], v[104:107]
	v_mfma_f32_16x16x32_bf16 v[104:107], v[170:173], v[204:207], v[104:107]
	v_mfma_f32_16x16x32_bf16 v[108:111], v[118:121], v[200:203], v[108:111]
	v_mfma_f32_16x16x32_bf16 v[108:111], v[122:125], v[204:207], v[108:111]
	v_mfma_f32_16x16x32_bf16 v[92:95], v[118:121], v[208:211], v[92:95]
	v_mfma_f32_16x16x32_bf16 v[92:95], v[122:125], v[212:215], v[92:95]
	v_mfma_f32_16x16x32_bf16 v[88:91], v[126:129], v[208:211], v[88:91]
	v_mfma_f32_16x16x32_bf16 v[88:91], v[170:173], v[212:215], v[88:91]
	v_mfma_f32_16x16x32_bf16 v[72:75], v[126:129], v[216:219], v[72:75]
	v_mfma_f32_16x16x32_bf16 v[72:75], v[170:173], v[220:223], v[72:75]
	v_mfma_f32_16x16x32_bf16 v[76:79], v[118:121], v[216:219], v[76:79]
	v_mfma_f32_16x16x32_bf16 v[76:79], v[122:125], v[220:223], v[76:79]
	s_setprio 0
	s_setprio 1
	v_mfma_f32_16x16x32_bf16 v[130:133], v[174:177], v[192:195], v[132:135]
	v_mfma_f32_16x16x32_bf16 v[130:133], v[178:181], v[196:199], v[130:133]
	v_mfma_f32_16x16x32_bf16 v[112:115], v[184:187], v[192:195], v[112:115]
	v_mfma_f32_16x16x32_bf16 v[112:115], v[188:191], v[196:199], v[112:115]
	v_mfma_f32_16x16x32_bf16 v[96:99], v[184:187], v[200:203], v[96:99]
	v_mfma_f32_16x16x32_bf16 v[96:99], v[188:191], v[204:207], v[96:99]
	v_mfma_f32_16x16x32_bf16 v[100:103], v[174:177], v[200:203], v[100:103]
	v_mfma_f32_16x16x32_bf16 v[100:103], v[178:181], v[204:207], v[100:103]
	v_mfma_f32_16x16x32_bf16 v[84:87], v[174:177], v[208:211], v[84:87]
	v_mfma_f32_16x16x32_bf16 v[84:87], v[178:181], v[212:215], v[84:87]
	v_mfma_f32_16x16x32_bf16 v[80:83], v[184:187], v[208:211], v[80:83]
	v_mfma_f32_16x16x32_bf16 v[80:83], v[188:191], v[212:215], v[80:83]
	v_mfma_f32_16x16x32_bf16 v[64:67], v[184:187], v[216:219], v[64:67]
	v_mfma_f32_16x16x32_bf16 v[64:67], v[188:191], v[220:223], v[64:67]
	v_mfma_f32_16x16x32_bf16 v[68:71], v[174:177], v[216:219], v[68:71]
	v_mfma_f32_16x16x32_bf16 v[68:71], v[178:181], v[220:223], v[68:71]
	s_setprio 0
	s_barrier
	s_add_i32 s14, s71, s55
	s_mov_b32 m0, s14
	ds_read_b128 v[192:195], v168 offset:16384
	ds_read_b128 v[196:199], v168 offset:17408
	ds_read_b128 v[200:203], v168 offset:18432
	ds_read_b128 v[204:207], v168 offset:19456
	ds_read_b128 v[208:211], v168 offset:20480
	ds_read_b128 v[212:215], v168 offset:21504
	ds_read_b128 v[216:219], v168 offset:22528
	ds_read_b128 v[220:223], v168 offset:23552
	global_load_lds_dwordx4 v148, s[50:51]
	s_add_i32 m0, s14, 0x2000
	s_add_u32 s76, s50, 0x40000
	v_lshl_add_u64 v[226:227], s[50:51], 0, v[144:145]
	s_addc_u32 s77, s51, 0
	s_add_i32 s14, s72, s55
	global_load_lds_dwordx4 v144, s[50:51]
	s_mov_b32 m0, s14
	v_lshl_add_u64 v[228:229], s[52:53], 0, v[150:151]
	global_load_lds_dwordx4 v148, s[76:77]
	s_add_i32 m0, s14, 0x2000
	v_lshl_add_u64 v[230:231], s[52:53], 0, v[146:147]
	global_load_lds_dwordx4 v144, s[76:77]
	s_mov_b32 m0, s58
	s_nop 0
	global_load_lds_dwordx4 v150, s[52:53]
	s_mov_b32 m0, s59
	s_nop 0
	global_load_lds_dwordx4 v146, s[52:53]
	s_waitcnt vmcnt(8)
	s_waitcnt lgkmcnt(0)
	s_barrier
; #define PG8_STAGE(bufoff, gbase, voff) do { _Pragma("unroll") for (int _i = 0; _i < 2; ++_i) \
;         __builtin_amdgcn_global_load_lds((const unsigned*)((const char*)(gbase) + (voff)[_i]), (PG8_LAS unsigned*)(lds + (bufoff) + ldsw + _i * 8192), 16, 0, 0); } while (0)
; #define PG8_LDA(dst, b, h) do { _Pragma("unroll") for (int m = 0; m < 4; ++m) _Pragma("unroll") for (int k = 0; k < 2; ++k) dst[m][k] = *(const PG8_LAS bf16x8*)(lds + PG8_SA(b, h) + aoff + m * 2048 + k * 1024); } while (0)
; #define PG8_LDB(dst, b, h) do { _Pragma("unroll") for (int n = 0; n < 2; ++n) _Pragma("unroll") for (int k = 0; k < 2; ++k) dst[n][k] = *(const PG8_LAS bf16x8*)(lds + PG8_SB(b, h) + boff + n * 2048 + k * 1024); } while (0)
; #define PG8_MMA(ai, bj, At, Bt) do { __builtin_amdgcn_s_setprio(1); _Pragma("unroll") for (int m = 0; m < 4; ++m) _Pragma("unroll") for (int n = 0; n < 2; ++n) _Pragma("unroll") for (int k = 0; k < 2; ++k) \
;         acc[ai][bj][m][n] = __builtin_amdgcn_mfma_f32_16x16x32_bf16(Bt[n][k], At[m][k], acc[ai][bj][m][n], 0, 0, 0); __builtin_amdgcn_s_setprio(0); } while (0)
; #define PG8_WAIT_V(n) asm volatile("s_waitcnt vmcnt(" #n ")" ::: "memory")
; #define PG8_WAIT_L(n) asm volatile("s_waitcnt lgkmcnt(" #n ")" ::: "memory")
; #define PG8_BAR __builtin_amdgcn_s_barrier()
; #define PG8_SCHED __builtin_amdgcn_sched_barrier(0)
; template <class Epi, class Sched, bool ALIGN_EPI = false, bool SP2 = false>
; __device__ __forceinline__ void gemm_phase(PG8_LAS unsigned char* lds, const Gemm g, const Sched& S, const Epi& E) {
;     ...
;             PG8_WAIT_V(8); PG8_WAIT_L(0); PG8_BAR; PG8_MMA(1, 0, At, B0); PG8_MMA(1, 1, At, B1); PG8_BAR; PG8_SCHED;
;             PG8_LDB(B0, 1, 0); PG8_LDB(B1, 1, 1); PG8_SCHED; PG8_LDA(At, 1, 0); PG8_STAGE(PG8_SA(0, 1), a2 + hstep, voffA);
;             PG8_WAIT_V(8); PG8_WAIT_L(0); PG8_BAR; PG8_MMA(0, 0, At, B0); PG8_MMA(0, 1, At, B1); PG8_BAR; PG8_SCHED;
;             PG8_LDA(At, 1, 1); PG8_STAGE(PG8_SB(1, 0), b3, voffB); PG8_STAGE(PG8_SB(1, 1), b3 + hstep, voffB); PG8_STAGE(PG8_SA(1, 0), a3, voffA);
	s_setprio 1
	s_waitcnt lgkmcnt(0)
	v_mfma_f32_16x16x32_bf16 v[60:63], v[118:121], v[192:195], v[60:63]
	v_mfma_f32_16x16x32_bf16 v[60:63], v[122:125], v[196:199], v[60:63]
	v_mfma_f32_16x16x32_bf16 v[56:59], v[126:129], v[192:195], v[56:59]
	v_mfma_f32_16x16x32_bf16 v[56:59], v[170:173], v[196:199], v[56:59]
	v_mfma_f32_16x16x32_bf16 v[40:43], v[126:129], v[200:203], v[40:43]
	v_mfma_f32_16x16x32_bf16 v[40:43], v[170:173], v[204:207], v[40:43]
	v_mfma_f32_16x16x32_bf16 v[44:47], v[118:121], v[200:203], v[44:47]
	v_mfma_f32_16x16x32_bf16 v[44:47], v[122:125], v[204:207], v[44:47]
	v_mfma_f32_16x16x32_bf16 v[28:31], v[118:121], v[208:211], v[28:31]
	v_mfma_f32_16x16x32_bf16 v[28:31], v[122:125], v[212:215], v[28:31]
	v_mfma_f32_16x16x32_bf16 v[24:27], v[126:129], v[208:211], v[24:27]
	v_mfma_f32_16x16x32_bf16 v[24:27], v[170:173], v[212:215], v[24:27]
	v_mfma_f32_16x16x32_bf16 v[8:11], v[126:129], v[216:219], v[8:11]
	v_mfma_f32_16x16x32_bf16 v[8:11], v[170:173], v[220:223], v[8:11]
	v_mfma_f32_16x16x32_bf16 v[12:15], v[118:121], v[216:219], v[12:15]
	v_mfma_f32_16x16x32_bf16 v[12:15], v[122:125], v[220:223], v[12:15]
	s_setprio 0
	s_setprio 1
	v_mfma_f32_16x16x32_bf16 v[52:55], v[174:177], v[192:195], v[52:55]
	v_mfma_f32_16x16x32_bf16 v[52:55], v[178:181], v[196:199], v[52:55]
	v_mfma_f32_16x16x32_bf16 v[48:51], v[184:187], v[192:195], v[48:51]
	v_mfma_f32_16x16x32_bf16 v[48:51], v[188:191], v[196:199], v[48:51]
	v_mfma_f32_16x16x32_bf16 v[32:35], v[184:187], v[200:203], v[32:35]
	v_mfma_f32_16x16x32_bf16 v[32:35], v[188:191], v[204:207], v[32:35]
	v_mfma_f32_16x16x32_bf16 v[36:39], v[174:177], v[200:203], v[36:39]
	v_mfma_f32_16x16x32_bf16 v[36:39], v[178:181], v[204:207], v[36:39]
	v_mfma_f32_16x16x32_bf16 v[20:23], v[174:177], v[208:211], v[20:23]
	v_mfma_f32_16x16x32_bf16 v[20:23], v[178:181], v[212:215], v[20:23]
	v_mfma_f32_16x16x32_bf16 v[16:19], v[184:187], v[208:211], v[16:19]
	v_mfma_f32_16x16x32_bf16 v[16:19], v[188:191], v[212:215], v[16:19]
	v_mfma_f32_16x16x32_bf16 v[0:3], v[184:187], v[216:219], v[0:3]
	v_mfma_f32_16x16x32_bf16 v[0:3], v[188:191], v[220:223], v[0:3]
	v_mfma_f32_16x16x32_bf16 v[4:7], v[174:177], v[216:219], v[4:7]
	v_mfma_f32_16x16x32_bf16 v[4:7], v[178:181], v[220:223], v[4:7]
	s_setprio 0
	s_barrier
	s_add_i32 s14, 0, 0x18000
	v_add_u32_e32 v134, s14, v163
	s_add_i32 s15, 0, 0x1c000
	ds_read_b128 v[118:121], v134
	ds_read_b128 v[122:125], v134 offset:1024
	ds_read_b128 v[126:129], v134 offset:2048
	ds_read_b128 v[170:173], v134 offset:3072
	v_add_u32_e32 v134, s15, v163
	ds_read_b128 v[174:177], v134
	ds_read_b128 v[178:181], v134 offset:1024
	ds_read_b128 v[184:187], v134 offset:2048
	ds_read_b128 v[188:191], v134 offset:3072
	s_add_u32 s52, s52, 0x40000
	s_addc_u32 s53, s53, 0
	s_mov_b32 m0, s60
	ds_read_b128 v[192:195], v168 offset:32768
	ds_read_b128 v[196:199], v168 offset:33792
	ds_read_b128 v[200:203], v168 offset:34816
	ds_read_b128 v[204:207], v168 offset:35840
	ds_read_b128 v[208:211], v168 offset:36864
	ds_read_b128 v[212:215], v168 offset:37888
	ds_read_b128 v[216:219], v168 offset:38912
	ds_read_b128 v[220:223], v168 offset:39936
	global_load_lds_dwordx4 v150, s[52:53]
	s_mov_b32 m0, s61
	s_nop 0
	global_load_lds_dwordx4 v146, s[52:53]
	s_waitcnt vmcnt(8)
	s_waitcnt lgkmcnt(0)
	s_barrier
	s_setprio 1
	s_waitcnt lgkmcnt(0)
	v_mfma_f32_16x16x32_bf16 v[140:143], v[118:121], v[192:195], v[140:143]
	v_mfma_f32_16x16x32_bf16 v[140:143], v[122:125], v[196:199], v[140:143]
	v_mfma_f32_16x16x32_bf16 v[134:137], v[126:129], v[192:195], v[136:139]
	v_mfma_f32_16x16x32_bf16 v[136:139], v[170:173], v[196:199], v[134:137]
	v_mfma_f32_16x16x32_bf16 v[104:107], v[126:129], v[200:203], v[104:107]
	v_mfma_f32_16x16x32_bf16 v[104:107], v[170:173], v[204:207], v[104:107]
	v_mfma_f32_16x16x32_bf16 v[108:111], v[118:121], v[200:203], v[108:111]
	v_mfma_f32_16x16x32_bf16 v[108:111], v[122:125], v[204:207], v[108:111]
	v_mfma_f32_16x16x32_bf16 v[92:95], v[118:121], v[208:211], v[92:95]
	v_mfma_f32_16x16x32_bf16 v[92:95], v[122:125], v[212:215], v[92:95]
	v_mfma_f32_16x16x32_bf16 v[88:91], v[126:129], v[208:211], v[88:91]
	v_mfma_f32_16x16x32_bf16 v[88:91], v[170:173], v[212:215], v[88:91]
	v_mfma_f32_16x16x32_bf16 v[72:75], v[126:129], v[216:219], v[72:75]
	v_mfma_f32_16x16x32_bf16 v[72:75], v[170:173], v[220:223], v[72:75]
	v_mfma_f32_16x16x32_bf16 v[76:79], v[118:121], v[216:219], v[76:79]
	v_mfma_f32_16x16x32_bf16 v[76:79], v[122:125], v[220:223], v[76:79]
	s_setprio 0
	s_setprio 1
	v_mfma_f32_16x16x32_bf16 v[130:133], v[174:177], v[192:195], v[130:133]
	v_mfma_f32_16x16x32_bf16 v[132:135], v[178:181], v[196:199], v[130:133]
	v_mfma_f32_16x16x32_bf16 v[112:115], v[184:187], v[192:195], v[112:115]
	v_mfma_f32_16x16x32_bf16 v[112:115], v[188:191], v[196:199], v[112:115]
	v_mfma_f32_16x16x32_bf16 v[96:99], v[184:187], v[200:203], v[96:99]
	v_mfma_f32_16x16x32_bf16 v[96:99], v[188:191], v[204:207], v[96:99]
	v_mfma_f32_16x16x32_bf16 v[100:103], v[174:177], v[200:203], v[100:103]
	v_mfma_f32_16x16x32_bf16 v[100:103], v[178:181], v[204:207], v[100:103]
	v_mfma_f32_16x16x32_bf16 v[84:87], v[174:177], v[208:211], v[84:87]
	v_mfma_f32_16x16x32_bf16 v[84:87], v[178:181], v[212:215], v[84:87]
	v_mfma_f32_16x16x32_bf16 v[80:83], v[184:187], v[208:211], v[80:83]
	v_mfma_f32_16x16x32_bf16 v[80:83], v[188:191], v[212:215], v[80:83]
	v_mfma_f32_16x16x32_bf16 v[64:67], v[184:187], v[216:219], v[64:67]
	v_mfma_f32_16x16x32_bf16 v[64:67], v[188:191], v[220:223], v[64:67]
	v_mfma_f32_16x16x32_bf16 v[68:71], v[174:177], v[216:219], v[68:71]
	v_mfma_f32_16x16x32_bf16 v[68:71], v[178:181], v[220:223], v[68:71]
	s_setprio 0
	s_barrier
; #define PG8_STAGE(bufoff, gbase, voff) do { _Pragma("unroll") for (int _i = 0; _i < 2; ++_i) \
;         __builtin_amdgcn_global_load_lds((const unsigned*)((const char*)(gbase) + (voff)[_i]), (PG8_LAS unsigned*)(lds + (bufoff) + ldsw + _i * 8192), 16, 0, 0); } while (0)
; #define PG8_LDA(dst, b, h) do { _Pragma("unroll") for (int m = 0; m < 4; ++m) _Pragma("unroll") for (int k = 0; k < 2; ++k) dst[m][k] = *(const PG8_LAS bf16x8*)(lds + PG8_SA(b, h) + aoff + m * 2048 + k * 1024); } while (0)
; #define PG8_MMA(ai, bj, At, Bt) do { __builtin_amdgcn_s_setprio(1); _Pragma("unroll") for (int m = 0; m < 4; ++m) _Pragma("unroll") for (int n = 0; n < 2; ++n) _Pragma("unroll") for (int k = 0; k < 2; ++k) \
;         acc[ai][bj][m][n] = __builtin_amdgcn_mfma_f32_16x16x32_bf16(Bt[n][k], At[m][k], acc[ai][bj][m][n], 0, 0, 0); __builtin_amdgcn_s_setprio(0); } while (0)
; #define PG8_WAIT_V(n) asm volatile("s_waitcnt vmcnt(" #n ")" ::: "memory")
; #define PG8_WAIT_L(n) asm volatile("s_waitcnt lgkmcnt(" #n ")" ::: "memory")
; #define PG8_BAR __builtin_amdgcn_s_barrier()
; #define PG8_SCHED __builtin_amdgcn_sched_barrier(0)
; template <class Epi, class Sched, bool ALIGN_EPI = false, bool SP2 = false>
; __device__ __forceinline__ void gemm_phase(PG8_LAS unsigned char* lds, const Gemm g, const Sched& S, const Epi& E) {
;     ...
;             PG8_LDA(At, 1, 1); PG8_STAGE(PG8_SB(1, 0), b3, voffB); PG8_STAGE(PG8_SB(1, 1), b3 + hstep, voffB); PG8_STAGE(PG8_SA(1, 0), a3, voffA);
;             PG8_WAIT_V(8); PG8_WAIT_L(0); PG8_BAR; PG8_MMA(1, 0, At, B0); PG8_MMA(1, 1, At, B1); PG8_BAR; PG8_SCHED;
	s_add_i32 s14, s14, s55
	s_add_u32 s98, s50, s18
	s_addc_u32 s99, s51, s19
	s_mov_b32 m0, s14
	ds_read_b128 v[192:195], v168 offset:49152
	ds_read_b128 v[196:199], v168 offset:50176
	ds_read_b128 v[200:203], v168 offset:51200
	ds_read_b128 v[204:207], v168 offset:52224
	ds_read_b128 v[208:211], v168 offset:53248
	ds_read_b128 v[212:215], v168 offset:54272
	ds_read_b128 v[216:219], v168 offset:55296
	ds_read_b128 v[220:223], v168 offset:56320
	global_load_lds_dwordx4 v148, s[98:99]
	s_add_i32 m0, s14, 0x2000
	s_add_u32 s50, s50, 0x40080
	v_lshl_add_u64 v[130:131], v[226:227], 0, s[18:19]
	s_addc_u32 s51, s51, 0
	s_add_i32 s14, s15, s55
	global_load_lds_dwordx4 v[130:131], off
	s_mov_b32 m0, s14
	s_nop 0
	global_load_lds_dwordx4 v148, s[50:51]
	s_add_i32 m0, s14, 0x2000
	s_nop 0
	global_load_lds_dwordx4 v144, s[50:51]
	v_lshl_add_u64 v[130:131], v[228:229], 0, s[18:19]
	s_mov_b32 m0, s64
	s_nop 0
	global_load_lds_dwordx4 v[130:131], off
	v_lshl_add_u64 v[130:131], v[230:231], 0, s[18:19]
	s_mov_b32 m0, s65
	s_nop 0
	global_load_lds_dwordx4 v[130:131], off
	s_waitcnt vmcnt(8)
	s_waitcnt lgkmcnt(0)
	s_barrier
	s_setprio 1
	s_waitcnt lgkmcnt(0)
	v_mfma_f32_16x16x32_bf16 v[60:63], v[118:121], v[192:195], v[60:63]
	v_mfma_f32_16x16x32_bf16 v[60:63], v[122:125], v[196:199], v[60:63]
	v_mfma_f32_16x16x32_bf16 v[56:59], v[126:129], v[192:195], v[56:59]
	v_mfma_f32_16x16x32_bf16 v[56:59], v[170:173], v[196:199], v[56:59]
	v_mfma_f32_16x16x32_bf16 v[40:43], v[126:129], v[200:203], v[40:43]
	v_mfma_f32_16x16x32_bf16 v[40:43], v[170:173], v[204:207], v[40:43]
	v_mfma_f32_16x16x32_bf16 v[44:47], v[118:121], v[200:203], v[44:47]
	v_mfma_f32_16x16x32_bf16 v[44:47], v[122:125], v[204:207], v[44:47]
	v_mfma_f32_16x16x32_bf16 v[28:31], v[118:121], v[208:211], v[28:31]
	v_mfma_f32_16x16x32_bf16 v[28:31], v[122:125], v[212:215], v[28:31]
	v_mfma_f32_16x16x32_bf16 v[24:27], v[126:129], v[208:211], v[24:27]
	v_mfma_f32_16x16x32_bf16 v[24:27], v[170:173], v[212:215], v[24:27]
	v_mfma_f32_16x16x32_bf16 v[8:11], v[126:129], v[216:219], v[8:11]
	v_mfma_f32_16x16x32_bf16 v[8:11], v[170:173], v[220:223], v[8:11]
	v_mfma_f32_16x16x32_bf16 v[12:15], v[118:121], v[216:219], v[12:15]
	v_mfma_f32_16x16x32_bf16 v[12:15], v[122:125], v[220:223], v[12:15]
	s_setprio 0
	s_setprio 1
	v_mfma_f32_16x16x32_bf16 v[52:55], v[174:177], v[192:195], v[52:55]
	v_mfma_f32_16x16x32_bf16 v[52:55], v[178:181], v[196:199], v[52:55]
	v_mfma_f32_16x16x32_bf16 v[48:51], v[184:187], v[192:195], v[48:51]
	v_mfma_f32_16x16x32_bf16 v[48:51], v[188:191], v[196:199], v[48:51]
	v_mfma_f32_16x16x32_bf16 v[32:35], v[184:187], v[200:203], v[32:35]
	v_mfma_f32_16x16x32_bf16 v[32:35], v[188:191], v[204:207], v[32:35]
	v_mfma_f32_16x16x32_bf16 v[36:39], v[174:177], v[200:203], v[36:39]
	v_mfma_f32_16x16x32_bf16 v[36:39], v[178:181], v[204:207], v[36:39]
	v_mfma_f32_16x16x32_bf16 v[20:23], v[174:177], v[208:211], v[20:23]
	v_mfma_f32_16x16x32_bf16 v[20:23], v[178:181], v[212:215], v[20:23]
	v_mfma_f32_16x16x32_bf16 v[16:19], v[184:187], v[208:211], v[16:19]
	v_mfma_f32_16x16x32_bf16 v[16:19], v[188:191], v[212:215], v[16:19]
	v_mfma_f32_16x16x32_bf16 v[0:3], v[184:187], v[216:219], v[0:3]
	v_mfma_f32_16x16x32_bf16 v[0:3], v[188:191], v[220:223], v[0:3]
	v_mfma_f32_16x16x32_bf16 v[4:7], v[174:177], v[216:219], v[4:7]
	v_mfma_f32_16x16x32_bf16 v[4:7], v[178:181], v[220:223], v[4:7]
	s_setprio 0
	s_barrier
	s_add_i32 s75, s75, 2
	s_add_u32 s45, s45, 0x100
	s_addc_u32 s47, s47, 0
	s_add_u32 s48, s48, 0x100
	s_addc_u32 s49, s49, 0
	s_cmp_gt_u32 s75, 13
	s_cbranch_scc1 .LBB0_1361

; #define PG8_STAGE(bufoff, gbase, voff) do { _Pragma("unroll") for (int _i = 0; _i < 2; ++_i) \
;         __builtin_amdgcn_global_load_lds((const unsigned*)((const char*)(gbase) + (voff)[_i]), (PG8_LAS unsigned*)(lds + (bufoff) + ldsw + _i * 8192), 16, 0, 0); } while (0)
; #define PG8_LDA(dst, b, h) do { _Pragma("unroll") for (int m = 0; m < 4; ++m) _Pragma("unroll") for (int k = 0; k < 2; ++k) dst[m][k] = *(const PG8_LAS bf16x8*)(lds + PG8_SA(b, h) + aoff + m * 2048 + k * 1024); } while (0)
; #define PG8_LDB(dst, b, h) do { _Pragma("unroll") for (int n = 0; n < 2; ++n) _Pragma("unroll") for (int k = 0; k < 2; ++k) dst[n][k] = *(const PG8_LAS bf16x8*)(lds + PG8_SB(b, h) + boff + n * 2048 + k * 1024); } while (0)
; #define PG8_MMA(ai, bj, At, Bt) do { __builtin_amdgcn_s_setprio(1); _Pragma("unroll") for (int m = 0; m < 4; ++m) _Pragma("unroll") for (int n = 0; n < 2; ++n) _Pragma("unroll") for (int k = 0; k < 2; ++k) \
;         acc[ai][bj][m][n] = __builtin_amdgcn_mfma_f32_16x16x32_bf16(Bt[n][k], At[m][k], acc[ai][bj][m][n], 0, 0, 0); __builtin_amdgcn_s_setprio(0); } while (0)
; #define PG8_WAIT_V(n) asm volatile("s_waitcnt vmcnt(" #n ")" ::: "memory")
; #define PG8_WAIT_L(n) asm volatile("s_waitcnt lgkmcnt(" #n ")" ::: "memory")
; #define PG8_BAR __builtin_amdgcn_s_barrier()
; #define PG8_SCHED __builtin_amdgcn_sched_barrier(0)
; template <class Epi, class Sched, bool ALIGN_EPI = false, bool SP2 = false>
; __device__ __forceinline__ void gemm_phase(PG8_LAS unsigned char* lds, const Gemm g, const Sched& S, const Epi& E) {
;     ...
;             PG8_LDB(B0, 0, 0); PG8_LDB(B1, 0, 1); PG8_SCHED; PG8_LDA(At, 0, 0); PG8_STAGE(PG8_SA(1, 1), a1 + hstep, voffA);
;             PG8_WAIT_V(8); PG8_WAIT_L(0); PG8_BAR; PG8_MMA(0, 0, At, B0); PG8_MMA(0, 1, At, B1); PG8_BAR; PG8_SCHED;
;             PG8_LDA(At, 0, 1); PG8_STAGE(PG8_SB(0, 0), b2, voffB); PG8_STAGE(PG8_SB(0, 1), b2 + hstep, voffB); PG8_STAGE(PG8_SA(0, 0), a2, voffA);
;             PG8_WAIT_V(8); PG8_WAIT_L(0); PG8_BAR; PG8_MMA(1, 0, At, B0); PG8_MMA(1, 1, At, B1); PG8_BAR; PG8_SCHED;
.LBB0_1432:
	ds_read_b128 v[128:131], v167
	ds_read_b128 v[132:135], v167 offset:1024
	ds_read_b128 v[136:139], v167 offset:2048
	ds_read_b128 v[140:143], v167 offset:3072
	ds_read_b128 v[160:163], v168
	ds_read_b128 v[170:173], v168 offset:1024
	ds_read_b128 v[174:177], v168 offset:2048
	ds_read_b128 v[178:181], v168 offset:3072
	s_add_u32 s20, s18, 0x100
	s_addc_u32 s21, s19, 0
	s_cmp_eq_u32 s52, 40
	s_cselect_b32 s27, s5, s21
	s_cselect_b32 s26, s4, s20
	s_cselect_b32 s23, s17, s51
	s_cselect_b32 s22, s16, s50
	v_lshl_add_u64 v[214:215], s[18:19], 0, v[154:155]
	s_add_i32 m0, s36, 0xc000
	ds_read_b128 v[182:185], v169
	ds_read_b128 v[186:189], v169 offset:1024
	ds_read_b128 v[190:193], v169 offset:2048
	ds_read_b128 v[194:197], v169 offset:3072
	ds_read_b128 v[198:201], v169 offset:4096
	ds_read_b128 v[202:205], v169 offset:5120
	ds_read_b128 v[206:209], v169 offset:6144
	ds_read_b128 v[210:213], v169 offset:7168
	global_load_lds_dwordx4 v[214:215], off
	v_lshl_add_u64 v[214:215], s[18:19], 0, v[152:153]
	s_add_i32 m0, s36, 0xe000
	s_nop 0
	global_load_lds_dwordx4 v[214:215], off
	s_waitcnt vmcnt(8)
	s_waitcnt lgkmcnt(0)
	s_barrier
	s_setprio 1
	s_waitcnt lgkmcnt(0)
	v_mfma_f32_16x16x32_bf16 v[124:127], v[128:131], v[182:185], v[124:127]
	v_mfma_f32_16x16x32_bf16 v[124:127], v[132:135], v[186:189], v[124:127]
	v_mfma_f32_16x16x32_bf16 v[120:123], v[136:139], v[182:185], v[120:123]
	v_mfma_f32_16x16x32_bf16 v[120:123], v[140:143], v[186:189], v[120:123]
	v_mfma_f32_16x16x32_bf16 v[108:111], v[136:139], v[190:193], v[108:111]
	v_mfma_f32_16x16x32_bf16 v[108:111], v[140:143], v[194:197], v[108:111]
	v_mfma_f32_16x16x32_bf16 v[116:119], v[128:131], v[190:193], v[116:119]
	v_mfma_f32_16x16x32_bf16 v[116:119], v[132:135], v[194:197], v[116:119]
	v_mfma_f32_16x16x32_bf16 v[100:103], v[128:131], v[198:201], v[100:103]
	v_mfma_f32_16x16x32_bf16 v[100:103], v[132:135], v[202:205], v[100:103]
	v_mfma_f32_16x16x32_bf16 v[92:95], v[136:139], v[198:201], v[92:95]
	v_mfma_f32_16x16x32_bf16 v[92:95], v[140:143], v[202:205], v[92:95]
	v_mfma_f32_16x16x32_bf16 v[76:79], v[136:139], v[206:209], v[76:79]
	v_mfma_f32_16x16x32_bf16 v[76:79], v[140:143], v[210:213], v[76:79]
	v_mfma_f32_16x16x32_bf16 v[84:87], v[128:131], v[206:209], v[84:87]
	v_mfma_f32_16x16x32_bf16 v[84:87], v[132:135], v[210:213], v[84:87]
	s_setprio 0
	s_setprio 1
	v_mfma_f32_16x16x32_bf16 v[112:115], v[160:163], v[182:185], v[112:115]
	v_mfma_f32_16x16x32_bf16 v[112:115], v[170:173], v[186:189], v[112:115]
	v_mfma_f32_16x16x32_bf16 v[104:107], v[174:177], v[182:185], v[104:107]
	v_mfma_f32_16x16x32_bf16 v[104:107], v[178:181], v[186:189], v[104:107]
	v_mfma_f32_16x16x32_bf16 v[88:91], v[174:177], v[190:193], v[88:91]
	v_mfma_f32_16x16x32_bf16 v[88:91], v[178:181], v[194:197], v[88:91]
	v_mfma_f32_16x16x32_bf16 v[96:99], v[160:163], v[190:193], v[96:99]
	v_mfma_f32_16x16x32_bf16 v[96:99], v[170:173], v[194:197], v[96:99]
	v_mfma_f32_16x16x32_bf16 v[80:83], v[160:163], v[198:201], v[80:83]
	v_mfma_f32_16x16x32_bf16 v[80:83], v[170:173], v[202:205], v[80:83]
	v_mfma_f32_16x16x32_bf16 v[72:75], v[174:177], v[198:201], v[72:75]
	v_mfma_f32_16x16x32_bf16 v[72:75], v[178:181], v[202:205], v[72:75]
	v_mfma_f32_16x16x32_bf16 v[64:67], v[174:177], v[206:209], v[64:67]
	v_mfma_f32_16x16x32_bf16 v[64:67], v[178:181], v[210:213], v[64:67]
	v_mfma_f32_16x16x32_bf16 v[68:71], v[160:163], v[206:209], v[68:71]
	v_mfma_f32_16x16x32_bf16 v[68:71], v[170:173], v[210:213], v[68:71]
	s_setprio 0
	s_barrier
	s_add_i32 s18, s44, s33
	s_mov_b32 m0, s18
	ds_read_b128 v[182:185], v169 offset:16384
	ds_read_b128 v[186:189], v169 offset:17408
	ds_read_b128 v[190:193], v169 offset:18432
	ds_read_b128 v[194:197], v169 offset:19456
	ds_read_b128 v[198:201], v169 offset:20480
	ds_read_b128 v[202:205], v169 offset:21504
	ds_read_b128 v[206:209], v169 offset:22528
	ds_read_b128 v[210:213], v169 offset:23552
	global_load_lds_dwordx4 v148, s[22:23]
	s_add_i32 m0, s18, 0x2000
	s_add_u32 s18, s22, 0xb0000
	v_lshl_add_u64 v[216:217], s[22:23], 0, v[144:145]
	s_addc_u32 s19, s23, 0
	s_add_i32 s53, s45, s33
	global_load_lds_dwordx4 v144, s[22:23]
	s_mov_b32 m0, s53
	s_nop 0
	global_load_lds_dwordx4 v148, s[18:19]
	s_add_i32 m0, s53, 0x2000
	s_nop 0
	global_load_lds_dwordx4 v144, s[18:19]
	s_mov_b32 m0, s36
	s_nop 0
	global_load_lds_dwordx4 v150, s[26:27]
	s_mov_b32 m0, s37
	s_nop 0
	global_load_lds_dwordx4 v146, s[26:27]
	s_waitcnt vmcnt(8)
	s_waitcnt lgkmcnt(0)
	s_barrier
	s_setprio 1
	s_waitcnt lgkmcnt(0)
	v_mfma_f32_16x16x32_bf16 v[60:63], v[128:131], v[182:185], v[60:63]
	v_mfma_f32_16x16x32_bf16 v[60:63], v[132:135], v[186:189], v[60:63]
	v_mfma_f32_16x16x32_bf16 v[56:59], v[136:139], v[182:185], v[56:59]
	v_mfma_f32_16x16x32_bf16 v[56:59], v[140:143], v[186:189], v[56:59]
	v_mfma_f32_16x16x32_bf16 v[44:47], v[136:139], v[190:193], v[44:47]
	v_mfma_f32_16x16x32_bf16 v[44:47], v[140:143], v[194:197], v[44:47]
	v_mfma_f32_16x16x32_bf16 v[48:51], v[128:131], v[190:193], v[48:51]
	v_mfma_f32_16x16x32_bf16 v[48:51], v[132:135], v[194:197], v[48:51]
	v_mfma_f32_16x16x32_bf16 v[36:39], v[128:131], v[198:201], v[36:39]
	v_mfma_f32_16x16x32_bf16 v[36:39], v[132:135], v[202:205], v[36:39]
	v_mfma_f32_16x16x32_bf16 v[28:31], v[136:139], v[198:201], v[28:31]
	v_mfma_f32_16x16x32_bf16 v[28:31], v[140:143], v[202:205], v[28:31]
	v_mfma_f32_16x16x32_bf16 v[12:15], v[136:139], v[206:209], v[12:15]
	v_mfma_f32_16x16x32_bf16 v[12:15], v[140:143], v[210:213], v[12:15]
	v_mfma_f32_16x16x32_bf16 v[20:23], v[128:131], v[206:209], v[20:23]
	v_mfma_f32_16x16x32_bf16 v[20:23], v[132:135], v[210:213], v[20:23]
	s_setprio 0
	s_setprio 1
	v_mfma_f32_16x16x32_bf16 v[52:55], v[160:163], v[182:185], v[52:55]
	v_mfma_f32_16x16x32_bf16 v[52:55], v[170:173], v[186:189], v[52:55]
	v_mfma_f32_16x16x32_bf16 v[40:43], v[174:177], v[182:185], v[40:43]
	v_mfma_f32_16x16x32_bf16 v[40:43], v[178:181], v[186:189], v[40:43]
	v_mfma_f32_16x16x32_bf16 v[24:27], v[174:177], v[190:193], v[24:27]
	v_mfma_f32_16x16x32_bf16 v[24:27], v[178:181], v[194:197], v[24:27]
	v_mfma_f32_16x16x32_bf16 v[32:35], v[160:163], v[190:193], v[32:35]
	v_mfma_f32_16x16x32_bf16 v[32:35], v[170:173], v[194:197], v[32:35]
	v_mfma_f32_16x16x32_bf16 v[16:19], v[160:163], v[198:201], v[16:19]
	v_mfma_f32_16x16x32_bf16 v[16:19], v[170:173], v[202:205], v[16:19]
	v_mfma_f32_16x16x32_bf16 v[8:11], v[174:177], v[198:201], v[8:11]
	v_mfma_f32_16x16x32_bf16 v[8:11], v[178:181], v[202:205], v[8:11]
	v_mfma_f32_16x16x32_bf16 v[0:3], v[174:177], v[206:209], v[0:3]
	v_mfma_f32_16x16x32_bf16 v[0:3], v[178:181], v[210:213], v[0:3]
	v_mfma_f32_16x16x32_bf16 v[4:7], v[160:163], v[206:209], v[4:7]
	v_mfma_f32_16x16x32_bf16 v[4:7], v[170:173], v[210:213], v[4:7]
	s_setprio 0
	s_barrier
; #define PG8_STAGE(bufoff, gbase, voff) do { _Pragma("unroll") for (int _i = 0; _i < 2; ++_i) \
;         __builtin_amdgcn_global_load_lds((const unsigned*)((const char*)(gbase) + (voff)[_i]), (PG8_LAS unsigned*)(lds + (bufoff) + ldsw + _i * 8192), 16, 0, 0); } while (0)
; #define PG8_LDA(dst, b, h) do { _Pragma("unroll") for (int m = 0; m < 4; ++m) _Pragma("unroll") for (int k = 0; k < 2; ++k) dst[m][k] = *(const PG8_LAS bf16x8*)(lds + PG8_SA(b, h) + aoff + m * 2048 + k * 1024); } while (0)
; #define PG8_LDB(dst, b, h) do { _Pragma("unroll") for (int n = 0; n < 2; ++n) _Pragma("unroll") for (int k = 0; k < 2; ++k) dst[n][k] = *(const PG8_LAS bf16x8*)(lds + PG8_SB(b, h) + boff + n * 2048 + k * 1024); } while (0)
; #define PG8_MMA(ai, bj, At, Bt) do { __builtin_amdgcn_s_setprio(1); _Pragma("unroll") for (int m = 0; m < 4; ++m) _Pragma("unroll") for (int n = 0; n < 2; ++n) _Pragma("unroll") for (int k = 0; k < 2; ++k) \
;         acc[ai][bj][m][n] = __builtin_amdgcn_mfma_f32_16x16x32_bf16(Bt[n][k], At[m][k], acc[ai][bj][m][n], 0, 0, 0); __builtin_amdgcn_s_setprio(0); } while (0)
; #define PG8_WAIT_V(n) asm volatile("s_waitcnt vmcnt(" #n ")" ::: "memory")
; #define PG8_WAIT_L(n) asm volatile("s_waitcnt lgkmcnt(" #n ")" ::: "memory")
; #define PG8_BAR __builtin_amdgcn_s_barrier()
; #define PG8_SCHED __builtin_amdgcn_sched_barrier(0)
; template <class Epi, class Sched, bool ALIGN_EPI = false, bool SP2 = false>
; __device__ __forceinline__ void gemm_phase(PG8_LAS unsigned char* lds, const Gemm g, const Sched& S, const Epi& E) {
;     ...
;             PG8_LDB(B0, 1, 0); PG8_LDB(B1, 1, 1); PG8_SCHED; PG8_LDA(At, 1, 0); PG8_STAGE(PG8_SA(0, 1), a2 + hstep, voffA);
;             PG8_WAIT_V(8); PG8_WAIT_L(0); PG8_BAR; PG8_MMA(0, 0, At, B0); PG8_MMA(0, 1, At, B1); PG8_BAR; PG8_SCHED;
;             PG8_LDA(At, 1, 1); PG8_STAGE(PG8_SB(1, 0), b3, voffB); PG8_STAGE(PG8_SB(1, 1), b3 + hstep, voffB); PG8_STAGE(PG8_SA(1, 0), a3, voffA);
;             PG8_WAIT_V(8); PG8_WAIT_L(0); PG8_BAR; PG8_MMA(1, 0, At, B0); PG8_MMA(1, 1, At, B1); PG8_BAR; PG8_SCHED;
	s_add_i32 s53, 0, 0x18000
	s_add_i32 s54, 0, 0x1c000
	v_add_u32_e32 v140, s53, v165
	v_add_u32_e32 v178, s54, v165
	ds_read_b128 v[128:131], v140
	ds_read_b128 v[132:135], v140 offset:1024
	ds_read_b128 v[136:139], v140 offset:2048
	ds_read_b128 v[140:143], v140 offset:3072
	ds_read_b128 v[160:163], v178
	ds_read_b128 v[170:173], v178 offset:1024
	ds_read_b128 v[174:177], v178 offset:2048
	ds_read_b128 v[178:181], v178 offset:3072
	s_add_u32 s18, s26, 0xb0000
	s_addc_u32 s19, s27, 0
	s_mov_b32 m0, s38
	ds_read_b128 v[182:185], v169 offset:32768
	ds_read_b128 v[186:189], v169 offset:33792
	ds_read_b128 v[190:193], v169 offset:34816
	ds_read_b128 v[194:197], v169 offset:35840
	ds_read_b128 v[198:201], v169 offset:36864
	ds_read_b128 v[202:205], v169 offset:37888
	ds_read_b128 v[206:209], v169 offset:38912
	ds_read_b128 v[210:213], v169 offset:39936
	global_load_lds_dwordx4 v150, s[18:19]
	s_mov_b32 m0, s39
	s_nop 0
	global_load_lds_dwordx4 v146, s[18:19]
	s_waitcnt vmcnt(8)
	s_waitcnt lgkmcnt(0)
	s_barrier
	s_setprio 1
	s_waitcnt lgkmcnt(0)
	v_mfma_f32_16x16x32_bf16 v[124:127], v[128:131], v[182:185], v[124:127]
	v_mfma_f32_16x16x32_bf16 v[124:127], v[132:135], v[186:189], v[124:127]
	v_mfma_f32_16x16x32_bf16 v[120:123], v[136:139], v[182:185], v[120:123]
	v_mfma_f32_16x16x32_bf16 v[120:123], v[140:143], v[186:189], v[120:123]
	v_mfma_f32_16x16x32_bf16 v[108:111], v[136:139], v[190:193], v[108:111]
	v_mfma_f32_16x16x32_bf16 v[108:111], v[140:143], v[194:197], v[108:111]
	v_mfma_f32_16x16x32_bf16 v[116:119], v[128:131], v[190:193], v[116:119]
	v_mfma_f32_16x16x32_bf16 v[116:119], v[132:135], v[194:197], v[116:119]
	v_mfma_f32_16x16x32_bf16 v[100:103], v[128:131], v[198:201], v[100:103]
	v_mfma_f32_16x16x32_bf16 v[100:103], v[132:135], v[202:205], v[100:103]
	v_mfma_f32_16x16x32_bf16 v[92:95], v[136:139], v[198:201], v[92:95]
	v_mfma_f32_16x16x32_bf16 v[92:95], v[140:143], v[202:205], v[92:95]
	v_mfma_f32_16x16x32_bf16 v[76:79], v[136:139], v[206:209], v[76:79]
	v_mfma_f32_16x16x32_bf16 v[76:79], v[140:143], v[210:213], v[76:79]
	v_mfma_f32_16x16x32_bf16 v[84:87], v[128:131], v[206:209], v[84:87]
	v_mfma_f32_16x16x32_bf16 v[84:87], v[132:135], v[210:213], v[84:87]
	s_setprio 0
	s_setprio 1
	v_mfma_f32_16x16x32_bf16 v[112:115], v[160:163], v[182:185], v[112:115]
	v_mfma_f32_16x16x32_bf16 v[112:115], v[170:173], v[186:189], v[112:115]
	v_mfma_f32_16x16x32_bf16 v[104:107], v[174:177], v[182:185], v[104:107]
	v_mfma_f32_16x16x32_bf16 v[104:107], v[178:181], v[186:189], v[104:107]
	v_mfma_f32_16x16x32_bf16 v[88:91], v[174:177], v[190:193], v[88:91]
	v_mfma_f32_16x16x32_bf16 v[88:91], v[178:181], v[194:197], v[88:91]
	v_mfma_f32_16x16x32_bf16 v[96:99], v[160:163], v[190:193], v[96:99]
	v_mfma_f32_16x16x32_bf16 v[96:99], v[170:173], v[194:197], v[96:99]
	v_mfma_f32_16x16x32_bf16 v[80:83], v[160:163], v[198:201], v[80:83]
	v_mfma_f32_16x16x32_bf16 v[80:83], v[170:173], v[202:205], v[80:83]
	v_mfma_f32_16x16x32_bf16 v[72:75], v[174:177], v[198:201], v[72:75]
	v_mfma_f32_16x16x32_bf16 v[72:75], v[178:181], v[202:205], v[72:75]
	v_mfma_f32_16x16x32_bf16 v[64:67], v[174:177], v[206:209], v[64:67]
	v_mfma_f32_16x16x32_bf16 v[64:67], v[178:181], v[210:213], v[64:67]
	v_mfma_f32_16x16x32_bf16 v[68:71], v[160:163], v[206:209], v[68:71]
	v_mfma_f32_16x16x32_bf16 v[68:71], v[170:173], v[210:213], v[68:71]
	s_setprio 0
	s_barrier
	s_add_i32 s18, s53, s33
	s_add_u32 s98, s22, s12
	s_addc_u32 s99, s23, s13
	s_add_u32 s100, s26, s12
	s_addc_u32 s101, s27, s13
	s_mov_b32 m0, s18
	ds_read_b128 v[182:185], v169 offset:49152
	ds_read_b128 v[186:189], v169 offset:50176
	ds_read_b128 v[190:193], v169 offset:51200
	ds_read_b128 v[194:197], v169 offset:52224
	ds_read_b128 v[198:201], v169 offset:53248
	ds_read_b128 v[202:205], v169 offset:54272
	ds_read_b128 v[206:209], v169 offset:55296
	ds_read_b128 v[210:213], v169 offset:56320
	global_load_lds_dwordx4 v148, s[98:99]
	s_add_i32 m0, s18, 0x2000
	s_add_u32 s18, s22, 0xb0080
	v_lshl_add_u64 v[214:215], v[216:217], 0, s[12:13]
	s_addc_u32 s19, s23, 0
	s_add_i32 s22, s54, s33
	global_load_lds_dwordx4 v[214:215], off
	s_mov_b32 m0, s22
	s_nop 0
	global_load_lds_dwordx4 v148, s[18:19]
	s_add_i32 m0, s22, 0x2000
	s_nop 0
	global_load_lds_dwordx4 v144, s[18:19]
	s_mov_b32 m0, s41
	s_nop 0
	global_load_lds_dwordx4 v150, s[100:101]
	s_mov_b32 m0, s42
	s_nop 0
	global_load_lds_dwordx4 v146, s[100:101]
	s_waitcnt vmcnt(8)
	s_waitcnt lgkmcnt(0)
	s_barrier
	s_setprio 1
	s_waitcnt lgkmcnt(0)
	v_mfma_f32_16x16x32_bf16 v[60:63], v[128:131], v[182:185], v[60:63]
	v_mfma_f32_16x16x32_bf16 v[60:63], v[132:135], v[186:189], v[60:63]
	v_mfma_f32_16x16x32_bf16 v[56:59], v[136:139], v[182:185], v[56:59]
	v_mfma_f32_16x16x32_bf16 v[56:59], v[140:143], v[186:189], v[56:59]
	v_mfma_f32_16x16x32_bf16 v[44:47], v[136:139], v[190:193], v[44:47]
	v_mfma_f32_16x16x32_bf16 v[44:47], v[140:143], v[194:197], v[44:47]
	v_mfma_f32_16x16x32_bf16 v[48:51], v[128:131], v[190:193], v[48:51]
	v_mfma_f32_16x16x32_bf16 v[48:51], v[132:135], v[194:197], v[48:51]
	v_mfma_f32_16x16x32_bf16 v[36:39], v[128:131], v[198:201], v[36:39]
	v_mfma_f32_16x16x32_bf16 v[36:39], v[132:135], v[202:205], v[36:39]
	v_mfma_f32_16x16x32_bf16 v[28:31], v[136:139], v[198:201], v[28:31]
	v_mfma_f32_16x16x32_bf16 v[28:31], v[140:143], v[202:205], v[28:31]
	v_mfma_f32_16x16x32_bf16 v[12:15], v[136:139], v[206:209], v[12:15]
	v_mfma_f32_16x16x32_bf16 v[12:15], v[140:143], v[210:213], v[12:15]
	v_mfma_f32_16x16x32_bf16 v[20:23], v[128:131], v[206:209], v[20:23]
	v_mfma_f32_16x16x32_bf16 v[20:23], v[132:135], v[210:213], v[20:23]
	s_setprio 0
	s_setprio 1
	v_mfma_f32_16x16x32_bf16 v[52:55], v[160:163], v[182:185], v[52:55]
	v_mfma_f32_16x16x32_bf16 v[52:55], v[170:173], v[186:189], v[52:55]
	v_mfma_f32_16x16x32_bf16 v[40:43], v[174:177], v[182:185], v[40:43]
	v_mfma_f32_16x16x32_bf16 v[40:43], v[178:181], v[186:189], v[40:43]
	v_mfma_f32_16x16x32_bf16 v[24:27], v[174:177], v[190:193], v[24:27]
	v_mfma_f32_16x16x32_bf16 v[24:27], v[178:181], v[194:197], v[24:27]
	v_mfma_f32_16x16x32_bf16 v[32:35], v[160:163], v[190:193], v[32:35]
	v_mfma_f32_16x16x32_bf16 v[32:35], v[170:173], v[194:197], v[32:35]
	v_mfma_f32_16x16x32_bf16 v[16:19], v[160:163], v[198:201], v[16:19]
	v_mfma_f32_16x16x32_bf16 v[16:19], v[170:173], v[202:205], v[16:19]
	v_mfma_f32_16x16x32_bf16 v[8:11], v[174:177], v[198:201], v[8:11]
	v_mfma_f32_16x16x32_bf16 v[8:11], v[178:181], v[202:205], v[8:11]
	v_mfma_f32_16x16x32_bf16 v[0:3], v[174:177], v[206:209], v[0:3]
	v_mfma_f32_16x16x32_bf16 v[0:3], v[178:181], v[210:213], v[0:3]
	v_mfma_f32_16x16x32_bf16 v[4:7], v[160:163], v[206:209], v[4:7]
	v_mfma_f32_16x16x32_bf16 v[4:7], v[170:173], v[210:213], v[4:7]
	s_setprio 0
	s_barrier
	s_add_i32 s52, s52, 2
	s_add_u32 s50, s50, 0x100
	s_addc_u32 s51, s51, 0
	s_cmp_gt_u32 s52, 41
	s_mov_b64 s[18:19], s[20:21]
	s_cbranch_scc0 .LBB0_1432
	s_and_b64 vcc, exec, s[14:15]
	s_cbranch_vccz .LBB0_1435
	s_barrier
